# GEMM K-loops: 8 of 13 LDS-DMA loads per K-loop use SGPR base + 32-bit VGPR offset (no v_lshl_add_u64); on top of v85
# baseline (speedup 1.0000x reference)
; #define PG8_STAGE(bufoff, gbase, voff) do { _Pragma("unroll") for (int _i = 0; _i < 2; ++_i) \
;         __builtin_amdgcn_global_load_lds((const unsigned*)((const char*)(gbase) + (voff)[_i]), (LAS unsigned*)(lds + (bufoff) + ldsw + _i * 8192), 16, 0, 0); } while (0)
; #define PG8_WAIT_V(n) asm volatile("s_waitcnt vmcnt(" #n ")" ::: "memory")
; #define PG8_BAR __builtin_amdgcn_s_barrier()
; template <class Epi, bool SP2 = false>
; __device__ __forceinline__ void gemm_phase(LAS unsigned char* lds, const Gemm g, const StaticOrder& S, const Epi& E) {
;     const int tid = threadIdx.x, wid = __builtin_amdgcn_readfirstlane(tid >> 6), lane = tid & 63, wr = wid >> 2, wc = wid & 3, fr = lane & 15, fq = lane >> 4;
;     const int K = g.K, nt = K / BK, lda = g.lda;
;     unsigned voffA[2], voffB[2];
; #pragma unroll
;     for (int i = 0; i < 2; ++i) { int R, C; stage_rc(tid * 16 + i * 8192, R, C); const int Rb = Epi::PERM ? ((R & ~31) + perm32(R & 31)) : R;
;         voffA[i] = (unsigned)(R * lda + C) * 2u; voffB[i] = (unsigned)(Rb * K + C) * 2u; }
;     const size_t kstep = (size_t)(BK * 2);
;     const size_t hstepA = (size_t)HALF * lda * 2, hstepB = (size_t)HALF * K * 2;
;     const size_t tstepA = 2 * hstepA, tstepB = 2 * hstepB;
;     const unsigned ldsw = (unsigned)wid * 1024u;
;     const int aoff = lds_byte(wr * 64 + fr, fq * 8), boff = lds_byte(wc * 32 + fr, fq * 8);
;     ...
;         PG8_WAIT_V(2); PG8_BAR;
;         PG8_STAGE(PG8_SB(1, 0), cB + kstep, voffB); PG8_STAGE(PG8_SA(1, 0), cA + kstep, voffA); PG8_STAGE(PG8_SB(1, 1), cB + hstepB + kstep, voffB);
;         PG8_WAIT_V(6); PG8_BAR;
.LBB0_257:
	s_lshl_b32 s12, s12, 5
	s_lshl_b32 s58, s13, 6
	s_lshl_b32 s24, s13, 13
	s_and_b32 s59, s12, 0x60
	s_mov_b64 s[12:13], 0x80
	s_add_i32 m0, s41, 0x18000
	v_lshl_add_u64 v[6:7], v[6:7], 0, s[12:13]
	s_lshl_b32 s25, s59, 7
	s_waitcnt vmcnt(2)
	s_barrier
	global_load_lds_dwordx4 v[6:7], off
	v_lshl_add_u64 v[4:5], v[4:5], 0, s[12:13]
	s_add_i32 m0, s41, 0x1a000
	s_add_i32 s60, s41, 0x8000
	s_add_i32 s61, s41, 0xa000
	global_load_lds_dwordx4 v[4:5], off
	v_lshl_add_u64 v[0:1], v[0:1], 0, s[12:13]
	s_mov_b32 m0, s60
	s_add_u32 s18, s44, 0x40080
	global_load_lds_dwordx4 v[0:1], off
	v_lshl_add_u64 v[0:1], v[2:3], 0, s[12:13]
	s_mov_b32 m0, s61
	s_addc_u32 s19, s45, 0
	global_load_lds_dwordx4 v[0:1], off
	s_add_i32 m0, s41, 0x1c000
	s_nop 0
	global_load_lds_dwordx4 v134, s[18:19]
	v_lshl_add_u64 v[0:1], s[18:19], 0, v[130:131]
	s_add_i32 m0, s41, 0x1e000
	s_sext_i32_i16 s33, s0
	global_load_lds_dwordx4 v[0:1], off
	v_and_b32_e32 v0, 48, v128
	v_lshlrev_b32_e32 v1, 6, v128
	s_movk_i32 s0, 0x3c0
	v_and_or_b32 v0, v1, s0, v0
	v_lshlrev_b32_e32 v1, 2, v128
	v_and_b32_e32 v1, 32, v1
	v_bitop3_b32 v2, v0, s24, v1 bitop3:0xde
	v_bitop3_b32 v148, s25, v0, v1 bitop3:0xf6
	v_lshlrev_b32_e32 v0, 8, v128
	v_and_b32_e32 v0, 0x38000, v0
	v_lshlrev_b32_e32 v1, 11, v11
	v_or3_b32 v0, v9, v0, v1
	v_add_u32_e32 v138, v0, v10
	v_lshlrev_b32_e32 v0, 4, v8
	s_waitcnt vmcnt(6)
	s_cmpk_lt_u32 s1, 0x100
	v_and_b32_e32 v0, 0x78000, v0
	s_cselect_b64 s[18:19], -1, 0
	v_or3_b32 v0, v9, v0, v1
	s_add_i32 s64, 0, 0x10000
	s_add_i32 s65, 0, 0x14000
	s_ashr_i32 s62, s90, 31
	s_mov_b32 s63, s90
	v_mov_b32_e32 v139, v135
	v_add_u32_e32 v140, v0, v10
	v_mov_b32_e32 v141, v135
	v_mov_b64_e32 v[142:143], 0x2100
	v_mov_b64_e32 v[144:145], 0x20ff
	v_add_u32_e32 v149, s64, v148
	v_add_u32_e32 v150, s65, v148
	v_add_u32_e32 v151, 0, v2
	s_movk_i32 s66, 0x1600
	s_barrier
	s_branch .LBB0_260

; #define PG8_STAGE(bufoff, gbase, voff) do { _Pragma("unroll") for (int _i = 0; _i < 2; ++_i) \
;         __builtin_amdgcn_global_load_lds((const unsigned*)((const char*)(gbase) + (voff)[_i]), (LAS unsigned*)(lds + (bufoff) + ldsw + _i * 8192), 16, 0, 0); } while (0)
; #define PG8_LDA(dst, b, h) do { _Pragma("unroll") for (int m = 0; m < 4; ++m) _Pragma("unroll") for (int k = 0; k < 2; ++k) dst[m][k] = *(const LAS bf16x8*)(lds + PG8_SA(b, h) + aoff + m * 2048 + k * 1024); } while (0)
; #define PG8_LDB(dst, b, h) do { _Pragma("unroll") for (int n = 0; n < 2; ++n) _Pragma("unroll") for (int k = 0; k < 2; ++k) dst[n][k] = *(const LAS bf16x8*)(lds + PG8_SB(b, h) + boff + n * 2048 + k * 1024); } while (0)
; #define PG8_MMA(ai, bj, At, Bt) do { __builtin_amdgcn_s_setprio(1); _Pragma("unroll") for (int m = 0; m < 4; ++m) _Pragma("unroll") for (int n = 0; n < 2; ++n) _Pragma("unroll") for (int k = 0; k < 2; ++k) \
;         acc[ai][bj][m][n] = __builtin_amdgcn_mfma_f32_16x16x32_bf16(Bt[n][k], At[m][k], acc[ai][bj][m][n], 0, 0, 0); __builtin_amdgcn_s_setprio(0); } while (0)
; #define PG8_WAIT_V(n) asm volatile("s_waitcnt vmcnt(" #n ")" ::: "memory")
; #define PG8_WAIT_L(n) asm volatile("s_waitcnt lgkmcnt(" #n ")" ::: "memory")
; #define PG8_BAR __builtin_amdgcn_s_barrier()
; #define PG8_SCHED __builtin_amdgcn_sched_barrier(0)
; template <class Epi, bool SP2 = false>
; __device__ __forceinline__ void gemm_phase(LAS unsigned char* lds, const Gemm g, const StaticOrder& S, const Epi& E) {
;     ...
;             const bool last = (t == nt - 2);
;             const char* a1 = cA + (size_t)(t + 1) * kstep;
;             const char* a2 = last ? nA : cA + (size_t)(t + 2) * kstep; const char* b2 = last ? nB : cB + (size_t)(t + 2) * kstep;
;             const char* a3 = a2 + kstep; const char* b3 = b2 + kstep;
;             if constexpr (SP2) {
;             PG8_LDB(B0, 0, 0); PG8_LDB(B1, 0, 1); PG8_SCHED; PG8_LDA(At, 0, 0); PG8_STAGE(PG8_SA(1, 1), a1 + hstepA, voffA);
;             PG8_WAIT_V(8); PG8_WAIT_L(0); PG8_BAR; PG8_MMA(0, 0, At, B0); PG8_MMA(0, 1, At, B1); PG8_BAR; PG8_SCHED;
;             PG8_LDA(At, 0, 1); PG8_STAGE(PG8_SB(0, 0), b2, voffB); PG8_STAGE(PG8_SB(0, 1), b2 + hstepB, voffB); PG8_STAGE(PG8_SA(0, 0), a2, voffA);
;             PG8_WAIT_V(8); PG8_WAIT_L(0); PG8_BAR; PG8_MMA(1, 0, At, B0); PG8_MMA(1, 1, At, B1); PG8_BAR; PG8_SCHED;
.LBB0_263:
	ds_read_b128 v[152:155], v149
	ds_read_b128 v[156:159], v149 offset:1024
	ds_read_b128 v[160:163], v149 offset:2048
	ds_read_b128 v[164:167], v149 offset:3072
	ds_read_b128 v[168:171], v150
	ds_read_b128 v[172:175], v150 offset:1024
	ds_read_b128 v[176:179], v150 offset:2048
	ds_read_b128 v[180:183], v150 offset:3072
	s_add_u32 s44, s34, 0xfffc0080
	s_addc_u32 s45, s35, -1
	s_cmp_eq_u32 s75, 12
	s_cselect_b32 s51, s27, s45
	s_cselect_b32 s50, s67, s44
	s_cselect_b32 s45, s25, s74
	s_cselect_b32 s44, s72, s73
	s_add_i32 m0, s41, 0xc000
	ds_read_b128 v[184:187], v151
	ds_read_b128 v[188:191], v151 offset:1024
	ds_read_b128 v[192:195], v151 offset:2048
	ds_read_b128 v[196:199], v151 offset:3072
	ds_read_b128 v[200:203], v151 offset:4096
	ds_read_b128 v[204:207], v151 offset:5120
	ds_read_b128 v[208:211], v151 offset:6144
	ds_read_b128 v[212:215], v151 offset:7168
	global_load_lds_dwordx4 v138, s[34:35]
	s_add_i32 m0, s41, 0xe000
	s_nop 0
	global_load_lds_dwordx4 v140, s[34:35]
	s_waitcnt vmcnt(8)
	s_waitcnt lgkmcnt(0)
	s_barrier
	v_mfma_f32_16x16x32_bf16 v[124:127], v[152:155], v[184:187], v[124:127]
	v_mfma_f32_16x16x32_bf16 v[120:123], v[160:163], v[184:187], v[120:123]
	v_mfma_f32_16x16x32_bf16 v[108:111], v[152:155], v[192:195], v[108:111]
	v_mfma_f32_16x16x32_bf16 v[104:107], v[160:163], v[192:195], v[104:107]
	v_mfma_f32_16x16x32_bf16 v[92:95], v[152:155], v[200:203], v[92:95]
	v_mfma_f32_16x16x32_bf16 v[88:91], v[160:163], v[200:203], v[88:91]
	v_mfma_f32_16x16x32_bf16 v[76:79], v[152:155], v[208:211], v[76:79]
	v_mfma_f32_16x16x32_bf16 v[72:75], v[160:163], v[208:211], v[72:75]
	v_mfma_f32_16x16x32_bf16 v[124:127], v[156:159], v[188:191], v[124:127]
	v_mfma_f32_16x16x32_bf16 v[120:123], v[164:167], v[188:191], v[120:123]
	v_mfma_f32_16x16x32_bf16 v[108:111], v[156:159], v[196:199], v[108:111]
	v_mfma_f32_16x16x32_bf16 v[104:107], v[164:167], v[196:199], v[104:107]
	v_mfma_f32_16x16x32_bf16 v[92:95], v[156:159], v[204:207], v[92:95]
	v_mfma_f32_16x16x32_bf16 v[88:91], v[164:167], v[204:207], v[88:91]
	v_mfma_f32_16x16x32_bf16 v[76:79], v[156:159], v[212:215], v[76:79]
	v_mfma_f32_16x16x32_bf16 v[72:75], v[164:167], v[212:215], v[72:75]
	v_mfma_f32_16x16x32_bf16 v[116:119], v[168:171], v[184:187], v[116:119]
	v_mfma_f32_16x16x32_bf16 v[112:115], v[176:179], v[184:187], v[112:115]
	v_mfma_f32_16x16x32_bf16 v[100:103], v[168:171], v[192:195], v[100:103]
	v_mfma_f32_16x16x32_bf16 v[96:99], v[176:179], v[192:195], v[96:99]
	v_mfma_f32_16x16x32_bf16 v[84:87], v[168:171], v[200:203], v[84:87]
	v_mfma_f32_16x16x32_bf16 v[80:83], v[176:179], v[200:203], v[80:83]
	v_mfma_f32_16x16x32_bf16 v[68:71], v[168:171], v[208:211], v[68:71]
	v_mfma_f32_16x16x32_bf16 v[64:67], v[176:179], v[208:211], v[64:67]
	v_mfma_f32_16x16x32_bf16 v[116:119], v[172:175], v[188:191], v[116:119]
	v_mfma_f32_16x16x32_bf16 v[112:115], v[180:183], v[188:191], v[112:115]
	v_mfma_f32_16x16x32_bf16 v[100:103], v[172:175], v[196:199], v[100:103]
	v_mfma_f32_16x16x32_bf16 v[96:99], v[180:183], v[196:199], v[96:99]
	v_mfma_f32_16x16x32_bf16 v[84:87], v[172:175], v[204:207], v[84:87]
	v_mfma_f32_16x16x32_bf16 v[80:83], v[180:183], v[204:207], v[80:83]
	v_mfma_f32_16x16x32_bf16 v[68:71], v[172:175], v[212:215], v[68:71]
	v_mfma_f32_16x16x32_bf16 v[64:67], v[180:183], v[212:215], v[64:67]
	s_barrier
	s_add_i32 s68, s64, s3
	v_lshl_add_u64 v[146:147], s[44:45], 0, v[134:135]
	s_mov_b32 m0, s68
	ds_read_b128 v[184:187], v151 offset:16384
	ds_read_b128 v[188:191], v151 offset:17408
	ds_read_b128 v[192:195], v151 offset:18432
	ds_read_b128 v[196:199], v151 offset:19456
	ds_read_b128 v[200:203], v151 offset:20480
	ds_read_b128 v[204:207], v151 offset:21504
	ds_read_b128 v[208:211], v151 offset:22528
	ds_read_b128 v[212:215], v151 offset:23552
	global_load_lds_dwordx4 v[146:147], off
	s_add_i32 m0, s68, 0x2000
	s_add_u32 s68, s44, 0x40000
	v_lshl_add_u64 v[216:217], s[44:45], 0, v[130:131]
	s_addc_u32 s69, s45, 0
	s_add_i32 s70, s65, s3
	global_load_lds_dwordx4 v[216:217], off
	s_mov_b32 m0, s70
	v_lshl_add_u64 v[220:221], s[50:51], 0, v[132:133]
	global_load_lds_dwordx4 v134, s[68:69]
	s_add_i32 m0, s70, 0x2000
	s_nop 0
	global_load_lds_dwordx4 v130, s[68:69]
	v_lshl_add_u64 v[218:219], s[50:51], 0, v[136:137]
	s_mov_b32 m0, s41
	s_nop 0
	global_load_lds_dwordx4 v[218:219], off
	s_mov_b32 m0, s54
	s_nop 0
	global_load_lds_dwordx4 v[220:221], off
	s_waitcnt vmcnt(8)
	s_waitcnt lgkmcnt(0)
	s_barrier
	v_mfma_f32_16x16x32_bf16 v[60:63], v[152:155], v[184:187], v[60:63]
	v_mfma_f32_16x16x32_bf16 v[56:59], v[160:163], v[184:187], v[56:59]
	v_mfma_f32_16x16x32_bf16 v[44:47], v[152:155], v[192:195], v[44:47]
	v_mfma_f32_16x16x32_bf16 v[40:43], v[160:163], v[192:195], v[40:43]
	v_mfma_f32_16x16x32_bf16 v[28:31], v[152:155], v[200:203], v[28:31]
	v_mfma_f32_16x16x32_bf16 v[24:27], v[160:163], v[200:203], v[24:27]
	v_mfma_f32_16x16x32_bf16 v[12:15], v[152:155], v[208:211], v[12:15]
	v_mfma_f32_16x16x32_bf16 v[8:11], v[160:163], v[208:211], v[8:11]
	v_mfma_f32_16x16x32_bf16 v[60:63], v[156:159], v[188:191], v[60:63]
	v_mfma_f32_16x16x32_bf16 v[56:59], v[164:167], v[188:191], v[56:59]
	v_mfma_f32_16x16x32_bf16 v[44:47], v[156:159], v[196:199], v[44:47]
	v_mfma_f32_16x16x32_bf16 v[40:43], v[164:167], v[196:199], v[40:43]
	v_mfma_f32_16x16x32_bf16 v[28:31], v[156:159], v[204:207], v[28:31]
	v_mfma_f32_16x16x32_bf16 v[24:27], v[164:167], v[204:207], v[24:27]
	v_mfma_f32_16x16x32_bf16 v[12:15], v[156:159], v[212:215], v[12:15]
	v_mfma_f32_16x16x32_bf16 v[8:11], v[164:167], v[212:215], v[8:11]
	v_mfma_f32_16x16x32_bf16 v[52:55], v[168:171], v[184:187], v[52:55]
	v_mfma_f32_16x16x32_bf16 v[48:51], v[176:179], v[184:187], v[48:51]
	v_mfma_f32_16x16x32_bf16 v[36:39], v[168:171], v[192:195], v[36:39]
	v_mfma_f32_16x16x32_bf16 v[32:35], v[176:179], v[192:195], v[32:35]
	v_mfma_f32_16x16x32_bf16 v[20:23], v[168:171], v[200:203], v[20:23]
	v_mfma_f32_16x16x32_bf16 v[16:19], v[176:179], v[200:203], v[16:19]
	v_mfma_f32_16x16x32_bf16 v[4:7], v[168:171], v[208:211], v[4:7]
	v_mfma_f32_16x16x32_bf16 v[0:3], v[176:179], v[208:211], v[0:3]
	v_mfma_f32_16x16x32_bf16 v[52:55], v[172:175], v[188:191], v[52:55]
	v_mfma_f32_16x16x32_bf16 v[48:51], v[180:183], v[188:191], v[48:51]
	v_mfma_f32_16x16x32_bf16 v[36:39], v[172:175], v[196:199], v[36:39]
	v_mfma_f32_16x16x32_bf16 v[32:35], v[180:183], v[196:199], v[32:35]
	v_mfma_f32_16x16x32_bf16 v[20:23], v[172:175], v[204:207], v[20:23]
	v_mfma_f32_16x16x32_bf16 v[16:19], v[180:183], v[204:207], v[16:19]
	v_mfma_f32_16x16x32_bf16 v[4:7], v[172:175], v[212:215], v[4:7]
	v_mfma_f32_16x16x32_bf16 v[0:3], v[180:183], v[212:215], v[0:3]
	s_barrier
; #define PG8_STAGE(bufoff, gbase, voff) do { _Pragma("unroll") for (int _i = 0; _i < 2; ++_i) \
;         __builtin_amdgcn_global_load_lds((const unsigned*)((const char*)(gbase) + (voff)[_i]), (LAS unsigned*)(lds + (bufoff) + ldsw + _i * 8192), 16, 0, 0); } while (0)
; #define PG8_LDA(dst, b, h) do { _Pragma("unroll") for (int m = 0; m < 4; ++m) _Pragma("unroll") for (int k = 0; k < 2; ++k) dst[m][k] = *(const LAS bf16x8*)(lds + PG8_SA(b, h) + aoff + m * 2048 + k * 1024); } while (0)
; #define PG8_LDB(dst, b, h) do { _Pragma("unroll") for (int n = 0; n < 2; ++n) _Pragma("unroll") for (int k = 0; k < 2; ++k) dst[n][k] = *(const LAS bf16x8*)(lds + PG8_SB(b, h) + boff + n * 2048 + k * 1024); } while (0)
; #define PG8_MMA(ai, bj, At, Bt) do { __builtin_amdgcn_s_setprio(1); _Pragma("unroll") for (int m = 0; m < 4; ++m) _Pragma("unroll") for (int n = 0; n < 2; ++n) _Pragma("unroll") for (int k = 0; k < 2; ++k) \
;         acc[ai][bj][m][n] = __builtin_amdgcn_mfma_f32_16x16x32_bf16(Bt[n][k], At[m][k], acc[ai][bj][m][n], 0, 0, 0); __builtin_amdgcn_s_setprio(0); } while (0)
; #define PG8_WAIT_V(n) asm volatile("s_waitcnt vmcnt(" #n ")" ::: "memory")
; #define PG8_WAIT_L(n) asm volatile("s_waitcnt lgkmcnt(" #n ")" ::: "memory")
; #define PG8_BAR __builtin_amdgcn_s_barrier()
; #define PG8_SCHED __builtin_amdgcn_sched_barrier(0)
; template <class Epi, bool SP2 = false>
; __device__ __forceinline__ void gemm_phase(LAS unsigned char* lds, const Gemm g, const StaticOrder& S, const Epi& E) {
;     ...
;             PG8_LDB(B0, 1, 0); PG8_LDB(B1, 1, 1); PG8_SCHED; PG8_LDA(At, 1, 0); PG8_STAGE(PG8_SA(0, 1), a2 + hstepA, voffA);
;             PG8_WAIT_V(8); PG8_WAIT_L(0); PG8_BAR; PG8_MMA(0, 0, At, B0); PG8_MMA(0, 1, At, B1); PG8_BAR; PG8_SCHED;
;             PG8_LDA(At, 1, 1); PG8_STAGE(PG8_SB(1, 0), b3, voffB); PG8_STAGE(PG8_SB(1, 1), b3 + hstepB, voffB); PG8_STAGE(PG8_SA(1, 0), a3, voffA);
;             PG8_WAIT_V(8); PG8_WAIT_L(0); PG8_BAR; PG8_MMA(1, 0, At, B0); PG8_MMA(1, 1, At, B1); PG8_BAR; PG8_SCHED;
;     ...
;         if constexpr (SP2) { if (wr == 0) PG8_BAR; }
	s_add_i32 s68, 0, 0x18000
	s_add_i32 s69, 0, 0x1c000
	v_add_u32_e32 v164, s68, v148
	v_add_u32_e32 v180, s69, v148
	ds_read_b128 v[152:155], v164
	ds_read_b128 v[156:159], v164 offset:1024
	ds_read_b128 v[160:163], v164 offset:2048
	ds_read_b128 v[164:167], v164 offset:3072
	ds_read_b128 v[168:171], v180
	ds_read_b128 v[172:175], v180 offset:1024
	ds_read_b128 v[176:179], v180 offset:2048
	ds_read_b128 v[180:183], v180 offset:3072
	s_add_u32 s50, s50, 0x40000
	s_addc_u32 s51, s51, 0
	s_mov_b32 m0, s55
	ds_read_b128 v[184:187], v151 offset:32768
	ds_read_b128 v[188:191], v151 offset:33792
	ds_read_b128 v[192:195], v151 offset:34816
	ds_read_b128 v[196:199], v151 offset:35840
	ds_read_b128 v[200:203], v151 offset:36864
	ds_read_b128 v[204:207], v151 offset:37888
	ds_read_b128 v[208:211], v151 offset:38912
	ds_read_b128 v[212:215], v151 offset:39936
	global_load_lds_dwordx4 v136, s[50:51]
	v_lshl_add_u64 v[222:223], s[50:51], 0, v[132:133]
	s_mov_b32 m0, s56
	s_nop 0
	global_load_lds_dwordx4 v[222:223], off
	s_waitcnt vmcnt(8)
	s_waitcnt lgkmcnt(0)
	s_barrier
	v_mfma_f32_16x16x32_bf16 v[124:127], v[152:155], v[184:187], v[124:127]
	v_mfma_f32_16x16x32_bf16 v[120:123], v[160:163], v[184:187], v[120:123]
	v_mfma_f32_16x16x32_bf16 v[108:111], v[152:155], v[192:195], v[108:111]
	v_mfma_f32_16x16x32_bf16 v[104:107], v[160:163], v[192:195], v[104:107]
	v_mfma_f32_16x16x32_bf16 v[92:95], v[152:155], v[200:203], v[92:95]
	v_mfma_f32_16x16x32_bf16 v[88:91], v[160:163], v[200:203], v[88:91]
	v_mfma_f32_16x16x32_bf16 v[76:79], v[152:155], v[208:211], v[76:79]
	v_mfma_f32_16x16x32_bf16 v[72:75], v[160:163], v[208:211], v[72:75]
	v_mfma_f32_16x16x32_bf16 v[124:127], v[156:159], v[188:191], v[124:127]
	v_mfma_f32_16x16x32_bf16 v[120:123], v[164:167], v[188:191], v[120:123]
	v_mfma_f32_16x16x32_bf16 v[108:111], v[156:159], v[196:199], v[108:111]
	v_mfma_f32_16x16x32_bf16 v[104:107], v[164:167], v[196:199], v[104:107]
	v_mfma_f32_16x16x32_bf16 v[92:95], v[156:159], v[204:207], v[92:95]
	v_mfma_f32_16x16x32_bf16 v[88:91], v[164:167], v[204:207], v[88:91]
	v_mfma_f32_16x16x32_bf16 v[76:79], v[156:159], v[212:215], v[76:79]
	v_mfma_f32_16x16x32_bf16 v[72:75], v[164:167], v[212:215], v[72:75]
	v_mfma_f32_16x16x32_bf16 v[116:119], v[168:171], v[184:187], v[116:119]
	v_mfma_f32_16x16x32_bf16 v[112:115], v[176:179], v[184:187], v[112:115]
	v_mfma_f32_16x16x32_bf16 v[100:103], v[168:171], v[192:195], v[100:103]
	v_mfma_f32_16x16x32_bf16 v[96:99], v[176:179], v[192:195], v[96:99]
	v_mfma_f32_16x16x32_bf16 v[84:87], v[168:171], v[200:203], v[84:87]
	v_mfma_f32_16x16x32_bf16 v[80:83], v[176:179], v[200:203], v[80:83]
	v_mfma_f32_16x16x32_bf16 v[68:71], v[168:171], v[208:211], v[68:71]
	v_mfma_f32_16x16x32_bf16 v[64:67], v[176:179], v[208:211], v[64:67]
	v_mfma_f32_16x16x32_bf16 v[116:119], v[172:175], v[188:191], v[116:119]
	v_mfma_f32_16x16x32_bf16 v[112:115], v[180:183], v[188:191], v[112:115]
	v_mfma_f32_16x16x32_bf16 v[100:103], v[172:175], v[196:199], v[100:103]
	v_mfma_f32_16x16x32_bf16 v[96:99], v[180:183], v[196:199], v[96:99]
	v_mfma_f32_16x16x32_bf16 v[84:87], v[172:175], v[204:207], v[84:87]
	v_mfma_f32_16x16x32_bf16 v[80:83], v[180:183], v[204:207], v[80:83]
	v_mfma_f32_16x16x32_bf16 v[68:71], v[172:175], v[212:215], v[68:71]
	v_mfma_f32_16x16x32_bf16 v[64:67], v[180:183], v[212:215], v[64:67]
	s_barrier
	s_add_i32 s50, s68, s3
	v_lshl_add_u64 v[146:147], v[146:147], 0, s[12:13]
	s_mov_b32 m0, s50
	ds_read_b128 v[184:187], v151 offset:49152
	ds_read_b128 v[188:191], v151 offset:50176
	ds_read_b128 v[192:195], v151 offset:51200
	ds_read_b128 v[196:199], v151 offset:52224
	ds_read_b128 v[200:203], v151 offset:53248
	ds_read_b128 v[204:207], v151 offset:54272
	ds_read_b128 v[208:211], v151 offset:55296
	ds_read_b128 v[212:215], v151 offset:56320
	global_load_lds_dwordx4 v[146:147], off
	s_add_i32 m0, s50, 0x2000
	s_add_u32 s44, s44, 0x40080
	v_lshl_add_u64 v[146:147], v[216:217], 0, s[12:13]
	s_addc_u32 s45, s45, 0
	s_add_i32 s50, s69, s3
	global_load_lds_dwordx4 v[146:147], off
	s_mov_b32 m0, s50
	s_nop 0
	global_load_lds_dwordx4 v134, s[44:45]
	s_add_i32 m0, s50, 0x2000
	s_nop 0
	global_load_lds_dwordx4 v130, s[44:45]
	v_lshl_add_u64 v[146:147], v[218:219], 0, s[12:13]
	s_mov_b32 m0, s60
	s_nop 0
	global_load_lds_dwordx4 v[146:147], off
	v_lshl_add_u64 v[146:147], v[220:221], 0, s[12:13]
	s_mov_b32 m0, s61
	s_nop 0
	global_load_lds_dwordx4 v[146:147], off
	s_waitcnt vmcnt(8)
	s_waitcnt lgkmcnt(0)
	s_barrier
	v_mfma_f32_16x16x32_bf16 v[60:63], v[152:155], v[184:187], v[60:63]
	v_mfma_f32_16x16x32_bf16 v[56:59], v[160:163], v[184:187], v[56:59]
	v_mfma_f32_16x16x32_bf16 v[44:47], v[152:155], v[192:195], v[44:47]
	v_mfma_f32_16x16x32_bf16 v[40:43], v[160:163], v[192:195], v[40:43]
	v_mfma_f32_16x16x32_bf16 v[28:31], v[152:155], v[200:203], v[28:31]
	v_mfma_f32_16x16x32_bf16 v[24:27], v[160:163], v[200:203], v[24:27]
	v_mfma_f32_16x16x32_bf16 v[12:15], v[152:155], v[208:211], v[12:15]
	v_mfma_f32_16x16x32_bf16 v[8:11], v[160:163], v[208:211], v[8:11]
	v_mfma_f32_16x16x32_bf16 v[60:63], v[156:159], v[188:191], v[60:63]
	v_mfma_f32_16x16x32_bf16 v[56:59], v[164:167], v[188:191], v[56:59]
	v_mfma_f32_16x16x32_bf16 v[44:47], v[156:159], v[196:199], v[44:47]
	v_mfma_f32_16x16x32_bf16 v[40:43], v[164:167], v[196:199], v[40:43]
	v_mfma_f32_16x16x32_bf16 v[28:31], v[156:159], v[204:207], v[28:31]
	v_mfma_f32_16x16x32_bf16 v[24:27], v[164:167], v[204:207], v[24:27]
	v_mfma_f32_16x16x32_bf16 v[12:15], v[156:159], v[212:215], v[12:15]
	v_mfma_f32_16x16x32_bf16 v[8:11], v[164:167], v[212:215], v[8:11]
	v_mfma_f32_16x16x32_bf16 v[52:55], v[168:171], v[184:187], v[52:55]
	v_mfma_f32_16x16x32_bf16 v[48:51], v[176:179], v[184:187], v[48:51]
	v_mfma_f32_16x16x32_bf16 v[36:39], v[168:171], v[192:195], v[36:39]
	v_mfma_f32_16x16x32_bf16 v[32:35], v[176:179], v[192:195], v[32:35]
	v_mfma_f32_16x16x32_bf16 v[20:23], v[168:171], v[200:203], v[20:23]
	v_mfma_f32_16x16x32_bf16 v[16:19], v[176:179], v[200:203], v[16:19]
	v_mfma_f32_16x16x32_bf16 v[4:7], v[168:171], v[208:211], v[4:7]
	v_mfma_f32_16x16x32_bf16 v[0:3], v[176:179], v[208:211], v[0:3]
	v_mfma_f32_16x16x32_bf16 v[52:55], v[172:175], v[188:191], v[52:55]
	v_mfma_f32_16x16x32_bf16 v[48:51], v[180:183], v[188:191], v[48:51]
	v_mfma_f32_16x16x32_bf16 v[36:39], v[172:175], v[196:199], v[36:39]
	v_mfma_f32_16x16x32_bf16 v[32:35], v[180:183], v[196:199], v[32:35]
	v_mfma_f32_16x16x32_bf16 v[20:23], v[172:175], v[204:207], v[20:23]
	v_mfma_f32_16x16x32_bf16 v[16:19], v[180:183], v[204:207], v[16:19]
	v_mfma_f32_16x16x32_bf16 v[4:7], v[172:175], v[212:215], v[4:7]
	v_mfma_f32_16x16x32_bf16 v[0:3], v[180:183], v[212:215], v[0:3]
	s_barrier
	s_add_i32 s75, s75, 2
	s_add_u32 s34, s34, 0x100
	s_addc_u32 s35, s35, 0
	s_add_u32 s73, s73, 0x100
	s_addc_u32 s74, s74, 0
	s_cmp_gt_u32 s75, 13
	s_cbranch_scc0 .LBB0_263
	s_and_b64 vcc, exec, s[18:19]
	s_cbranch_vccz .LBB0_266
	s_barrier

; #define PG8_STAGE(bufoff, gbase, voff) do { _Pragma("unroll") for (int _i = 0; _i < 2; ++_i) \
;         __builtin_amdgcn_global_load_lds((const unsigned*)((const char*)(gbase) + (voff)[_i]), (LAS unsigned*)(lds + (bufoff) + ldsw + _i * 8192), 16, 0, 0); } while (0)
; #define PG8_WAIT_V(n) asm volatile("s_waitcnt vmcnt(" #n ")" ::: "memory")
; #define PG8_BAR __builtin_amdgcn_s_barrier()
; template <class Epi, bool SP2 = false>
; __device__ __forceinline__ void gemm_phase(LAS unsigned char* lds, const Gemm g, const StaticOrder& S, const Epi& E) {
;     const int tid = threadIdx.x, wid = __builtin_amdgcn_readfirstlane(tid >> 6), lane = tid & 63, wr = wid >> 2, wc = wid & 3, fr = lane & 15, fq = lane >> 4;
;     const int K = g.K, nt = K / BK, lda = g.lda;
;     unsigned voffA[2], voffB[2];
; #pragma unroll
;     for (int i = 0; i < 2; ++i) { int R, C; stage_rc(tid * 16 + i * 8192, R, C); const int Rb = Epi::PERM ? ((R & ~31) + perm32(R & 31)) : R;
;         voffA[i] = (unsigned)(R * lda + C) * 2u; voffB[i] = (unsigned)(Rb * K + C) * 2u; }
;     const size_t kstep = (size_t)(BK * 2);
;     const size_t hstepA = (size_t)HALF * lda * 2, hstepB = (size_t)HALF * K * 2;
;     const size_t tstepA = 2 * hstepA, tstepB = 2 * hstepB;
;     const unsigned ldsw = (unsigned)wid * 1024u;
;     const int aoff = lds_byte(wr * 64 + fr, fq * 8), boff = lds_byte(wc * 32 + fr, fq * 8);
;     ...
;         PG8_WAIT_V(2); PG8_BAR;
;         PG8_STAGE(PG8_SB(1, 0), cB + kstep, voffB); PG8_STAGE(PG8_SA(1, 0), cA + kstep, voffA); PG8_STAGE(PG8_SB(1, 1), cB + hstepB + kstep, voffB);
;         PG8_WAIT_V(6); PG8_BAR;
.LBB0_324:
	s_lshl_b32 s1, s1, 5
	s_mov_b64 s[24:25], 0x80
	s_and_b32 s65, s1, 0x60
	s_add_i32 m0, s59, 0x18000
	v_lshl_add_u64 v[6:7], v[6:7], 0, s[24:25]
	s_lshl_b32 s64, s4, 6
	s_lshl_b32 s4, s4, 13
	s_lshl_b32 s1, s65, 7
	s_waitcnt vmcnt(2)
	s_barrier
	global_load_lds_dwordx4 v[6:7], off
	v_lshl_add_u64 v[4:5], v[4:5], 0, s[24:25]
	s_add_i32 m0, s59, 0x1a000
	s_add_i32 s66, s59, 0x8000
	s_add_i32 s67, s59, 0xa000
	global_load_lds_dwordx4 v[4:5], off
	v_lshl_add_u64 v[0:1], v[0:1], 0, s[24:25]
	s_mov_b32 m0, s66
	s_add_u32 s26, s52, 0xb0080
	global_load_lds_dwordx4 v[0:1], off
	v_lshl_add_u64 v[0:1], v[2:3], 0, s[24:25]
	s_mov_b32 m0, s67
	s_addc_u32 s27, s53, 0
	global_load_lds_dwordx4 v[0:1], off
	s_add_i32 m0, s59, 0x1c000
	s_nop 0
	global_load_lds_dwordx4 v134, s[26:27]
	v_lshl_add_u64 v[0:1], s[26:27], 0, v[130:131]
	s_add_i32 m0, s59, 0x1e000
	s_sext_i32_i8 s83, s5
	global_load_lds_dwordx4 v[0:1], off
	v_and_b32_e32 v0, 48, v128
	v_lshlrev_b32_e32 v1, 6, v128
	s_movk_i32 s5, 0x3c0
	v_and_or_b32 v0, v1, s5, v0
	v_lshlrev_b32_e32 v1, 2, v128
	v_and_b32_e32 v1, 32, v1
	v_bitop3_b32 v2, v0, s4, v1 bitop3:0xde
	v_bitop3_b32 v146, s1, v0, v1 bitop3:0xf6
	s_waitcnt vmcnt(6)
	s_cmpk_lt_u32 s0, 0x100
	v_add_u16_e32 v0, v8, v9
	s_cselect_b64 s[26:27], -1, 0
	v_lshrrev_b16_e32 v0, 1, v0
	s_add_i32 s74, 0, 0x10000
	s_add_i32 s75, 0, 0x14000
	s_ashr_i32 s72, s90, 31
	s_mov_b32 s73, s90
	v_add_lshl_u32 v138, v11, v0, 1
	v_mov_b32_e32 v139, v135
	v_add_lshl_u32 v140, v10, v0, 1
	v_mov_b32_e32 v141, v135
	v_mov_b64_e32 v[142:143], 0x600
	v_mov_b64_e32 v[144:145], 0x5ff
	v_add_u32_e32 v147, s74, v146
	v_add_u32_e32 v148, s75, v146
	v_add_u32_e32 v149, 0, v2
	s_mov_b64 s[28:29], 0x40000
	s_mov_b32 s76, 0x40000
	s_mov_b64 s[30:31], 0x48000
	s_mov_b32 s77, 0x48000
	s_waitcnt lgkmcnt(0)
	s_mov_b64 s[40:41], 0x50000
	s_mov_b32 s78, 0x50000
	s_mov_b64 s[44:45], 0x58000
	s_mov_b32 s79, 0x58000
	s_barrier
	s_branch .LBB0_327

; #define PG8_STAGE(bufoff, gbase, voff) do { _Pragma("unroll") for (int _i = 0; _i < 2; ++_i) \
;         __builtin_amdgcn_global_load_lds((const unsigned*)((const char*)(gbase) + (voff)[_i]), (LAS unsigned*)(lds + (bufoff) + ldsw + _i * 8192), 16, 0, 0); } while (0)
; #define PG8_LDA(dst, b, h) do { _Pragma("unroll") for (int m = 0; m < 4; ++m) _Pragma("unroll") for (int k = 0; k < 2; ++k) dst[m][k] = *(const LAS bf16x8*)(lds + PG8_SA(b, h) + aoff + m * 2048 + k * 1024); } while (0)
; #define PG8_LDB(dst, b, h) do { _Pragma("unroll") for (int n = 0; n < 2; ++n) _Pragma("unroll") for (int k = 0; k < 2; ++k) dst[n][k] = *(const LAS bf16x8*)(lds + PG8_SB(b, h) + boff + n * 2048 + k * 1024); } while (0)
; #define PG8_MMA(ai, bj, At, Bt) do { __builtin_amdgcn_s_setprio(1); _Pragma("unroll") for (int m = 0; m < 4; ++m) _Pragma("unroll") for (int n = 0; n < 2; ++n) _Pragma("unroll") for (int k = 0; k < 2; ++k) \
;         acc[ai][bj][m][n] = __builtin_amdgcn_mfma_f32_16x16x32_bf16(Bt[n][k], At[m][k], acc[ai][bj][m][n], 0, 0, 0); __builtin_amdgcn_s_setprio(0); } while (0)
; #define PG8_WAIT_V(n) asm volatile("s_waitcnt vmcnt(" #n ")" ::: "memory")
; #define PG8_WAIT_L(n) asm volatile("s_waitcnt lgkmcnt(" #n ")" ::: "memory")
; #define PG8_BAR __builtin_amdgcn_s_barrier()
; #define PG8_SCHED __builtin_amdgcn_sched_barrier(0)
; template <class Epi, bool SP2 = false>
; __device__ __forceinline__ void gemm_phase(LAS unsigned char* lds, const Gemm g, const StaticOrder& S, const Epi& E) {
;     ...
;             const bool last = (t == nt - 2);
;             const char* a1 = cA + (size_t)(t + 1) * kstep;
;             const char* a2 = last ? nA : cA + (size_t)(t + 2) * kstep; const char* b2 = last ? nB : cB + (size_t)(t + 2) * kstep;
;             const char* a3 = a2 + kstep; const char* b3 = b2 + kstep;
;             if constexpr (SP2) {
;             PG8_LDB(B0, 0, 0); PG8_LDB(B1, 0, 1); PG8_SCHED; PG8_LDA(At, 0, 0); PG8_STAGE(PG8_SA(1, 1), a1 + hstepA, voffA);
;             PG8_WAIT_V(8); PG8_WAIT_L(0); PG8_BAR; PG8_MMA(0, 0, At, B0); PG8_MMA(0, 1, At, B1); PG8_BAR; PG8_SCHED;
;             PG8_LDA(At, 0, 1); PG8_STAGE(PG8_SB(0, 0), b2, voffB); PG8_STAGE(PG8_SB(0, 1), b2 + hstepB, voffB); PG8_STAGE(PG8_SA(0, 0), a2, voffA);
;             PG8_WAIT_V(8); PG8_WAIT_L(0); PG8_BAR; PG8_MMA(1, 0, At, B0); PG8_MMA(1, 1, At, B1); PG8_BAR; PG8_SCHED;
.LBB0_334:
	ds_read_b128 v[150:153], v147
	ds_read_b128 v[154:157], v147 offset:1024
	ds_read_b128 v[158:161], v147 offset:2048
	ds_read_b128 v[162:165], v147 offset:3072
	ds_read_b128 v[166:169], v148
	ds_read_b128 v[170:173], v148 offset:1024
	ds_read_b128 v[174:177], v148 offset:2048
	ds_read_b128 v[178:181], v148 offset:3072
	s_add_u32 s52, s34, 0xfff50080
	s_addc_u32 s53, s35, -1
	s_cmp_eq_u32 s86, 40
	s_cselect_b32 s55, s5, s53
	s_cselect_b32 s54, s4, s52
	s_cselect_b32 s53, s51, s85
	s_cselect_b32 s52, s50, s84
	s_add_i32 m0, s59, 0xc000
	ds_read_b128 v[182:185], v149
	ds_read_b128 v[186:189], v149 offset:1024
	ds_read_b128 v[190:193], v149 offset:2048
	ds_read_b128 v[194:197], v149 offset:3072
	ds_read_b128 v[198:201], v149 offset:4096
	ds_read_b128 v[202:205], v149 offset:5120
	ds_read_b128 v[206:209], v149 offset:6144
	ds_read_b128 v[210:213], v149 offset:7168
	global_load_lds_dwordx4 v138, s[34:35]
	s_add_i32 m0, s59, 0xe000
	s_nop 0
	global_load_lds_dwordx4 v140, s[34:35]
	s_waitcnt vmcnt(8)
	s_waitcnt lgkmcnt(0)
	s_barrier
	v_mfma_f32_16x16x32_bf16 v[124:127], v[150:153], v[182:185], v[124:127]
	v_mfma_f32_16x16x32_bf16 v[120:123], v[158:161], v[182:185], v[120:123]
	v_mfma_f32_16x16x32_bf16 v[116:119], v[150:153], v[190:193], v[116:119]
	v_mfma_f32_16x16x32_bf16 v[112:115], v[158:161], v[190:193], v[112:115]
	v_mfma_f32_16x16x32_bf16 v[100:103], v[150:153], v[198:201], v[100:103]
	v_mfma_f32_16x16x32_bf16 v[96:99], v[158:161], v[198:201], v[96:99]
	v_mfma_f32_16x16x32_bf16 v[84:87], v[150:153], v[206:209], v[84:87]
	v_mfma_f32_16x16x32_bf16 v[80:83], v[158:161], v[206:209], v[80:83]
	v_mfma_f32_16x16x32_bf16 v[124:127], v[154:157], v[186:189], v[124:127]
	v_mfma_f32_16x16x32_bf16 v[120:123], v[162:165], v[186:189], v[120:123]
	v_mfma_f32_16x16x32_bf16 v[116:119], v[154:157], v[194:197], v[116:119]
	v_mfma_f32_16x16x32_bf16 v[112:115], v[162:165], v[194:197], v[112:115]
	v_mfma_f32_16x16x32_bf16 v[100:103], v[154:157], v[202:205], v[100:103]
	v_mfma_f32_16x16x32_bf16 v[96:99], v[162:165], v[202:205], v[96:99]
	v_mfma_f32_16x16x32_bf16 v[84:87], v[154:157], v[210:213], v[84:87]
	v_mfma_f32_16x16x32_bf16 v[80:83], v[162:165], v[210:213], v[80:83]
	v_mfma_f32_16x16x32_bf16 v[108:111], v[166:169], v[182:185], v[108:111]
	v_mfma_f32_16x16x32_bf16 v[104:107], v[174:177], v[182:185], v[104:107]
	v_mfma_f32_16x16x32_bf16 v[92:95], v[166:169], v[190:193], v[92:95]
	v_mfma_f32_16x16x32_bf16 v[88:91], v[174:177], v[190:193], v[88:91]
	v_mfma_f32_16x16x32_bf16 v[76:79], v[166:169], v[198:201], v[76:79]
	v_mfma_f32_16x16x32_bf16 v[72:75], v[174:177], v[198:201], v[72:75]
	v_mfma_f32_16x16x32_bf16 v[68:71], v[166:169], v[206:209], v[68:71]
	v_mfma_f32_16x16x32_bf16 v[64:67], v[174:177], v[206:209], v[64:67]
	v_mfma_f32_16x16x32_bf16 v[108:111], v[170:173], v[186:189], v[108:111]
	v_mfma_f32_16x16x32_bf16 v[104:107], v[178:181], v[186:189], v[104:107]
	v_mfma_f32_16x16x32_bf16 v[92:95], v[170:173], v[194:197], v[92:95]
	v_mfma_f32_16x16x32_bf16 v[88:91], v[178:181], v[194:197], v[88:91]
	v_mfma_f32_16x16x32_bf16 v[76:79], v[170:173], v[202:205], v[76:79]
	v_mfma_f32_16x16x32_bf16 v[72:75], v[178:181], v[202:205], v[72:75]
	v_mfma_f32_16x16x32_bf16 v[68:71], v[170:173], v[210:213], v[68:71]
	v_mfma_f32_16x16x32_bf16 v[64:67], v[178:181], v[210:213], v[64:67]
	s_barrier
	s_add_i32 s68, s74, s56
	v_lshl_add_u64 v[214:215], s[52:53], 0, v[134:135]
	s_mov_b32 m0, s68
	ds_read_b128 v[182:185], v149 offset:16384
	ds_read_b128 v[186:189], v149 offset:17408
	ds_read_b128 v[190:193], v149 offset:18432
	ds_read_b128 v[194:197], v149 offset:19456
	ds_read_b128 v[198:201], v149 offset:20480
	ds_read_b128 v[202:205], v149 offset:21504
	ds_read_b128 v[206:209], v149 offset:22528
	ds_read_b128 v[210:213], v149 offset:23552
	global_load_lds_dwordx4 v[214:215], off
	s_add_i32 m0, s68, 0x2000
	s_add_u32 s68, s52, 0xb0000
	v_lshl_add_u64 v[216:217], s[52:53], 0, v[130:131]
	s_addc_u32 s69, s53, 0
	s_add_i32 s70, s75, s56
	global_load_lds_dwordx4 v[216:217], off
	s_mov_b32 m0, s70
	v_lshl_add_u64 v[220:221], s[54:55], 0, v[132:133]
	global_load_lds_dwordx4 v134, s[68:69]
	s_add_i32 m0, s70, 0x2000
	s_nop 0
	global_load_lds_dwordx4 v130, s[68:69]
	v_lshl_add_u64 v[218:219], s[54:55], 0, v[136:137]
	s_mov_b32 m0, s59
	s_nop 0
	global_load_lds_dwordx4 v[218:219], off
	s_mov_b32 m0, s60
	s_nop 0
	global_load_lds_dwordx4 v[220:221], off
	s_waitcnt vmcnt(8)
	s_waitcnt lgkmcnt(0)
	s_barrier
	v_mfma_f32_16x16x32_bf16 v[60:63], v[150:153], v[182:185], v[60:63]
	v_mfma_f32_16x16x32_bf16 v[56:59], v[158:161], v[182:185], v[56:59]
	v_mfma_f32_16x16x32_bf16 v[52:55], v[150:153], v[190:193], v[52:55]
	v_mfma_f32_16x16x32_bf16 v[48:51], v[158:161], v[190:193], v[48:51]
	v_mfma_f32_16x16x32_bf16 v[36:39], v[150:153], v[198:201], v[36:39]
	v_mfma_f32_16x16x32_bf16 v[32:35], v[158:161], v[198:201], v[32:35]
	v_mfma_f32_16x16x32_bf16 v[20:23], v[150:153], v[206:209], v[20:23]
	v_mfma_f32_16x16x32_bf16 v[16:19], v[158:161], v[206:209], v[16:19]
	v_mfma_f32_16x16x32_bf16 v[60:63], v[154:157], v[186:189], v[60:63]
	v_mfma_f32_16x16x32_bf16 v[56:59], v[162:165], v[186:189], v[56:59]
	v_mfma_f32_16x16x32_bf16 v[52:55], v[154:157], v[194:197], v[52:55]
	v_mfma_f32_16x16x32_bf16 v[48:51], v[162:165], v[194:197], v[48:51]
	v_mfma_f32_16x16x32_bf16 v[36:39], v[154:157], v[202:205], v[36:39]
	v_mfma_f32_16x16x32_bf16 v[32:35], v[162:165], v[202:205], v[32:35]
	v_mfma_f32_16x16x32_bf16 v[20:23], v[154:157], v[210:213], v[20:23]
	v_mfma_f32_16x16x32_bf16 v[16:19], v[162:165], v[210:213], v[16:19]
	v_mfma_f32_16x16x32_bf16 v[44:47], v[166:169], v[182:185], v[44:47]
	v_mfma_f32_16x16x32_bf16 v[40:43], v[174:177], v[182:185], v[40:43]
	v_mfma_f32_16x16x32_bf16 v[28:31], v[166:169], v[190:193], v[28:31]
	v_mfma_f32_16x16x32_bf16 v[24:27], v[174:177], v[190:193], v[24:27]
	v_mfma_f32_16x16x32_bf16 v[12:15], v[166:169], v[198:201], v[12:15]
	v_mfma_f32_16x16x32_bf16 v[8:11], v[174:177], v[198:201], v[8:11]
	v_mfma_f32_16x16x32_bf16 v[4:7], v[166:169], v[206:209], v[4:7]
	v_mfma_f32_16x16x32_bf16 v[0:3], v[174:177], v[206:209], v[0:3]
	v_mfma_f32_16x16x32_bf16 v[44:47], v[170:173], v[186:189], v[44:47]
	v_mfma_f32_16x16x32_bf16 v[40:43], v[178:181], v[186:189], v[40:43]
	v_mfma_f32_16x16x32_bf16 v[28:31], v[170:173], v[194:197], v[28:31]
	v_mfma_f32_16x16x32_bf16 v[24:27], v[178:181], v[194:197], v[24:27]
	v_mfma_f32_16x16x32_bf16 v[12:15], v[170:173], v[202:205], v[12:15]
	v_mfma_f32_16x16x32_bf16 v[8:11], v[178:181], v[202:205], v[8:11]
	v_mfma_f32_16x16x32_bf16 v[4:7], v[170:173], v[210:213], v[4:7]
	v_mfma_f32_16x16x32_bf16 v[0:3], v[178:181], v[210:213], v[0:3]
	s_barrier
; #define PG8_STAGE(bufoff, gbase, voff) do { _Pragma("unroll") for (int _i = 0; _i < 2; ++_i) \
;         __builtin_amdgcn_global_load_lds((const unsigned*)((const char*)(gbase) + (voff)[_i]), (LAS unsigned*)(lds + (bufoff) + ldsw + _i * 8192), 16, 0, 0); } while (0)
; #define PG8_LDA(dst, b, h) do { _Pragma("unroll") for (int m = 0; m < 4; ++m) _Pragma("unroll") for (int k = 0; k < 2; ++k) dst[m][k] = *(const LAS bf16x8*)(lds + PG8_SA(b, h) + aoff + m * 2048 + k * 1024); } while (0)
; #define PG8_LDB(dst, b, h) do { _Pragma("unroll") for (int n = 0; n < 2; ++n) _Pragma("unroll") for (int k = 0; k < 2; ++k) dst[n][k] = *(const LAS bf16x8*)(lds + PG8_SB(b, h) + boff + n * 2048 + k * 1024); } while (0)
; #define PG8_MMA(ai, bj, At, Bt) do { __builtin_amdgcn_s_setprio(1); _Pragma("unroll") for (int m = 0; m < 4; ++m) _Pragma("unroll") for (int n = 0; n < 2; ++n) _Pragma("unroll") for (int k = 0; k < 2; ++k) \
;         acc[ai][bj][m][n] = __builtin_amdgcn_mfma_f32_16x16x32_bf16(Bt[n][k], At[m][k], acc[ai][bj][m][n], 0, 0, 0); __builtin_amdgcn_s_setprio(0); } while (0)
; #define PG8_WAIT_V(n) asm volatile("s_waitcnt vmcnt(" #n ")" ::: "memory")
; #define PG8_WAIT_L(n) asm volatile("s_waitcnt lgkmcnt(" #n ")" ::: "memory")
; #define PG8_BAR __builtin_amdgcn_s_barrier()
; #define PG8_SCHED __builtin_amdgcn_sched_barrier(0)
; template <class Epi, bool SP2 = false>
; __device__ __forceinline__ void gemm_phase(LAS unsigned char* lds, const Gemm g, const StaticOrder& S, const Epi& E) {
;     ...
;             PG8_LDB(B0, 1, 0); PG8_LDB(B1, 1, 1); PG8_SCHED; PG8_LDA(At, 1, 0); PG8_STAGE(PG8_SA(0, 1), a2 + hstepA, voffA);
;             PG8_WAIT_V(8); PG8_WAIT_L(0); PG8_BAR; PG8_MMA(0, 0, At, B0); PG8_MMA(0, 1, At, B1); PG8_BAR; PG8_SCHED;
;             PG8_LDA(At, 1, 1); PG8_STAGE(PG8_SB(1, 0), b3, voffB); PG8_STAGE(PG8_SB(1, 1), b3 + hstepB, voffB); PG8_STAGE(PG8_SA(1, 0), a3, voffA);
;             PG8_WAIT_V(8); PG8_WAIT_L(0); PG8_BAR; PG8_MMA(1, 0, At, B0); PG8_MMA(1, 1, At, B1); PG8_BAR; PG8_SCHED;
;     ...
;         if constexpr (SP2) { if (wr == 0) PG8_BAR; }
	s_add_i32 s68, 0, 0x18000
	s_add_i32 s69, 0, 0x1c000
	v_add_u32_e32 v162, s68, v146
	v_add_u32_e32 v178, s69, v146
	ds_read_b128 v[150:153], v162
	ds_read_b128 v[154:157], v162 offset:1024
	ds_read_b128 v[158:161], v162 offset:2048
	ds_read_b128 v[162:165], v162 offset:3072
	ds_read_b128 v[166:169], v178
	ds_read_b128 v[170:173], v178 offset:1024
	ds_read_b128 v[174:177], v178 offset:2048
	ds_read_b128 v[178:181], v178 offset:3072
	s_add_u32 s54, s54, 0xb0000
	s_addc_u32 s55, s55, 0
	s_mov_b32 m0, s61
	ds_read_b128 v[182:185], v149 offset:32768
	ds_read_b128 v[186:189], v149 offset:33792
	ds_read_b128 v[190:193], v149 offset:34816
	ds_read_b128 v[194:197], v149 offset:35840
	ds_read_b128 v[198:201], v149 offset:36864
	ds_read_b128 v[202:205], v149 offset:37888
	ds_read_b128 v[206:209], v149 offset:38912
	ds_read_b128 v[210:213], v149 offset:39936
	global_load_lds_dwordx4 v136, s[54:55]
	v_lshl_add_u64 v[222:223], s[54:55], 0, v[132:133]
	s_mov_b32 m0, s62
	s_nop 0
	global_load_lds_dwordx4 v[222:223], off
	s_waitcnt vmcnt(8)
	s_waitcnt lgkmcnt(0)
	s_barrier
	v_mfma_f32_16x16x32_bf16 v[124:127], v[150:153], v[182:185], v[124:127]
	v_mfma_f32_16x16x32_bf16 v[120:123], v[158:161], v[182:185], v[120:123]
	v_mfma_f32_16x16x32_bf16 v[116:119], v[150:153], v[190:193], v[116:119]
	v_mfma_f32_16x16x32_bf16 v[112:115], v[158:161], v[190:193], v[112:115]
	v_mfma_f32_16x16x32_bf16 v[100:103], v[150:153], v[198:201], v[100:103]
	v_mfma_f32_16x16x32_bf16 v[96:99], v[158:161], v[198:201], v[96:99]
	v_mfma_f32_16x16x32_bf16 v[84:87], v[150:153], v[206:209], v[84:87]
	v_mfma_f32_16x16x32_bf16 v[80:83], v[158:161], v[206:209], v[80:83]
	v_mfma_f32_16x16x32_bf16 v[124:127], v[154:157], v[186:189], v[124:127]
	v_mfma_f32_16x16x32_bf16 v[120:123], v[162:165], v[186:189], v[120:123]
	v_mfma_f32_16x16x32_bf16 v[116:119], v[154:157], v[194:197], v[116:119]
	v_mfma_f32_16x16x32_bf16 v[112:115], v[162:165], v[194:197], v[112:115]
	v_mfma_f32_16x16x32_bf16 v[100:103], v[154:157], v[202:205], v[100:103]
	v_mfma_f32_16x16x32_bf16 v[96:99], v[162:165], v[202:205], v[96:99]
	v_mfma_f32_16x16x32_bf16 v[84:87], v[154:157], v[210:213], v[84:87]
	v_mfma_f32_16x16x32_bf16 v[80:83], v[162:165], v[210:213], v[80:83]
	v_mfma_f32_16x16x32_bf16 v[108:111], v[166:169], v[182:185], v[108:111]
	v_mfma_f32_16x16x32_bf16 v[104:107], v[174:177], v[182:185], v[104:107]
	v_mfma_f32_16x16x32_bf16 v[92:95], v[166:169], v[190:193], v[92:95]
	v_mfma_f32_16x16x32_bf16 v[88:91], v[174:177], v[190:193], v[88:91]
	v_mfma_f32_16x16x32_bf16 v[76:79], v[166:169], v[198:201], v[76:79]
	v_mfma_f32_16x16x32_bf16 v[72:75], v[174:177], v[198:201], v[72:75]
	v_mfma_f32_16x16x32_bf16 v[68:71], v[166:169], v[206:209], v[68:71]
	v_mfma_f32_16x16x32_bf16 v[64:67], v[174:177], v[206:209], v[64:67]
	v_mfma_f32_16x16x32_bf16 v[108:111], v[170:173], v[186:189], v[108:111]
	v_mfma_f32_16x16x32_bf16 v[104:107], v[178:181], v[186:189], v[104:107]
	v_mfma_f32_16x16x32_bf16 v[92:95], v[170:173], v[194:197], v[92:95]
	v_mfma_f32_16x16x32_bf16 v[88:91], v[178:181], v[194:197], v[88:91]
	v_mfma_f32_16x16x32_bf16 v[76:79], v[170:173], v[202:205], v[76:79]
	v_mfma_f32_16x16x32_bf16 v[72:75], v[178:181], v[202:205], v[72:75]
	v_mfma_f32_16x16x32_bf16 v[68:71], v[170:173], v[210:213], v[68:71]
	v_mfma_f32_16x16x32_bf16 v[64:67], v[178:181], v[210:213], v[64:67]
	s_barrier
	s_add_i32 s54, s68, s56
	v_lshl_add_u64 v[214:215], v[214:215], 0, s[24:25]
	s_mov_b32 m0, s54
	ds_read_b128 v[182:185], v149 offset:49152
	ds_read_b128 v[186:189], v149 offset:50176
	ds_read_b128 v[190:193], v149 offset:51200
	ds_read_b128 v[194:197], v149 offset:52224
	ds_read_b128 v[198:201], v149 offset:53248
	ds_read_b128 v[202:205], v149 offset:54272
	ds_read_b128 v[206:209], v149 offset:55296
	ds_read_b128 v[210:213], v149 offset:56320
	global_load_lds_dwordx4 v[214:215], off
	s_add_i32 m0, s54, 0x2000
	s_add_u32 s52, s52, 0xb0080
	v_lshl_add_u64 v[214:215], v[216:217], 0, s[24:25]
	s_addc_u32 s53, s53, 0
	s_add_i32 s54, s69, s56
	global_load_lds_dwordx4 v[214:215], off
	s_mov_b32 m0, s54
	s_nop 0
	global_load_lds_dwordx4 v134, s[52:53]
	s_add_i32 m0, s54, 0x2000
	s_nop 0
	global_load_lds_dwordx4 v130, s[52:53]
	v_lshl_add_u64 v[214:215], v[218:219], 0, s[24:25]
	s_mov_b32 m0, s66
	s_nop 0
	global_load_lds_dwordx4 v[214:215], off
	v_lshl_add_u64 v[214:215], v[220:221], 0, s[24:25]
	s_mov_b32 m0, s67
	s_nop 0
	global_load_lds_dwordx4 v[214:215], off
	s_waitcnt vmcnt(8)
	s_waitcnt lgkmcnt(0)
	s_barrier
	v_mfma_f32_16x16x32_bf16 v[60:63], v[150:153], v[182:185], v[60:63]
	v_mfma_f32_16x16x32_bf16 v[56:59], v[158:161], v[182:185], v[56:59]
	v_mfma_f32_16x16x32_bf16 v[52:55], v[150:153], v[190:193], v[52:55]
	v_mfma_f32_16x16x32_bf16 v[48:51], v[158:161], v[190:193], v[48:51]
	v_mfma_f32_16x16x32_bf16 v[36:39], v[150:153], v[198:201], v[36:39]
	v_mfma_f32_16x16x32_bf16 v[32:35], v[158:161], v[198:201], v[32:35]
	v_mfma_f32_16x16x32_bf16 v[20:23], v[150:153], v[206:209], v[20:23]
	v_mfma_f32_16x16x32_bf16 v[16:19], v[158:161], v[206:209], v[16:19]
	v_mfma_f32_16x16x32_bf16 v[60:63], v[154:157], v[186:189], v[60:63]
	v_mfma_f32_16x16x32_bf16 v[56:59], v[162:165], v[186:189], v[56:59]
	v_mfma_f32_16x16x32_bf16 v[52:55], v[154:157], v[194:197], v[52:55]
	v_mfma_f32_16x16x32_bf16 v[48:51], v[162:165], v[194:197], v[48:51]
	v_mfma_f32_16x16x32_bf16 v[36:39], v[154:157], v[202:205], v[36:39]
	v_mfma_f32_16x16x32_bf16 v[32:35], v[162:165], v[202:205], v[32:35]
	v_mfma_f32_16x16x32_bf16 v[20:23], v[154:157], v[210:213], v[20:23]
	v_mfma_f32_16x16x32_bf16 v[16:19], v[162:165], v[210:213], v[16:19]
	v_mfma_f32_16x16x32_bf16 v[44:47], v[166:169], v[182:185], v[44:47]
	v_mfma_f32_16x16x32_bf16 v[40:43], v[174:177], v[182:185], v[40:43]
	v_mfma_f32_16x16x32_bf16 v[28:31], v[166:169], v[190:193], v[28:31]
	v_mfma_f32_16x16x32_bf16 v[24:27], v[174:177], v[190:193], v[24:27]
	v_mfma_f32_16x16x32_bf16 v[12:15], v[166:169], v[198:201], v[12:15]
	v_mfma_f32_16x16x32_bf16 v[8:11], v[174:177], v[198:201], v[8:11]
	v_mfma_f32_16x16x32_bf16 v[4:7], v[166:169], v[206:209], v[4:7]
	v_mfma_f32_16x16x32_bf16 v[0:3], v[174:177], v[206:209], v[0:3]
	v_mfma_f32_16x16x32_bf16 v[44:47], v[170:173], v[186:189], v[44:47]
	v_mfma_f32_16x16x32_bf16 v[40:43], v[178:181], v[186:189], v[40:43]
	v_mfma_f32_16x16x32_bf16 v[28:31], v[170:173], v[194:197], v[28:31]
	v_mfma_f32_16x16x32_bf16 v[24:27], v[178:181], v[194:197], v[24:27]
	v_mfma_f32_16x16x32_bf16 v[12:15], v[170:173], v[202:205], v[12:15]
	v_mfma_f32_16x16x32_bf16 v[8:11], v[178:181], v[202:205], v[8:11]
	v_mfma_f32_16x16x32_bf16 v[4:7], v[170:173], v[210:213], v[4:7]
	v_mfma_f32_16x16x32_bf16 v[0:3], v[178:181], v[210:213], v[0:3]
	s_barrier
	s_add_i32 s86, s86, 2
	s_add_u32 s34, s34, 0x100
	s_addc_u32 s35, s35, 0
	s_add_u32 s84, s84, 0x100
	s_addc_u32 s85, s85, 0
	s_cmp_gt_u32 s86, 41
	s_cbranch_scc0 .LBB0_334
	s_and_b64 vcc, exec, s[26:27]
	s_cbranch_vccz .LBB0_337
	s_barrier

; #define PG8_STAGE(bufoff, gbase, voff) do { _Pragma("unroll") for (int _i = 0; _i < 2; ++_i) \
;         __builtin_amdgcn_global_load_lds((const unsigned*)((const char*)(gbase) + (voff)[_i]), (LAS unsigned*)(lds + (bufoff) + ldsw + _i * 8192), 16, 0, 0); } while (0)
; #define PG8_WAIT_V(n) asm volatile("s_waitcnt vmcnt(" #n ")" ::: "memory")
; #define PG8_BAR __builtin_amdgcn_s_barrier()
; template <class Epi, bool SP2 = false>
; __device__ __forceinline__ void gemm_phase(LAS unsigned char* lds, const Gemm g, const StaticOrder& S, const Epi& E) {
;     const int tid = threadIdx.x, wid = __builtin_amdgcn_readfirstlane(tid >> 6), lane = tid & 63, wr = wid >> 2, wc = wid & 3, fr = lane & 15, fq = lane >> 4;
;     const int K = g.K, nt = K / BK, lda = g.lda;
;     unsigned voffA[2], voffB[2];
; #pragma unroll
;     for (int i = 0; i < 2; ++i) { int R, C; stage_rc(tid * 16 + i * 8192, R, C); const int Rb = Epi::PERM ? ((R & ~31) + perm32(R & 31)) : R;
;         voffA[i] = (unsigned)(R * lda + C) * 2u; voffB[i] = (unsigned)(Rb * K + C) * 2u; }
;     const size_t kstep = (size_t)(BK * 2);
;     const size_t hstepA = (size_t)HALF * lda * 2, hstepB = (size_t)HALF * K * 2;
;     const size_t tstepA = 2 * hstepA, tstepB = 2 * hstepB;
;     const unsigned ldsw = (unsigned)wid * 1024u;
;     const int aoff = lds_byte(wr * 64 + fr, fq * 8), boff = lds_byte(wc * 32 + fr, fq * 8);
;     ...
;         PG8_WAIT_V(2); PG8_BAR;
;         PG8_STAGE(PG8_SB(1, 0), cB + kstep, voffB); PG8_STAGE(PG8_SA(1, 0), cA + kstep, voffA); PG8_STAGE(PG8_SB(1, 1), cB + hstepB + kstep, voffB);
;         PG8_WAIT_V(6); PG8_BAR;
.LBB0_456:
	s_lshl_b32 s58, s0, 6
	s_lshl_b32 s5, s0, 13
	s_lshl_b32 s0, s1, 5
	s_mov_b64 s[10:11], 0x80
	s_and_b32 s59, s0, 0x60
	s_add_i32 m0, s31, 0x18000
	v_lshl_add_u64 v[6:7], v[6:7], 0, s[10:11]
	s_lshl_b32 s13, s59, 7
	s_waitcnt vmcnt(2)
	s_barrier
	global_load_lds_dwordx4 v[6:7], off
	v_lshl_add_u64 v[4:5], v[4:5], 0, s[10:11]
	s_add_i32 m0, s31, 0x1a000
	s_add_i32 s60, s31, 0x8000
	s_add_i32 s61, s31, 0xa000
	global_load_lds_dwordx4 v[4:5], off
	v_lshl_add_u64 v[0:1], v[0:1], 0, s[10:11]
	s_mov_b32 m0, s60
	s_add_u32 s0, s44, 0x40080
	global_load_lds_dwordx4 v[0:1], off
	v_lshl_add_u64 v[0:1], v[2:3], 0, s[10:11]
	s_mov_b32 m0, s61
	s_addc_u32 s1, s45, 0
	global_load_lds_dwordx4 v[0:1], off
	s_add_i32 m0, s31, 0x1c000
	s_nop 0
	global_load_lds_dwordx4 v132, s[0:1]
	v_lshl_add_u64 v[0:1], s[0:1], 0, v[136:137]
	s_add_i32 m0, s31, 0x1e000
	s_movk_i32 s0, 0x3c0
	global_load_lds_dwordx4 v[0:1], off
	v_and_b32_e32 v0, 48, v128
	v_lshlrev_b32_e32 v1, 6, v128
	v_and_or_b32 v0, v1, s0, v0
	v_lshlrev_b32_e32 v1, 2, v128
	v_and_b32_e32 v1, 32, v1
	v_bitop3_b32 v2, v0, s5, v1 bitop3:0xde
	v_bitop3_b32 v152, s13, v0, v1 bitop3:0xf6
	v_lshlrev_b32_e32 v0, 8, v128
	v_and_b32_e32 v0, 0x38000, v0
	v_lshlrev_b32_e32 v1, 11, v10
	v_or3_b32 v0, v8, v0, v1
	v_add_u32_e32 v138, v0, v9
	v_lshlrev_b32_e32 v0, 4, v11
	s_waitcnt vmcnt(6)
	s_cmpk_lt_u32 s12, 0x100
	v_and_b32_e32 v0, 0x78000, v0
	s_cselect_b64 s[12:13], -1, 0
	v_or3_b32 v0, v8, v0, v1
	s_add_i32 s66, 0, 0x10000
	s_add_i32 s67, 0, 0x14000
	s_ashr_i32 s62, s90, 31
	s_mov_b32 s63, s90
	s_ashr_i32 s64, s2, 31
	v_mov_b32_e32 v139, v133
	v_add_u32_e32 v140, v0, v9
	v_mov_b32_e32 v141, v133
	v_mov_b64_e32 v[142:143], 0xf00
	v_mov_b64_e32 v[144:145], 0xeff
	s_movk_i32 s65, 0x1e1
	v_add_u32_e32 v153, s66, v152
	v_add_u32_e32 v154, s67, v152
	v_add_u32_e32 v155, 0, v2
	s_barrier
	s_branch .LBB0_459

; #define PG8_STAGE(bufoff, gbase, voff) do { _Pragma("unroll") for (int _i = 0; _i < 2; ++_i) \
;         __builtin_amdgcn_global_load_lds((const unsigned*)((const char*)(gbase) + (voff)[_i]), (LAS unsigned*)(lds + (bufoff) + ldsw + _i * 8192), 16, 0, 0); } while (0)
; #define PG8_LDA(dst, b, h) do { _Pragma("unroll") for (int m = 0; m < 4; ++m) _Pragma("unroll") for (int k = 0; k < 2; ++k) dst[m][k] = *(const LAS bf16x8*)(lds + PG8_SA(b, h) + aoff + m * 2048 + k * 1024); } while (0)
; #define PG8_LDB(dst, b, h) do { _Pragma("unroll") for (int n = 0; n < 2; ++n) _Pragma("unroll") for (int k = 0; k < 2; ++k) dst[n][k] = *(const LAS bf16x8*)(lds + PG8_SB(b, h) + boff + n * 2048 + k * 1024); } while (0)
; #define PG8_MMA(ai, bj, At, Bt) do { __builtin_amdgcn_s_setprio(1); _Pragma("unroll") for (int m = 0; m < 4; ++m) _Pragma("unroll") for (int n = 0; n < 2; ++n) _Pragma("unroll") for (int k = 0; k < 2; ++k) \
;         acc[ai][bj][m][n] = __builtin_amdgcn_mfma_f32_16x16x32_bf16(Bt[n][k], At[m][k], acc[ai][bj][m][n], 0, 0, 0); __builtin_amdgcn_s_setprio(0); } while (0)
; #define PG8_WAIT_V(n) asm volatile("s_waitcnt vmcnt(" #n ")" ::: "memory")
; #define PG8_WAIT_L(n) asm volatile("s_waitcnt lgkmcnt(" #n ")" ::: "memory")
; #define PG8_BAR __builtin_amdgcn_s_barrier()
; #define PG8_SCHED __builtin_amdgcn_sched_barrier(0)
; template <class Epi, bool SP2 = false>
; __device__ __forceinline__ void gemm_phase(LAS unsigned char* lds, const Gemm g, const StaticOrder& S, const Epi& E) {
;     ...
;             const bool last = (t == nt - 2);
;             const char* a1 = cA + (size_t)(t + 1) * kstep;
;             const char* a2 = last ? nA : cA + (size_t)(t + 2) * kstep; const char* b2 = last ? nB : cB + (size_t)(t + 2) * kstep;
;             const char* a3 = a2 + kstep; const char* b3 = b2 + kstep;
;             if constexpr (SP2) {
;             PG8_LDB(B0, 0, 0); PG8_LDB(B1, 0, 1); PG8_SCHED; PG8_LDA(At, 0, 0); PG8_STAGE(PG8_SA(1, 1), a1 + hstepA, voffA);
;             PG8_WAIT_V(8); PG8_WAIT_L(0); PG8_BAR; PG8_MMA(0, 0, At, B0); PG8_MMA(0, 1, At, B1); PG8_BAR; PG8_SCHED;
;             PG8_LDA(At, 0, 1); PG8_STAGE(PG8_SB(0, 0), b2, voffB); PG8_STAGE(PG8_SB(0, 1), b2 + hstepB, voffB); PG8_STAGE(PG8_SA(0, 0), a2, voffA);
;             PG8_WAIT_V(8); PG8_WAIT_L(0); PG8_BAR; PG8_MMA(1, 0, At, B0); PG8_MMA(1, 1, At, B1); PG8_BAR; PG8_SCHED;
.LBB0_462:
	ds_read_b128 v[146:149], v153
	ds_read_b128 v[156:159], v153 offset:1024
	ds_read_b128 v[160:163], v153 offset:2048
	ds_read_b128 v[164:167], v153 offset:3072
	ds_read_b128 v[168:171], v154
	ds_read_b128 v[172:175], v154 offset:1024
	ds_read_b128 v[176:179], v154 offset:2048
	ds_read_b128 v[180:183], v154 offset:3072
	s_add_u32 s44, s34, 0xfffc0080
	s_addc_u32 s45, s35, -1
	s_cmp_eq_u32 s74, 12
	s_cselect_b32 s51, s5, s45
	s_cselect_b32 s50, s27, s44
	s_cselect_b32 s45, s25, s73
	s_cselect_b32 s44, s33, s72
	s_add_i32 m0, s31, 0xc000
	ds_read_b128 v[184:187], v155
	ds_read_b128 v[188:191], v155 offset:1024
	ds_read_b128 v[192:195], v155 offset:2048
	ds_read_b128 v[196:199], v155 offset:3072
	ds_read_b128 v[200:203], v155 offset:4096
	ds_read_b128 v[204:207], v155 offset:5120
	ds_read_b128 v[208:211], v155 offset:6144
	ds_read_b128 v[212:215], v155 offset:7168
	global_load_lds_dwordx4 v138, s[34:35]
	s_add_i32 m0, s31, 0xe000
	s_nop 0
	global_load_lds_dwordx4 v140, s[34:35]
	s_waitcnt vmcnt(8)
	s_waitcnt lgkmcnt(0)
	s_barrier
	v_mfma_f32_16x16x32_bf16 v[124:127], v[146:149], v[184:187], v[124:127]
	v_mfma_f32_16x16x32_bf16 v[120:123], v[160:163], v[184:187], v[120:123]
	v_mfma_f32_16x16x32_bf16 v[108:111], v[146:149], v[192:195], v[108:111]
	v_mfma_f32_16x16x32_bf16 v[104:107], v[160:163], v[192:195], v[104:107]
	v_mfma_f32_16x16x32_bf16 v[92:95], v[146:149], v[200:203], v[92:95]
	v_mfma_f32_16x16x32_bf16 v[88:91], v[160:163], v[200:203], v[88:91]
	v_mfma_f32_16x16x32_bf16 v[76:79], v[146:149], v[208:211], v[76:79]
	v_mfma_f32_16x16x32_bf16 v[72:75], v[160:163], v[208:211], v[72:75]
	v_mfma_f32_16x16x32_bf16 v[124:127], v[156:159], v[188:191], v[124:127]
	v_mfma_f32_16x16x32_bf16 v[120:123], v[164:167], v[188:191], v[120:123]
	v_mfma_f32_16x16x32_bf16 v[108:111], v[156:159], v[196:199], v[108:111]
	v_mfma_f32_16x16x32_bf16 v[104:107], v[164:167], v[196:199], v[104:107]
	v_mfma_f32_16x16x32_bf16 v[92:95], v[156:159], v[204:207], v[92:95]
	v_mfma_f32_16x16x32_bf16 v[88:91], v[164:167], v[204:207], v[88:91]
	v_mfma_f32_16x16x32_bf16 v[76:79], v[156:159], v[212:215], v[76:79]
	v_mfma_f32_16x16x32_bf16 v[72:75], v[164:167], v[212:215], v[72:75]
	v_mfma_f32_16x16x32_bf16 v[116:119], v[168:171], v[184:187], v[116:119]
	v_mfma_f32_16x16x32_bf16 v[112:115], v[176:179], v[184:187], v[112:115]
	v_mfma_f32_16x16x32_bf16 v[100:103], v[168:171], v[192:195], v[100:103]
	v_mfma_f32_16x16x32_bf16 v[96:99], v[176:179], v[192:195], v[96:99]
	v_mfma_f32_16x16x32_bf16 v[84:87], v[168:171], v[200:203], v[84:87]
	v_mfma_f32_16x16x32_bf16 v[80:83], v[176:179], v[200:203], v[80:83]
	v_mfma_f32_16x16x32_bf16 v[68:71], v[168:171], v[208:211], v[68:71]
	v_mfma_f32_16x16x32_bf16 v[64:67], v[176:179], v[208:211], v[64:67]
	v_mfma_f32_16x16x32_bf16 v[116:119], v[172:175], v[188:191], v[116:119]
	v_mfma_f32_16x16x32_bf16 v[112:115], v[180:183], v[188:191], v[112:115]
	v_mfma_f32_16x16x32_bf16 v[100:103], v[172:175], v[196:199], v[100:103]
	v_mfma_f32_16x16x32_bf16 v[96:99], v[180:183], v[196:199], v[96:99]
	v_mfma_f32_16x16x32_bf16 v[84:87], v[172:175], v[204:207], v[84:87]
	v_mfma_f32_16x16x32_bf16 v[80:83], v[180:183], v[204:207], v[80:83]
	v_mfma_f32_16x16x32_bf16 v[68:71], v[172:175], v[212:215], v[68:71]
	v_mfma_f32_16x16x32_bf16 v[64:67], v[180:183], v[212:215], v[64:67]
	s_barrier
	s_add_i32 s68, s66, s53
	v_lshl_add_u64 v[150:151], s[44:45], 0, v[132:133]
	s_mov_b32 m0, s68
	ds_read_b128 v[184:187], v155 offset:16384
	ds_read_b128 v[188:191], v155 offset:17408
	ds_read_b128 v[192:195], v155 offset:18432
	ds_read_b128 v[196:199], v155 offset:19456
	ds_read_b128 v[200:203], v155 offset:20480
	ds_read_b128 v[204:207], v155 offset:21504
	ds_read_b128 v[208:211], v155 offset:22528
	ds_read_b128 v[212:215], v155 offset:23552
	global_load_lds_dwordx4 v[150:151], off
	s_add_i32 m0, s68, 0x2000
	s_add_u32 s68, s44, 0x40000
	v_lshl_add_u64 v[216:217], s[44:45], 0, v[136:137]
	s_addc_u32 s69, s45, 0
	s_add_i32 s70, s67, s53
	global_load_lds_dwordx4 v[216:217], off
	s_mov_b32 m0, s70
	v_lshl_add_u64 v[220:221], s[50:51], 0, v[134:135]
	global_load_lds_dwordx4 v132, s[68:69]
	s_add_i32 m0, s70, 0x2000
	s_nop 0
	global_load_lds_dwordx4 v136, s[68:69]
	v_lshl_add_u64 v[218:219], s[50:51], 0, v[130:131]
	s_mov_b32 m0, s31
	s_nop 0
	global_load_lds_dwordx4 v[218:219], off
	s_mov_b32 m0, s54
	s_nop 0
	global_load_lds_dwordx4 v[220:221], off
	s_waitcnt vmcnt(8)
	s_waitcnt lgkmcnt(0)
	s_barrier
	v_mfma_f32_16x16x32_bf16 v[60:63], v[146:149], v[184:187], v[60:63]
	v_mfma_f32_16x16x32_bf16 v[56:59], v[160:163], v[184:187], v[56:59]
	v_mfma_f32_16x16x32_bf16 v[44:47], v[146:149], v[192:195], v[44:47]
	v_mfma_f32_16x16x32_bf16 v[40:43], v[160:163], v[192:195], v[40:43]
	v_mfma_f32_16x16x32_bf16 v[28:31], v[146:149], v[200:203], v[28:31]
	v_mfma_f32_16x16x32_bf16 v[24:27], v[160:163], v[200:203], v[24:27]
	v_mfma_f32_16x16x32_bf16 v[12:15], v[146:149], v[208:211], v[12:15]
	v_mfma_f32_16x16x32_bf16 v[8:11], v[160:163], v[208:211], v[8:11]
	v_mfma_f32_16x16x32_bf16 v[60:63], v[156:159], v[188:191], v[60:63]
	v_mfma_f32_16x16x32_bf16 v[56:59], v[164:167], v[188:191], v[56:59]
	v_mfma_f32_16x16x32_bf16 v[44:47], v[156:159], v[196:199], v[44:47]
	v_mfma_f32_16x16x32_bf16 v[40:43], v[164:167], v[196:199], v[40:43]
	v_mfma_f32_16x16x32_bf16 v[28:31], v[156:159], v[204:207], v[28:31]
	v_mfma_f32_16x16x32_bf16 v[24:27], v[164:167], v[204:207], v[24:27]
	v_mfma_f32_16x16x32_bf16 v[12:15], v[156:159], v[212:215], v[12:15]
	v_mfma_f32_16x16x32_bf16 v[8:11], v[164:167], v[212:215], v[8:11]
	v_mfma_f32_16x16x32_bf16 v[52:55], v[168:171], v[184:187], v[52:55]
	v_mfma_f32_16x16x32_bf16 v[48:51], v[176:179], v[184:187], v[48:51]
	v_mfma_f32_16x16x32_bf16 v[36:39], v[168:171], v[192:195], v[36:39]
	v_mfma_f32_16x16x32_bf16 v[32:35], v[176:179], v[192:195], v[32:35]
	v_mfma_f32_16x16x32_bf16 v[20:23], v[168:171], v[200:203], v[20:23]
	v_mfma_f32_16x16x32_bf16 v[16:19], v[176:179], v[200:203], v[16:19]
	v_mfma_f32_16x16x32_bf16 v[4:7], v[168:171], v[208:211], v[4:7]
	v_mfma_f32_16x16x32_bf16 v[0:3], v[176:179], v[208:211], v[0:3]
	v_mfma_f32_16x16x32_bf16 v[52:55], v[172:175], v[188:191], v[52:55]
	v_mfma_f32_16x16x32_bf16 v[48:51], v[180:183], v[188:191], v[48:51]
	v_mfma_f32_16x16x32_bf16 v[36:39], v[172:175], v[196:199], v[36:39]
	v_mfma_f32_16x16x32_bf16 v[32:35], v[180:183], v[196:199], v[32:35]
	v_mfma_f32_16x16x32_bf16 v[20:23], v[172:175], v[204:207], v[20:23]
	v_mfma_f32_16x16x32_bf16 v[16:19], v[180:183], v[204:207], v[16:19]
	v_mfma_f32_16x16x32_bf16 v[4:7], v[172:175], v[212:215], v[4:7]
	v_mfma_f32_16x16x32_bf16 v[0:3], v[180:183], v[212:215], v[0:3]
	s_barrier
; #define PG8_STAGE(bufoff, gbase, voff) do { _Pragma("unroll") for (int _i = 0; _i < 2; ++_i) \
;         __builtin_amdgcn_global_load_lds((const unsigned*)((const char*)(gbase) + (voff)[_i]), (LAS unsigned*)(lds + (bufoff) + ldsw + _i * 8192), 16, 0, 0); } while (0)
; #define PG8_LDA(dst, b, h) do { _Pragma("unroll") for (int m = 0; m < 4; ++m) _Pragma("unroll") for (int k = 0; k < 2; ++k) dst[m][k] = *(const LAS bf16x8*)(lds + PG8_SA(b, h) + aoff + m * 2048 + k * 1024); } while (0)
; #define PG8_LDB(dst, b, h) do { _Pragma("unroll") for (int n = 0; n < 2; ++n) _Pragma("unroll") for (int k = 0; k < 2; ++k) dst[n][k] = *(const LAS bf16x8*)(lds + PG8_SB(b, h) + boff + n * 2048 + k * 1024); } while (0)
; #define PG8_MMA(ai, bj, At, Bt) do { __builtin_amdgcn_s_setprio(1); _Pragma("unroll") for (int m = 0; m < 4; ++m) _Pragma("unroll") for (int n = 0; n < 2; ++n) _Pragma("unroll") for (int k = 0; k < 2; ++k) \
;         acc[ai][bj][m][n] = __builtin_amdgcn_mfma_f32_16x16x32_bf16(Bt[n][k], At[m][k], acc[ai][bj][m][n], 0, 0, 0); __builtin_amdgcn_s_setprio(0); } while (0)
; #define PG8_WAIT_V(n) asm volatile("s_waitcnt vmcnt(" #n ")" ::: "memory")
; #define PG8_WAIT_L(n) asm volatile("s_waitcnt lgkmcnt(" #n ")" ::: "memory")
; #define PG8_BAR __builtin_amdgcn_s_barrier()
; #define PG8_SCHED __builtin_amdgcn_sched_barrier(0)
; template <class Epi, bool SP2 = false>
; __device__ __forceinline__ void gemm_phase(LAS unsigned char* lds, const Gemm g, const StaticOrder& S, const Epi& E) {
;     ...
;             PG8_LDB(B0, 1, 0); PG8_LDB(B1, 1, 1); PG8_SCHED; PG8_LDA(At, 1, 0); PG8_STAGE(PG8_SA(0, 1), a2 + hstepA, voffA);
;             PG8_WAIT_V(8); PG8_WAIT_L(0); PG8_BAR; PG8_MMA(0, 0, At, B0); PG8_MMA(0, 1, At, B1); PG8_BAR; PG8_SCHED;
;             PG8_LDA(At, 1, 1); PG8_STAGE(PG8_SB(1, 0), b3, voffB); PG8_STAGE(PG8_SB(1, 1), b3 + hstepB, voffB); PG8_STAGE(PG8_SA(1, 0), a3, voffA);
;             PG8_WAIT_V(8); PG8_WAIT_L(0); PG8_BAR; PG8_MMA(1, 0, At, B0); PG8_MMA(1, 1, At, B1); PG8_BAR; PG8_SCHED;
;     ...
;         if constexpr (SP2) { if (wr == 0) PG8_BAR; }
	s_add_i32 s68, 0, 0x18000
	s_add_i32 s69, 0, 0x1c000
	v_add_u32_e32 v164, s68, v152
	v_add_u32_e32 v180, s69, v152
	ds_read_b128 v[146:149], v164
	ds_read_b128 v[156:159], v164 offset:1024
	ds_read_b128 v[160:163], v164 offset:2048
	ds_read_b128 v[164:167], v164 offset:3072
	ds_read_b128 v[168:171], v180
	ds_read_b128 v[172:175], v180 offset:1024
	ds_read_b128 v[176:179], v180 offset:2048
	ds_read_b128 v[180:183], v180 offset:3072
	s_add_u32 s50, s50, 0x40000
	s_addc_u32 s51, s51, 0
	s_mov_b32 m0, s55
	ds_read_b128 v[184:187], v155 offset:32768
	ds_read_b128 v[188:191], v155 offset:33792
	ds_read_b128 v[192:195], v155 offset:34816
	ds_read_b128 v[196:199], v155 offset:35840
	ds_read_b128 v[200:203], v155 offset:36864
	ds_read_b128 v[204:207], v155 offset:37888
	ds_read_b128 v[208:211], v155 offset:38912
	ds_read_b128 v[212:215], v155 offset:39936
	global_load_lds_dwordx4 v130, s[50:51]
	v_lshl_add_u64 v[222:223], s[50:51], 0, v[134:135]
	s_mov_b32 m0, s56
	s_nop 0
	global_load_lds_dwordx4 v[222:223], off
	s_waitcnt vmcnt(8)
	s_waitcnt lgkmcnt(0)
	s_barrier
	v_mfma_f32_16x16x32_bf16 v[124:127], v[146:149], v[184:187], v[124:127]
	v_mfma_f32_16x16x32_bf16 v[120:123], v[160:163], v[184:187], v[120:123]
	v_mfma_f32_16x16x32_bf16 v[108:111], v[146:149], v[192:195], v[108:111]
	v_mfma_f32_16x16x32_bf16 v[104:107], v[160:163], v[192:195], v[104:107]
	v_mfma_f32_16x16x32_bf16 v[92:95], v[146:149], v[200:203], v[92:95]
	v_mfma_f32_16x16x32_bf16 v[88:91], v[160:163], v[200:203], v[88:91]
	v_mfma_f32_16x16x32_bf16 v[76:79], v[146:149], v[208:211], v[76:79]
	v_mfma_f32_16x16x32_bf16 v[72:75], v[160:163], v[208:211], v[72:75]
	v_mfma_f32_16x16x32_bf16 v[124:127], v[156:159], v[188:191], v[124:127]
	v_mfma_f32_16x16x32_bf16 v[120:123], v[164:167], v[188:191], v[120:123]
	v_mfma_f32_16x16x32_bf16 v[108:111], v[156:159], v[196:199], v[108:111]
	v_mfma_f32_16x16x32_bf16 v[104:107], v[164:167], v[196:199], v[104:107]
	v_mfma_f32_16x16x32_bf16 v[92:95], v[156:159], v[204:207], v[92:95]
	v_mfma_f32_16x16x32_bf16 v[88:91], v[164:167], v[204:207], v[88:91]
	v_mfma_f32_16x16x32_bf16 v[76:79], v[156:159], v[212:215], v[76:79]
	v_mfma_f32_16x16x32_bf16 v[72:75], v[164:167], v[212:215], v[72:75]
	v_mfma_f32_16x16x32_bf16 v[116:119], v[168:171], v[184:187], v[116:119]
	v_mfma_f32_16x16x32_bf16 v[112:115], v[176:179], v[184:187], v[112:115]
	v_mfma_f32_16x16x32_bf16 v[100:103], v[168:171], v[192:195], v[100:103]
	v_mfma_f32_16x16x32_bf16 v[96:99], v[176:179], v[192:195], v[96:99]
	v_mfma_f32_16x16x32_bf16 v[84:87], v[168:171], v[200:203], v[84:87]
	v_mfma_f32_16x16x32_bf16 v[80:83], v[176:179], v[200:203], v[80:83]
	v_mfma_f32_16x16x32_bf16 v[68:71], v[168:171], v[208:211], v[68:71]
	v_mfma_f32_16x16x32_bf16 v[64:67], v[176:179], v[208:211], v[64:67]
	v_mfma_f32_16x16x32_bf16 v[116:119], v[172:175], v[188:191], v[116:119]
	v_mfma_f32_16x16x32_bf16 v[112:115], v[180:183], v[188:191], v[112:115]
	v_mfma_f32_16x16x32_bf16 v[100:103], v[172:175], v[196:199], v[100:103]
	v_mfma_f32_16x16x32_bf16 v[96:99], v[180:183], v[196:199], v[96:99]
	v_mfma_f32_16x16x32_bf16 v[84:87], v[172:175], v[204:207], v[84:87]
	v_mfma_f32_16x16x32_bf16 v[80:83], v[180:183], v[204:207], v[80:83]
	v_mfma_f32_16x16x32_bf16 v[68:71], v[172:175], v[212:215], v[68:71]
	v_mfma_f32_16x16x32_bf16 v[64:67], v[180:183], v[212:215], v[64:67]
	s_barrier
	s_add_i32 s50, s68, s53
	v_lshl_add_u64 v[150:151], v[150:151], 0, s[10:11]
	s_mov_b32 m0, s50
	ds_read_b128 v[184:187], v155 offset:49152
	ds_read_b128 v[188:191], v155 offset:50176
	ds_read_b128 v[192:195], v155 offset:51200
	ds_read_b128 v[196:199], v155 offset:52224
	ds_read_b128 v[200:203], v155 offset:53248
	ds_read_b128 v[204:207], v155 offset:54272
	ds_read_b128 v[208:211], v155 offset:55296
	ds_read_b128 v[212:215], v155 offset:56320
	global_load_lds_dwordx4 v[150:151], off
	s_add_i32 m0, s50, 0x2000
	s_add_u32 s44, s44, 0x40080
	v_lshl_add_u64 v[150:151], v[216:217], 0, s[10:11]
	s_addc_u32 s45, s45, 0
	s_add_i32 s50, s69, s53
	global_load_lds_dwordx4 v[150:151], off
	s_mov_b32 m0, s50
	s_nop 0
	global_load_lds_dwordx4 v132, s[44:45]
	s_add_i32 m0, s50, 0x2000
	s_nop 0
	global_load_lds_dwordx4 v136, s[44:45]
	v_lshl_add_u64 v[150:151], v[218:219], 0, s[10:11]
	s_mov_b32 m0, s60
	s_nop 0
	global_load_lds_dwordx4 v[150:151], off
	v_lshl_add_u64 v[150:151], v[220:221], 0, s[10:11]
	s_mov_b32 m0, s61
	s_nop 0
	global_load_lds_dwordx4 v[150:151], off
	s_waitcnt vmcnt(8)
	s_waitcnt lgkmcnt(0)
	s_barrier
	v_mfma_f32_16x16x32_bf16 v[60:63], v[146:149], v[184:187], v[60:63]
	v_mfma_f32_16x16x32_bf16 v[56:59], v[160:163], v[184:187], v[56:59]
	v_mfma_f32_16x16x32_bf16 v[44:47], v[146:149], v[192:195], v[44:47]
	v_mfma_f32_16x16x32_bf16 v[40:43], v[160:163], v[192:195], v[40:43]
	v_mfma_f32_16x16x32_bf16 v[28:31], v[146:149], v[200:203], v[28:31]
	v_mfma_f32_16x16x32_bf16 v[24:27], v[160:163], v[200:203], v[24:27]
	v_mfma_f32_16x16x32_bf16 v[12:15], v[146:149], v[208:211], v[12:15]
	v_mfma_f32_16x16x32_bf16 v[8:11], v[160:163], v[208:211], v[8:11]
	v_mfma_f32_16x16x32_bf16 v[60:63], v[156:159], v[188:191], v[60:63]
	v_mfma_f32_16x16x32_bf16 v[56:59], v[164:167], v[188:191], v[56:59]
	v_mfma_f32_16x16x32_bf16 v[44:47], v[156:159], v[196:199], v[44:47]
	v_mfma_f32_16x16x32_bf16 v[40:43], v[164:167], v[196:199], v[40:43]
	v_mfma_f32_16x16x32_bf16 v[28:31], v[156:159], v[204:207], v[28:31]
	v_mfma_f32_16x16x32_bf16 v[24:27], v[164:167], v[204:207], v[24:27]
	v_mfma_f32_16x16x32_bf16 v[12:15], v[156:159], v[212:215], v[12:15]
	v_mfma_f32_16x16x32_bf16 v[8:11], v[164:167], v[212:215], v[8:11]
	v_mfma_f32_16x16x32_bf16 v[52:55], v[168:171], v[184:187], v[52:55]
	v_mfma_f32_16x16x32_bf16 v[48:51], v[176:179], v[184:187], v[48:51]
	v_mfma_f32_16x16x32_bf16 v[36:39], v[168:171], v[192:195], v[36:39]
	v_mfma_f32_16x16x32_bf16 v[32:35], v[176:179], v[192:195], v[32:35]
	v_mfma_f32_16x16x32_bf16 v[20:23], v[168:171], v[200:203], v[20:23]
	v_mfma_f32_16x16x32_bf16 v[16:19], v[176:179], v[200:203], v[16:19]
	v_mfma_f32_16x16x32_bf16 v[4:7], v[168:171], v[208:211], v[4:7]
	v_mfma_f32_16x16x32_bf16 v[0:3], v[176:179], v[208:211], v[0:3]
	v_mfma_f32_16x16x32_bf16 v[52:55], v[172:175], v[188:191], v[52:55]
	v_mfma_f32_16x16x32_bf16 v[48:51], v[180:183], v[188:191], v[48:51]
	v_mfma_f32_16x16x32_bf16 v[36:39], v[172:175], v[196:199], v[36:39]
	v_mfma_f32_16x16x32_bf16 v[32:35], v[180:183], v[196:199], v[32:35]
	v_mfma_f32_16x16x32_bf16 v[20:23], v[172:175], v[204:207], v[20:23]
	v_mfma_f32_16x16x32_bf16 v[16:19], v[180:183], v[204:207], v[16:19]
	v_mfma_f32_16x16x32_bf16 v[4:7], v[172:175], v[212:215], v[4:7]
	v_mfma_f32_16x16x32_bf16 v[0:3], v[180:183], v[212:215], v[0:3]
	s_barrier
	s_add_i32 s74, s74, 2
	s_add_u32 s34, s34, 0x100
	s_addc_u32 s35, s35, 0
	s_add_u32 s72, s72, 0x100
	s_addc_u32 s73, s73, 0
	s_cmp_gt_u32 s74, 13
	s_cbranch_scc0 .LBB0_462
	s_and_b64 vcc, exec, s[12:13]
	s_cbranch_vccz .LBB0_465
	s_barrier

; #define PG8_STAGE(bufoff, gbase, voff) do { _Pragma("unroll") for (int _i = 0; _i < 2; ++_i) \
;         __builtin_amdgcn_global_load_lds((const unsigned*)((const char*)(gbase) + (voff)[_i]), (LAS unsigned*)(lds + (bufoff) + ldsw + _i * 8192), 16, 0, 0); } while (0)
; #define PG8_WAIT_V(n) asm volatile("s_waitcnt vmcnt(" #n ")" ::: "memory")
; #define PG8_BAR __builtin_amdgcn_s_barrier()
; template <class Epi, bool SP2 = false>
; __device__ __forceinline__ void gemm_phase(LAS unsigned char* lds, const Gemm g, const StaticOrder& S, const Epi& E) {
;     const int tid = threadIdx.x, wid = __builtin_amdgcn_readfirstlane(tid >> 6), lane = tid & 63, wr = wid >> 2, wc = wid & 3, fr = lane & 15, fq = lane >> 4;
;     const int K = g.K, nt = K / BK, lda = g.lda;
;     unsigned voffA[2], voffB[2];
; #pragma unroll
;     for (int i = 0; i < 2; ++i) { int R, C; stage_rc(tid * 16 + i * 8192, R, C); const int Rb = Epi::PERM ? ((R & ~31) + perm32(R & 31)) : R;
;         voffA[i] = (unsigned)(R * lda + C) * 2u; voffB[i] = (unsigned)(Rb * K + C) * 2u; }
;     const size_t kstep = (size_t)(BK * 2);
;     const size_t hstepA = (size_t)HALF * lda * 2, hstepB = (size_t)HALF * K * 2;
;     const size_t tstepA = 2 * hstepA, tstepB = 2 * hstepB;
;     const unsigned ldsw = (unsigned)wid * 1024u;
;     const int aoff = lds_byte(wr * 64 + fr, fq * 8), boff = lds_byte(wc * 32 + fr, fq * 8);
;     ...
;         PG8_WAIT_V(2); PG8_BAR;
;         PG8_STAGE(PG8_SB(1, 0), cB + kstep, voffB); PG8_STAGE(PG8_SA(1, 0), cA + kstep, voffA); PG8_STAGE(PG8_SB(1, 1), cB + hstepB + kstep, voffB);
;         PG8_WAIT_V(6); PG8_BAR;
.LBB0_799:
	s_lshl_b32 s10, s10, 5
	s_lshl_b32 s60, s11, 6
	s_lshl_b32 s28, s11, 13
	s_and_b32 s61, s10, 0x60
	s_mov_b64 s[10:11], 0x80
	s_add_i32 m0, s31, 0x18000
	v_lshl_add_u64 v[6:7], v[6:7], 0, s[10:11]
	s_lshl_b32 s29, s61, 7
	s_waitcnt vmcnt(2)
	s_barrier
	global_load_lds_dwordx4 v[6:7], off
	v_lshl_add_u64 v[2:3], v[2:3], 0, s[10:11]
	s_add_i32 m0, s31, 0x1a000
	s_add_i32 s62, s31, 0x8000
	s_add_i32 s63, s31, 0xa000
	global_load_lds_dwordx4 v[2:3], off
	v_lshl_add_u64 v[0:1], v[0:1], 0, s[10:11]
	s_mov_b32 m0, s62
	s_add_u32 s12, s48, 0x40080
	global_load_lds_dwordx4 v[0:1], off
	v_lshl_add_u64 v[0:1], v[4:5], 0, s[10:11]
	s_mov_b32 m0, s63
	s_addc_u32 s13, s49, 0
	global_load_lds_dwordx4 v[0:1], off
	s_add_i32 m0, s31, 0x1c000
	s_nop 0
	global_load_lds_dwordx4 v134, s[12:13]
	v_lshl_add_u64 v[0:1], s[12:13], 0, v[130:131]
	s_add_i32 m0, s31, 0x1e000
	s_sext_i32_i8 s33, s0
	global_load_lds_dwordx4 v[0:1], off
	v_and_b32_e32 v0, 48, v128
	v_lshlrev_b32_e32 v1, 6, v128
	s_movk_i32 s0, 0x3c0
	v_and_or_b32 v0, v1, s0, v0
	v_lshlrev_b32_e32 v1, 2, v128
	v_and_b32_e32 v1, 32, v1
	v_bitop3_b32 v2, v0, s28, v1 bitop3:0xde
	v_bitop3_b32 v152, s29, v0, v1 bitop3:0xf6
	v_lshlrev_b32_e32 v0, 8, v128
	v_and_b32_e32 v0, 0x38000, v0
	v_lshlrev_b32_e32 v1, 11, v11
	v_or3_b32 v0, v9, v0, v1
	v_add_u32_e32 v138, v0, v10
	v_lshlrev_b32_e32 v0, 4, v8
	s_waitcnt vmcnt(6)
	s_cmpk_lt_u32 s1, 0x100
	v_and_b32_e32 v0, 0x78000, v0
	s_cselect_b64 s[12:13], -1, 0
	v_or3_b32 v0, v9, v0, v1
	s_add_i32 s66, 0, 0x10000
	s_add_i32 s67, 0, 0x14000
	s_ashr_i32 s64, s90, 31
	s_mov_b32 s65, s90
	v_mov_b32_e32 v139, v135
	v_add_u32_e32 v140, v0, v10
	v_mov_b32_e32 v141, v135
	v_mov_b64_e32 v[142:143], 0xc00
	v_mov_b64_e32 v[144:145], 0xbff
	v_add_u32_e32 v153, s66, v152
	v_add_u32_e32 v154, s67, v152
	v_add_u32_e32 v155, 0, v2
	s_mov_b32 s72, 0x40000
	s_mov_b64 s[28:29], 0x48000
	s_mov_b32 s73, 0x48000
	s_mov_b64 s[36:37], 0x50000
	s_mov_b32 s74, 0x50000
	s_mov_b64 s[38:39], 0x58000
	s_mov_b32 s75, 0x58000
	s_barrier
	s_waitcnt vmcnt(0)
	s_branch .LBB0_802

; #define PG8_STAGE(bufoff, gbase, voff) do { _Pragma("unroll") for (int _i = 0; _i < 2; ++_i) \
;         __builtin_amdgcn_global_load_lds((const unsigned*)((const char*)(gbase) + (voff)[_i]), (LAS unsigned*)(lds + (bufoff) + ldsw + _i * 8192), 16, 0, 0); } while (0)
; #define PG8_LDA(dst, b, h) do { _Pragma("unroll") for (int m = 0; m < 4; ++m) _Pragma("unroll") for (int k = 0; k < 2; ++k) dst[m][k] = *(const LAS bf16x8*)(lds + PG8_SA(b, h) + aoff + m * 2048 + k * 1024); } while (0)
; #define PG8_LDB(dst, b, h) do { _Pragma("unroll") for (int n = 0; n < 2; ++n) _Pragma("unroll") for (int k = 0; k < 2; ++k) dst[n][k] = *(const LAS bf16x8*)(lds + PG8_SB(b, h) + boff + n * 2048 + k * 1024); } while (0)
; #define PG8_MMA(ai, bj, At, Bt) do { __builtin_amdgcn_s_setprio(1); _Pragma("unroll") for (int m = 0; m < 4; ++m) _Pragma("unroll") for (int n = 0; n < 2; ++n) _Pragma("unroll") for (int k = 0; k < 2; ++k) \
;         acc[ai][bj][m][n] = __builtin_amdgcn_mfma_f32_16x16x32_bf16(Bt[n][k], At[m][k], acc[ai][bj][m][n], 0, 0, 0); __builtin_amdgcn_s_setprio(0); } while (0)
; #define PG8_WAIT_V(n) asm volatile("s_waitcnt vmcnt(" #n ")" ::: "memory")
; #define PG8_WAIT_L(n) asm volatile("s_waitcnt lgkmcnt(" #n ")" ::: "memory")
; #define PG8_BAR __builtin_amdgcn_s_barrier()
; #define PG8_SCHED __builtin_amdgcn_sched_barrier(0)
; template <class Epi, bool SP2 = false>
; __device__ __forceinline__ void gemm_phase(LAS unsigned char* lds, const Gemm g, const StaticOrder& S, const Epi& E) {
;     ...
;             const bool last = (t == nt - 2);
;             const char* a1 = cA + (size_t)(t + 1) * kstep;
;             const char* a2 = last ? nA : cA + (size_t)(t + 2) * kstep; const char* b2 = last ? nB : cB + (size_t)(t + 2) * kstep;
;             const char* a3 = a2 + kstep; const char* b3 = b2 + kstep;
;             if constexpr (SP2) {
;             PG8_LDB(B0, 0, 0); PG8_LDB(B1, 0, 1); PG8_SCHED; PG8_LDA(At, 0, 0); PG8_STAGE(PG8_SA(1, 1), a1 + hstepA, voffA);
;             PG8_WAIT_V(8); PG8_WAIT_L(0); PG8_BAR; PG8_MMA(0, 0, At, B0); PG8_MMA(0, 1, At, B1); PG8_BAR; PG8_SCHED;
;             PG8_LDA(At, 0, 1); PG8_STAGE(PG8_SB(0, 0), b2, voffB); PG8_STAGE(PG8_SB(0, 1), b2 + hstepB, voffB); PG8_STAGE(PG8_SA(0, 0), a2, voffA);
;             PG8_WAIT_V(8); PG8_WAIT_L(0); PG8_BAR; PG8_MMA(1, 0, At, B0); PG8_MMA(1, 1, At, B1); PG8_BAR; PG8_SCHED;
.LBB0_805:
	ds_read_b128 v[146:149], v153
	ds_read_b128 v[156:159], v153 offset:1024
	ds_read_b128 v[160:163], v153 offset:2048
	ds_read_b128 v[164:167], v153 offset:3072
	ds_read_b128 v[168:171], v154
	ds_read_b128 v[172:175], v154 offset:1024
	ds_read_b128 v[176:179], v154 offset:2048
	ds_read_b128 v[180:183], v154 offset:3072
	s_add_u32 s48, s34, 0xfffc0080
	s_addc_u32 s49, s35, -1
	s_cmp_eq_u32 s80, 12
	s_cselect_b32 s51, s43, s49
	s_cselect_b32 s50, s76, s48
	s_cselect_b32 s49, s41, s79
	s_cselect_b32 s48, s77, s78
	s_add_i32 m0, s31, 0xc000
	ds_read_b128 v[184:187], v155
	ds_read_b128 v[188:191], v155 offset:1024
	ds_read_b128 v[192:195], v155 offset:2048
	ds_read_b128 v[196:199], v155 offset:3072
	ds_read_b128 v[200:203], v155 offset:4096
	ds_read_b128 v[204:207], v155 offset:5120
	ds_read_b128 v[208:211], v155 offset:6144
	ds_read_b128 v[212:215], v155 offset:7168
	global_load_lds_dwordx4 v138, s[34:35]
	s_add_i32 m0, s31, 0xe000
	s_nop 0
	global_load_lds_dwordx4 v140, s[34:35]
	s_waitcnt vmcnt(8)
	s_waitcnt lgkmcnt(0)
	s_barrier
	v_mfma_f32_16x16x32_bf16 v[124:127], v[146:149], v[184:187], v[124:127]
	v_mfma_f32_16x16x32_bf16 v[120:123], v[160:163], v[184:187], v[120:123]
	v_mfma_f32_16x16x32_bf16 v[108:111], v[146:149], v[192:195], v[108:111]
	v_mfma_f32_16x16x32_bf16 v[104:107], v[160:163], v[192:195], v[104:107]
	v_mfma_f32_16x16x32_bf16 v[92:95], v[146:149], v[200:203], v[92:95]
	v_mfma_f32_16x16x32_bf16 v[88:91], v[160:163], v[200:203], v[88:91]
	v_mfma_f32_16x16x32_bf16 v[76:79], v[146:149], v[208:211], v[76:79]
	v_mfma_f32_16x16x32_bf16 v[72:75], v[160:163], v[208:211], v[72:75]
	v_mfma_f32_16x16x32_bf16 v[124:127], v[156:159], v[188:191], v[124:127]
	v_mfma_f32_16x16x32_bf16 v[120:123], v[164:167], v[188:191], v[120:123]
	v_mfma_f32_16x16x32_bf16 v[108:111], v[156:159], v[196:199], v[108:111]
	v_mfma_f32_16x16x32_bf16 v[104:107], v[164:167], v[196:199], v[104:107]
	v_mfma_f32_16x16x32_bf16 v[92:95], v[156:159], v[204:207], v[92:95]
	v_mfma_f32_16x16x32_bf16 v[88:91], v[164:167], v[204:207], v[88:91]
	v_mfma_f32_16x16x32_bf16 v[76:79], v[156:159], v[212:215], v[76:79]
	v_mfma_f32_16x16x32_bf16 v[72:75], v[164:167], v[212:215], v[72:75]
	v_mfma_f32_16x16x32_bf16 v[116:119], v[168:171], v[184:187], v[116:119]
	v_mfma_f32_16x16x32_bf16 v[112:115], v[176:179], v[184:187], v[112:115]
	v_mfma_f32_16x16x32_bf16 v[100:103], v[168:171], v[192:195], v[100:103]
	v_mfma_f32_16x16x32_bf16 v[96:99], v[176:179], v[192:195], v[96:99]
	v_mfma_f32_16x16x32_bf16 v[84:87], v[168:171], v[200:203], v[84:87]
	v_mfma_f32_16x16x32_bf16 v[80:83], v[176:179], v[200:203], v[80:83]
	v_mfma_f32_16x16x32_bf16 v[68:71], v[168:171], v[208:211], v[68:71]
	v_mfma_f32_16x16x32_bf16 v[64:67], v[176:179], v[208:211], v[64:67]
	v_mfma_f32_16x16x32_bf16 v[116:119], v[172:175], v[188:191], v[116:119]
	v_mfma_f32_16x16x32_bf16 v[112:115], v[180:183], v[188:191], v[112:115]
	v_mfma_f32_16x16x32_bf16 v[100:103], v[172:175], v[196:199], v[100:103]
	v_mfma_f32_16x16x32_bf16 v[96:99], v[180:183], v[196:199], v[96:99]
	v_mfma_f32_16x16x32_bf16 v[84:87], v[172:175], v[204:207], v[84:87]
	v_mfma_f32_16x16x32_bf16 v[80:83], v[180:183], v[204:207], v[80:83]
	v_mfma_f32_16x16x32_bf16 v[68:71], v[172:175], v[212:215], v[68:71]
	v_mfma_f32_16x16x32_bf16 v[64:67], v[180:183], v[212:215], v[64:67]
	s_barrier
	s_add_i32 s68, s66, s53
	v_lshl_add_u64 v[150:151], s[48:49], 0, v[134:135]
	s_mov_b32 m0, s68
	ds_read_b128 v[184:187], v155 offset:16384
	ds_read_b128 v[188:191], v155 offset:17408
	ds_read_b128 v[192:195], v155 offset:18432
	ds_read_b128 v[196:199], v155 offset:19456
	ds_read_b128 v[200:203], v155 offset:20480
	ds_read_b128 v[204:207], v155 offset:21504
	ds_read_b128 v[208:211], v155 offset:22528
	ds_read_b128 v[212:215], v155 offset:23552
	global_load_lds_dwordx4 v[150:151], off
	s_add_i32 m0, s68, 0x2000
	s_add_u32 s68, s48, 0x40000
	v_lshl_add_u64 v[216:217], s[48:49], 0, v[130:131]
	s_addc_u32 s69, s49, 0
	s_add_i32 s70, s67, s53
	global_load_lds_dwordx4 v[216:217], off
	s_mov_b32 m0, s70
	v_lshl_add_u64 v[220:221], s[50:51], 0, v[132:133]
	global_load_lds_dwordx4 v134, s[68:69]
	s_add_i32 m0, s70, 0x2000
	s_nop 0
	global_load_lds_dwordx4 v130, s[68:69]
	v_lshl_add_u64 v[218:219], s[50:51], 0, v[136:137]
	s_mov_b32 m0, s31
	s_nop 0
	global_load_lds_dwordx4 v[218:219], off
	s_mov_b32 m0, s56
	s_nop 0
	global_load_lds_dwordx4 v[220:221], off
	s_waitcnt vmcnt(8)
	s_waitcnt lgkmcnt(0)
	s_barrier
	v_mfma_f32_16x16x32_bf16 v[60:63], v[146:149], v[184:187], v[60:63]
	v_mfma_f32_16x16x32_bf16 v[56:59], v[160:163], v[184:187], v[56:59]
	v_mfma_f32_16x16x32_bf16 v[44:47], v[146:149], v[192:195], v[44:47]
	v_mfma_f32_16x16x32_bf16 v[40:43], v[160:163], v[192:195], v[40:43]
	v_mfma_f32_16x16x32_bf16 v[28:31], v[146:149], v[200:203], v[28:31]
	v_mfma_f32_16x16x32_bf16 v[24:27], v[160:163], v[200:203], v[24:27]
	v_mfma_f32_16x16x32_bf16 v[12:15], v[146:149], v[208:211], v[12:15]
	v_mfma_f32_16x16x32_bf16 v[8:11], v[160:163], v[208:211], v[8:11]
	v_mfma_f32_16x16x32_bf16 v[60:63], v[156:159], v[188:191], v[60:63]
	v_mfma_f32_16x16x32_bf16 v[56:59], v[164:167], v[188:191], v[56:59]
	v_mfma_f32_16x16x32_bf16 v[44:47], v[156:159], v[196:199], v[44:47]
	v_mfma_f32_16x16x32_bf16 v[40:43], v[164:167], v[196:199], v[40:43]
	v_mfma_f32_16x16x32_bf16 v[28:31], v[156:159], v[204:207], v[28:31]
	v_mfma_f32_16x16x32_bf16 v[24:27], v[164:167], v[204:207], v[24:27]
	v_mfma_f32_16x16x32_bf16 v[12:15], v[156:159], v[212:215], v[12:15]
	v_mfma_f32_16x16x32_bf16 v[8:11], v[164:167], v[212:215], v[8:11]
	v_mfma_f32_16x16x32_bf16 v[52:55], v[168:171], v[184:187], v[52:55]
	v_mfma_f32_16x16x32_bf16 v[48:51], v[176:179], v[184:187], v[48:51]
	v_mfma_f32_16x16x32_bf16 v[36:39], v[168:171], v[192:195], v[36:39]
	v_mfma_f32_16x16x32_bf16 v[32:35], v[176:179], v[192:195], v[32:35]
	v_mfma_f32_16x16x32_bf16 v[20:23], v[168:171], v[200:203], v[20:23]
	v_mfma_f32_16x16x32_bf16 v[16:19], v[176:179], v[200:203], v[16:19]
	v_mfma_f32_16x16x32_bf16 v[4:7], v[168:171], v[208:211], v[4:7]
	v_mfma_f32_16x16x32_bf16 v[0:3], v[176:179], v[208:211], v[0:3]
	v_mfma_f32_16x16x32_bf16 v[52:55], v[172:175], v[188:191], v[52:55]
	v_mfma_f32_16x16x32_bf16 v[48:51], v[180:183], v[188:191], v[48:51]
	v_mfma_f32_16x16x32_bf16 v[36:39], v[172:175], v[196:199], v[36:39]
	v_mfma_f32_16x16x32_bf16 v[32:35], v[180:183], v[196:199], v[32:35]
	v_mfma_f32_16x16x32_bf16 v[20:23], v[172:175], v[204:207], v[20:23]
	v_mfma_f32_16x16x32_bf16 v[16:19], v[180:183], v[204:207], v[16:19]
	v_mfma_f32_16x16x32_bf16 v[4:7], v[172:175], v[212:215], v[4:7]
	v_mfma_f32_16x16x32_bf16 v[0:3], v[180:183], v[212:215], v[0:3]
	s_barrier
; #define PG8_STAGE(bufoff, gbase, voff) do { _Pragma("unroll") for (int _i = 0; _i < 2; ++_i) \
;         __builtin_amdgcn_global_load_lds((const unsigned*)((const char*)(gbase) + (voff)[_i]), (LAS unsigned*)(lds + (bufoff) + ldsw + _i * 8192), 16, 0, 0); } while (0)
; #define PG8_LDA(dst, b, h) do { _Pragma("unroll") for (int m = 0; m < 4; ++m) _Pragma("unroll") for (int k = 0; k < 2; ++k) dst[m][k] = *(const LAS bf16x8*)(lds + PG8_SA(b, h) + aoff + m * 2048 + k * 1024); } while (0)
; #define PG8_LDB(dst, b, h) do { _Pragma("unroll") for (int n = 0; n < 2; ++n) _Pragma("unroll") for (int k = 0; k < 2; ++k) dst[n][k] = *(const LAS bf16x8*)(lds + PG8_SB(b, h) + boff + n * 2048 + k * 1024); } while (0)
; #define PG8_WAIT_V(n) asm volatile("s_waitcnt vmcnt(" #n ")" ::: "memory")
; template <class Epi, bool SP2 = false>
; __device__ __forceinline__ void gemm_phase(LAS unsigned char* lds, const Gemm g, const StaticOrder& S, const Epi& E) {
;     ...
;         for (int t = 0; t < nt; t += 2) {
;             const bool last = (t == nt - 2);
;             const char* a1 = cA + (size_t)(t + 1) * kstep;
;             const char* a2 = last ? nA : cA + (size_t)(t + 2) * kstep; const char* b2 = last ? nB : cB + (size_t)(t + 2) * kstep;
;             const char* a3 = a2 + kstep; const char* b3 = b2 + kstep;
;             if constexpr (SP2) {
;             PG8_LDB(B0, 0, 0); PG8_LDB(B1, 0, 1); PG8_SCHED; PG8_LDA(At, 0, 0); PG8_STAGE(PG8_SA(1, 1), a1 + hstepA, voffA);
;             PG8_WAIT_V(8); PG8_WAIT_L(0); PG8_BAR; PG8_MMA(0, 0, At, B0); PG8_MMA(0, 1, At, B1); PG8_BAR; PG8_SCHED;
;             PG8_LDA(At, 0, 1); PG8_STAGE(PG8_SB(0, 0), b2, voffB); PG8_STAGE(PG8_SB(0, 1), b2 + hstepB, voffB); PG8_STAGE(PG8_SA(0, 0), a2, voffA);
;             PG8_WAIT_V(8); PG8_WAIT_L(0); PG8_BAR; PG8_MMA(1, 0, At, B0); PG8_MMA(1, 1, At, B1); PG8_BAR; PG8_SCHED;
;             PG8_LDB(B0, 1, 0); PG8_LDB(B1, 1, 1); PG8_SCHED; PG8_LDA(At, 1, 0); PG8_STAGE(PG8_SA(0, 1), a2 + hstepA, voffA);
;             PG8_WAIT_V(8); PG8_WAIT_L(0); PG8_BAR; PG8_MMA(0, 0, At, B0); PG8_MMA(0, 1, At, B1); PG8_BAR; PG8_SCHED;
;             PG8_LDA(At, 1, 1); PG8_STAGE(PG8_SB(1, 0), b3, voffB); PG8_STAGE(PG8_SB(1, 1), b3 + hstepB, voffB); PG8_STAGE(PG8_SA(1, 0), a3, voffA);
;             PG8_WAIT_V(8); PG8_WAIT_L(0); PG8_BAR; PG8_MMA(1, 0, At, B0); PG8_MMA(1, 1, At, B1); PG8_BAR; PG8_SCHED;
	s_add_i32 s68, 0, 0x18000
	s_add_i32 s69, 0, 0x1c000
	v_add_u32_e32 v164, s68, v152
	v_add_u32_e32 v180, s69, v152
	ds_read_b128 v[146:149], v164
	ds_read_b128 v[156:159], v164 offset:1024
	ds_read_b128 v[160:163], v164 offset:2048
	ds_read_b128 v[164:167], v164 offset:3072
	ds_read_b128 v[168:171], v180
	ds_read_b128 v[172:175], v180 offset:1024
	ds_read_b128 v[176:179], v180 offset:2048
	ds_read_b128 v[180:183], v180 offset:3072
	s_add_u32 s50, s50, 0x40000
	s_addc_u32 s51, s51, 0
	s_mov_b32 m0, s57
	ds_read_b128 v[184:187], v155 offset:32768
	ds_read_b128 v[188:191], v155 offset:33792
	ds_read_b128 v[192:195], v155 offset:34816
	ds_read_b128 v[196:199], v155 offset:35840
	ds_read_b128 v[200:203], v155 offset:36864
	ds_read_b128 v[204:207], v155 offset:37888
	ds_read_b128 v[208:211], v155 offset:38912
	ds_read_b128 v[212:215], v155 offset:39936
	global_load_lds_dwordx4 v136, s[50:51]
	v_lshl_add_u64 v[222:223], s[50:51], 0, v[132:133]
	s_mov_b32 m0, s58
	s_nop 0
	global_load_lds_dwordx4 v[222:223], off
	s_waitcnt vmcnt(8)
	s_waitcnt lgkmcnt(0)
	s_barrier
	v_mfma_f32_16x16x32_bf16 v[124:127], v[146:149], v[184:187], v[124:127]
	v_mfma_f32_16x16x32_bf16 v[120:123], v[160:163], v[184:187], v[120:123]
	v_mfma_f32_16x16x32_bf16 v[108:111], v[146:149], v[192:195], v[108:111]
	v_mfma_f32_16x16x32_bf16 v[104:107], v[160:163], v[192:195], v[104:107]
	v_mfma_f32_16x16x32_bf16 v[92:95], v[146:149], v[200:203], v[92:95]
	v_mfma_f32_16x16x32_bf16 v[88:91], v[160:163], v[200:203], v[88:91]
	v_mfma_f32_16x16x32_bf16 v[76:79], v[146:149], v[208:211], v[76:79]
	v_mfma_f32_16x16x32_bf16 v[72:75], v[160:163], v[208:211], v[72:75]
	v_mfma_f32_16x16x32_bf16 v[124:127], v[156:159], v[188:191], v[124:127]
	v_mfma_f32_16x16x32_bf16 v[120:123], v[164:167], v[188:191], v[120:123]
	v_mfma_f32_16x16x32_bf16 v[108:111], v[156:159], v[196:199], v[108:111]
	v_mfma_f32_16x16x32_bf16 v[104:107], v[164:167], v[196:199], v[104:107]
	v_mfma_f32_16x16x32_bf16 v[92:95], v[156:159], v[204:207], v[92:95]
	v_mfma_f32_16x16x32_bf16 v[88:91], v[164:167], v[204:207], v[88:91]
	v_mfma_f32_16x16x32_bf16 v[76:79], v[156:159], v[212:215], v[76:79]
	v_mfma_f32_16x16x32_bf16 v[72:75], v[164:167], v[212:215], v[72:75]
	v_mfma_f32_16x16x32_bf16 v[116:119], v[168:171], v[184:187], v[116:119]
	v_mfma_f32_16x16x32_bf16 v[112:115], v[176:179], v[184:187], v[112:115]
	v_mfma_f32_16x16x32_bf16 v[100:103], v[168:171], v[192:195], v[100:103]
	v_mfma_f32_16x16x32_bf16 v[96:99], v[176:179], v[192:195], v[96:99]
	v_mfma_f32_16x16x32_bf16 v[84:87], v[168:171], v[200:203], v[84:87]
	v_mfma_f32_16x16x32_bf16 v[80:83], v[176:179], v[200:203], v[80:83]
	v_mfma_f32_16x16x32_bf16 v[68:71], v[168:171], v[208:211], v[68:71]
	v_mfma_f32_16x16x32_bf16 v[64:67], v[176:179], v[208:211], v[64:67]
	v_mfma_f32_16x16x32_bf16 v[116:119], v[172:175], v[188:191], v[116:119]
	v_mfma_f32_16x16x32_bf16 v[112:115], v[180:183], v[188:191], v[112:115]
	v_mfma_f32_16x16x32_bf16 v[100:103], v[172:175], v[196:199], v[100:103]
	v_mfma_f32_16x16x32_bf16 v[96:99], v[180:183], v[196:199], v[96:99]
	v_mfma_f32_16x16x32_bf16 v[84:87], v[172:175], v[204:207], v[84:87]
	v_mfma_f32_16x16x32_bf16 v[80:83], v[180:183], v[204:207], v[80:83]
	v_mfma_f32_16x16x32_bf16 v[68:71], v[172:175], v[212:215], v[68:71]
	v_mfma_f32_16x16x32_bf16 v[64:67], v[180:183], v[212:215], v[64:67]
	s_barrier
	s_add_i32 s50, s68, s53
	v_lshl_add_u64 v[150:151], v[150:151], 0, s[10:11]
	s_mov_b32 m0, s50
	ds_read_b128 v[184:187], v155 offset:49152
	ds_read_b128 v[188:191], v155 offset:50176
	ds_read_b128 v[192:195], v155 offset:51200
	ds_read_b128 v[196:199], v155 offset:52224
	ds_read_b128 v[200:203], v155 offset:53248
	ds_read_b128 v[204:207], v155 offset:54272
	ds_read_b128 v[208:211], v155 offset:55296
	ds_read_b128 v[212:215], v155 offset:56320
	global_load_lds_dwordx4 v[150:151], off
	s_add_i32 m0, s50, 0x2000
	s_add_u32 s48, s48, 0x40080
	v_lshl_add_u64 v[150:151], v[216:217], 0, s[10:11]
	s_addc_u32 s49, s49, 0
	s_add_i32 s50, s69, s53
	global_load_lds_dwordx4 v[150:151], off
	s_mov_b32 m0, s50
	s_nop 0
	global_load_lds_dwordx4 v134, s[48:49]
	s_add_i32 m0, s50, 0x2000
	s_nop 0
	global_load_lds_dwordx4 v130, s[48:49]
	v_lshl_add_u64 v[150:151], v[218:219], 0, s[10:11]
	s_mov_b32 m0, s62
	s_nop 0
	global_load_lds_dwordx4 v[150:151], off
	v_lshl_add_u64 v[150:151], v[220:221], 0, s[10:11]
	s_mov_b32 m0, s63
	s_nop 0
	global_load_lds_dwordx4 v[150:151], off
	s_waitcnt vmcnt(8)
	s_waitcnt lgkmcnt(0)
	s_barrier
	v_mfma_f32_16x16x32_bf16 v[60:63], v[146:149], v[184:187], v[60:63]
	v_mfma_f32_16x16x32_bf16 v[56:59], v[160:163], v[184:187], v[56:59]
	v_mfma_f32_16x16x32_bf16 v[44:47], v[146:149], v[192:195], v[44:47]
	v_mfma_f32_16x16x32_bf16 v[40:43], v[160:163], v[192:195], v[40:43]
	v_mfma_f32_16x16x32_bf16 v[28:31], v[146:149], v[200:203], v[28:31]
	v_mfma_f32_16x16x32_bf16 v[24:27], v[160:163], v[200:203], v[24:27]
	v_mfma_f32_16x16x32_bf16 v[12:15], v[146:149], v[208:211], v[12:15]
	v_mfma_f32_16x16x32_bf16 v[8:11], v[160:163], v[208:211], v[8:11]
	v_mfma_f32_16x16x32_bf16 v[60:63], v[156:159], v[188:191], v[60:63]
	v_mfma_f32_16x16x32_bf16 v[56:59], v[164:167], v[188:191], v[56:59]
	v_mfma_f32_16x16x32_bf16 v[44:47], v[156:159], v[196:199], v[44:47]
	v_mfma_f32_16x16x32_bf16 v[40:43], v[164:167], v[196:199], v[40:43]
	v_mfma_f32_16x16x32_bf16 v[28:31], v[156:159], v[204:207], v[28:31]
	v_mfma_f32_16x16x32_bf16 v[24:27], v[164:167], v[204:207], v[24:27]
	v_mfma_f32_16x16x32_bf16 v[12:15], v[156:159], v[212:215], v[12:15]
	v_mfma_f32_16x16x32_bf16 v[8:11], v[164:167], v[212:215], v[8:11]
	v_mfma_f32_16x16x32_bf16 v[52:55], v[168:171], v[184:187], v[52:55]
	v_mfma_f32_16x16x32_bf16 v[48:51], v[176:179], v[184:187], v[48:51]
	v_mfma_f32_16x16x32_bf16 v[36:39], v[168:171], v[192:195], v[36:39]
	v_mfma_f32_16x16x32_bf16 v[32:35], v[176:179], v[192:195], v[32:35]
	v_mfma_f32_16x16x32_bf16 v[20:23], v[168:171], v[200:203], v[20:23]
	v_mfma_f32_16x16x32_bf16 v[16:19], v[176:179], v[200:203], v[16:19]
	v_mfma_f32_16x16x32_bf16 v[4:7], v[168:171], v[208:211], v[4:7]
	v_mfma_f32_16x16x32_bf16 v[0:3], v[176:179], v[208:211], v[0:3]
	v_mfma_f32_16x16x32_bf16 v[52:55], v[172:175], v[188:191], v[52:55]
	v_mfma_f32_16x16x32_bf16 v[48:51], v[180:183], v[188:191], v[48:51]
	v_mfma_f32_16x16x32_bf16 v[36:39], v[172:175], v[196:199], v[36:39]
	v_mfma_f32_16x16x32_bf16 v[32:35], v[180:183], v[196:199], v[32:35]
	v_mfma_f32_16x16x32_bf16 v[20:23], v[172:175], v[204:207], v[20:23]
	v_mfma_f32_16x16x32_bf16 v[16:19], v[180:183], v[204:207], v[16:19]
	v_mfma_f32_16x16x32_bf16 v[4:7], v[172:175], v[212:215], v[4:7]
	v_mfma_f32_16x16x32_bf16 v[0:3], v[180:183], v[212:215], v[0:3]
	s_barrier
	s_add_i32 s80, s80, 2
	s_add_u32 s34, s34, 0x100
	s_addc_u32 s35, s35, 0
	s_add_u32 s78, s78, 0x100
	s_addc_u32 s79, s79, 0
	s_cmp_gt_u32 s80, 13
	s_cbranch_scc0 .LBB0_805
	s_and_b64 vcc, exec, s[12:13]
	s_cbranch_vccz .LBB0_808
	s_barrier

; #define PG8_STAGE(bufoff, gbase, voff) do { _Pragma("unroll") for (int _i = 0; _i < 2; ++_i) \
;         __builtin_amdgcn_global_load_lds((const unsigned*)((const char*)(gbase) + (voff)[_i]), (LAS unsigned*)(lds + (bufoff) + ldsw + _i * 8192), 16, 0, 0); } while (0)
; #define PG8_WAIT_V(n) asm volatile("s_waitcnt vmcnt(" #n ")" ::: "memory")
; #define PG8_BAR __builtin_amdgcn_s_barrier()
; template <class Epi, bool SP2 = false>
; __device__ __forceinline__ void gemm_phase(LAS unsigned char* lds, const Gemm g, const StaticOrder& S, const Epi& E) {
;     const int tid = threadIdx.x, wid = __builtin_amdgcn_readfirstlane(tid >> 6), lane = tid & 63, wr = wid >> 2, wc = wid & 3, fr = lane & 15, fq = lane >> 4;
;     const int K = g.K, nt = K / BK, lda = g.lda;
;     unsigned voffA[2], voffB[2];
; #pragma unroll
;     for (int i = 0; i < 2; ++i) { int R, C; stage_rc(tid * 16 + i * 8192, R, C); const int Rb = Epi::PERM ? ((R & ~31) + perm32(R & 31)) : R;
;         voffA[i] = (unsigned)(R * lda + C) * 2u; voffB[i] = (unsigned)(Rb * K + C) * 2u; }
;     const size_t kstep = (size_t)(BK * 2);
;     const size_t hstepA = (size_t)HALF * lda * 2, hstepB = (size_t)HALF * K * 2;
;     const size_t tstepA = 2 * hstepA, tstepB = 2 * hstepB;
;     const unsigned ldsw = (unsigned)wid * 1024u;
;     const int aoff = lds_byte(wr * 64 + fr, fq * 8), boff = lds_byte(wc * 32 + fr, fq * 8);
;     ...
;     if constexpr (SP2) {
;         PG8_STAGE(PG8_SB(0, 0), cB, voffB); PG8_STAGE(PG8_SB(0, 1), cB + hstepB, voffB); PG8_STAGE(PG8_SA(0, 0), cA, voffA); PG8_STAGE(PG8_SA(0, 1), cA + hstepA, voffA);
;         if (wr == 1) PG8_BAR;
;         PG8_WAIT_V(2); PG8_BAR;
;         PG8_STAGE(PG8_SB(1, 0), cB + kstep, voffB); PG8_STAGE(PG8_SA(1, 0), cA + kstep, voffA); PG8_STAGE(PG8_SB(1, 1), cB + hstepB + kstep, voffB);
;         PG8_WAIT_V(6); PG8_BAR;
.LBB0_949:
	s_lshl_b32 s12, s12, 5
	s_lshl_b32 s57, s13, 6
	s_lshl_b32 s28, s13, 13
	s_and_b32 s58, s12, 0x60
	s_mov_b64 s[12:13], 0x80
	s_add_i32 m0, s53, 0x18000
	v_lshl_add_u64 v[6:7], v[6:7], 0, s[12:13]
	s_lshl_b32 s29, s58, 7
	s_waitcnt vmcnt(2)
	s_barrier
	global_load_lds_dwordx4 v[6:7], off
	v_lshl_add_u64 v[2:3], v[2:3], 0, s[12:13]
	s_add_i32 m0, s53, 0x1a000
	s_add_i32 s59, s53, 0x8000
	s_add_i32 s60, s53, 0xa000
	global_load_lds_dwordx4 v[2:3], off
	v_lshl_add_u64 v[0:1], v[0:1], 0, s[12:13]
	s_mov_b32 m0, s59
	s_add_u32 s26, s46, 0x40080
	global_load_lds_dwordx4 v[0:1], off
	v_lshl_add_u64 v[0:1], v[4:5], 0, s[12:13]
	s_mov_b32 m0, s60
	s_addc_u32 s27, s47, 0
	global_load_lds_dwordx4 v[0:1], off
	s_add_i32 m0, s53, 0x1c000
	s_nop 0
	global_load_lds_dwordx4 v134, s[26:27]
	v_lshl_add_u64 v[0:1], s[26:27], 0, v[130:131]
	s_add_i32 m0, s53, 0x1e000
	s_sext_i32_i8 s73, s0
	global_load_lds_dwordx4 v[0:1], off
	v_and_b32_e32 v0, 48, v128
	v_lshlrev_b32_e32 v1, 6, v128
	s_movk_i32 s0, 0x3c0
	v_and_or_b32 v0, v1, s0, v0
	v_lshlrev_b32_e32 v1, 2, v128
	v_and_b32_e32 v1, 32, v1
	v_bitop3_b32 v2, v0, s28, v1 bitop3:0xde
	v_bitop3_b32 v146, s29, v0, v1 bitop3:0xf6
	v_lshlrev_b32_e32 v0, 8, v128
	v_and_b32_e32 v0, 0x38000, v0
	v_lshlrev_b32_e32 v1, 11, v11
	v_or3_b32 v0, v9, v0, v1
	v_add_u32_e32 v138, v0, v10
	v_lshlrev_b32_e32 v0, 4, v8
	s_waitcnt vmcnt(6)
	s_cmpk_lt_u32 s1, 0x100
	v_and_b32_e32 v0, 0x78000, v0
	s_cselect_b64 s[26:27], -1, 0
	v_or3_b32 v0, v9, v0, v1
	s_add_i32 s63, 0, 0x10000
	s_add_i32 s64, 0, 0x14000
	s_ashr_i32 s61, s90, 31
	s_mov_b32 s62, s90
	v_mov_b32_e32 v139, v135
	v_add_u32_e32 v140, v0, v10
	v_mov_b32_e32 v141, v135
	v_mov_b64_e32 v[142:143], 0x600
	v_mov_b64_e32 v[144:145], 0x5ff
	v_add_u32_e32 v147, s63, v146
	v_add_u32_e32 v148, s64, v146
	v_add_u32_e32 v149, 0, v2
	s_mov_b32 s65, 0x40000
	s_mov_b64 s[28:29], 0x48000
	s_mov_b32 s66, 0x48000
	s_mov_b64 s[30:31], 0x50000
	s_mov_b32 s67, 0x50000
	s_mov_b64 s[36:37], 0x58000
	s_mov_b32 s72, 0x58000
	s_barrier
	s_waitcnt vmcnt(0)
	s_branch .LBB0_952

; #define PG8_STAGE(bufoff, gbase, voff) do { _Pragma("unroll") for (int _i = 0; _i < 2; ++_i) \
;         __builtin_amdgcn_global_load_lds((const unsigned*)((const char*)(gbase) + (voff)[_i]), (LAS unsigned*)(lds + (bufoff) + ldsw + _i * 8192), 16, 0, 0); } while (0)
; #define PG8_LDA(dst, b, h) do { _Pragma("unroll") for (int m = 0; m < 4; ++m) _Pragma("unroll") for (int k = 0; k < 2; ++k) dst[m][k] = *(const LAS bf16x8*)(lds + PG8_SA(b, h) + aoff + m * 2048 + k * 1024); } while (0)
; #define PG8_LDB(dst, b, h) do { _Pragma("unroll") for (int n = 0; n < 2; ++n) _Pragma("unroll") for (int k = 0; k < 2; ++k) dst[n][k] = *(const LAS bf16x8*)(lds + PG8_SB(b, h) + boff + n * 2048 + k * 1024); } while (0)
; #define PG8_MMA(ai, bj, At, Bt) do { __builtin_amdgcn_s_setprio(1); _Pragma("unroll") for (int m = 0; m < 4; ++m) _Pragma("unroll") for (int n = 0; n < 2; ++n) _Pragma("unroll") for (int k = 0; k < 2; ++k) \
;         acc[ai][bj][m][n] = __builtin_amdgcn_mfma_f32_16x16x32_bf16(Bt[n][k], At[m][k], acc[ai][bj][m][n], 0, 0, 0); __builtin_amdgcn_s_setprio(0); } while (0)
; template <class Epi, bool SP2 = false>
; __device__ __forceinline__ void gemm_phase(LAS unsigned char* lds, const Gemm g, const StaticOrder& S, const Epi& E) {
;     ...
;         const bool has_next = S.next(ui + 1, nxt);
;         const char* nA = has_next ? (const char*)g.A + (size_t)nxt.pm * tstepA : cA; const char* nB = has_next ? (const char*)g.Bt + (size_t)nxt.pn * tstepB : cB;
;         for (int t = 0; t < nt; t += 2) {
;             const bool last = (t == nt - 2);
;             const char* a1 = cA + (size_t)(t + 1) * kstep;
;             const char* a2 = last ? nA : cA + (size_t)(t + 2) * kstep; const char* b2 = last ? nB : cB + (size_t)(t + 2) * kstep;
;             const char* a3 = a2 + kstep; const char* b3 = b2 + kstep;
;             if constexpr (SP2) {
;             PG8_LDB(B0, 0, 0); PG8_LDB(B1, 0, 1); PG8_SCHED; PG8_LDA(At, 0, 0); PG8_STAGE(PG8_SA(1, 1), a1 + hstepA, voffA);
;             PG8_WAIT_V(8); PG8_WAIT_L(0); PG8_BAR; PG8_MMA(0, 0, At, B0); PG8_MMA(0, 1, At, B1); PG8_BAR; PG8_SCHED;
;             PG8_LDA(At, 0, 1); PG8_STAGE(PG8_SB(0, 0), b2, voffB); PG8_STAGE(PG8_SB(0, 1), b2 + hstepB, voffB); PG8_STAGE(PG8_SA(0, 0), a2, voffA);
;             PG8_WAIT_V(8); PG8_WAIT_L(0); PG8_BAR; PG8_MMA(1, 0, At, B0); PG8_MMA(1, 1, At, B1); PG8_BAR; PG8_SCHED;
.LBB0_955:
	ds_read_b128 v[150:153], v147
	ds_read_b128 v[154:157], v147 offset:1024
	ds_read_b128 v[158:161], v147 offset:2048
	ds_read_b128 v[162:165], v147 offset:3072
	ds_read_b128 v[166:169], v148
	ds_read_b128 v[170:173], v148 offset:1024
	ds_read_b128 v[174:177], v148 offset:2048
	ds_read_b128 v[178:181], v148 offset:3072
	s_add_u32 s46, s34, 0xfffc0080
	s_addc_u32 s47, s35, -1
	s_cmp_eq_u32 s78, 12
	s_cselect_b32 s49, s41, s47
	s_cselect_b32 s48, s74, s46
	s_cselect_b32 s47, s39, s77
	s_cselect_b32 s46, s75, s76
	s_add_i32 m0, s53, 0xc000
	ds_read_b128 v[182:185], v149
	ds_read_b128 v[186:189], v149 offset:1024
	ds_read_b128 v[190:193], v149 offset:2048
	ds_read_b128 v[194:197], v149 offset:3072
	ds_read_b128 v[198:201], v149 offset:4096
	ds_read_b128 v[202:205], v149 offset:5120
	ds_read_b128 v[206:209], v149 offset:6144
	ds_read_b128 v[210:213], v149 offset:7168
	global_load_lds_dwordx4 v138, s[34:35]
	s_add_i32 m0, s53, 0xe000
	s_nop 0
	global_load_lds_dwordx4 v140, s[34:35]
	s_waitcnt vmcnt(8)
	s_waitcnt lgkmcnt(0)
	s_barrier
	v_mfma_f32_16x16x32_bf16 v[124:127], v[150:153], v[182:185], v[124:127]
	v_mfma_f32_16x16x32_bf16 v[120:123], v[158:161], v[182:185], v[120:123]
	v_mfma_f32_16x16x32_bf16 v[116:119], v[150:153], v[190:193], v[116:119]
	v_mfma_f32_16x16x32_bf16 v[112:115], v[158:161], v[190:193], v[112:115]
	v_mfma_f32_16x16x32_bf16 v[100:103], v[150:153], v[198:201], v[100:103]
	v_mfma_f32_16x16x32_bf16 v[96:99], v[158:161], v[198:201], v[96:99]
	v_mfma_f32_16x16x32_bf16 v[84:87], v[150:153], v[206:209], v[84:87]
	v_mfma_f32_16x16x32_bf16 v[80:83], v[158:161], v[206:209], v[80:83]
	v_mfma_f32_16x16x32_bf16 v[124:127], v[154:157], v[186:189], v[124:127]
	v_mfma_f32_16x16x32_bf16 v[120:123], v[162:165], v[186:189], v[120:123]
	v_mfma_f32_16x16x32_bf16 v[116:119], v[154:157], v[194:197], v[116:119]
	v_mfma_f32_16x16x32_bf16 v[112:115], v[162:165], v[194:197], v[112:115]
	v_mfma_f32_16x16x32_bf16 v[100:103], v[154:157], v[202:205], v[100:103]
	v_mfma_f32_16x16x32_bf16 v[96:99], v[162:165], v[202:205], v[96:99]
	v_mfma_f32_16x16x32_bf16 v[84:87], v[154:157], v[210:213], v[84:87]
	v_mfma_f32_16x16x32_bf16 v[80:83], v[162:165], v[210:213], v[80:83]
	v_mfma_f32_16x16x32_bf16 v[108:111], v[166:169], v[182:185], v[108:111]
	v_mfma_f32_16x16x32_bf16 v[104:107], v[174:177], v[182:185], v[104:107]
	v_mfma_f32_16x16x32_bf16 v[92:95], v[166:169], v[190:193], v[92:95]
	v_mfma_f32_16x16x32_bf16 v[88:91], v[174:177], v[190:193], v[88:91]
	v_mfma_f32_16x16x32_bf16 v[76:79], v[166:169], v[198:201], v[76:79]
	v_mfma_f32_16x16x32_bf16 v[72:75], v[174:177], v[198:201], v[72:75]
	v_mfma_f32_16x16x32_bf16 v[68:71], v[166:169], v[206:209], v[68:71]
	v_mfma_f32_16x16x32_bf16 v[64:67], v[174:177], v[206:209], v[64:67]
	v_mfma_f32_16x16x32_bf16 v[108:111], v[170:173], v[186:189], v[108:111]
	v_mfma_f32_16x16x32_bf16 v[104:107], v[178:181], v[186:189], v[104:107]
	v_mfma_f32_16x16x32_bf16 v[92:95], v[170:173], v[194:197], v[92:95]
	v_mfma_f32_16x16x32_bf16 v[88:91], v[178:181], v[194:197], v[88:91]
	v_mfma_f32_16x16x32_bf16 v[76:79], v[170:173], v[202:205], v[76:79]
	v_mfma_f32_16x16x32_bf16 v[72:75], v[178:181], v[202:205], v[72:75]
	v_mfma_f32_16x16x32_bf16 v[68:71], v[170:173], v[210:213], v[68:71]
	v_mfma_f32_16x16x32_bf16 v[64:67], v[178:181], v[210:213], v[64:67]
	s_barrier
	s_add_i32 s68, s63, s50
	v_lshl_add_u64 v[214:215], s[46:47], 0, v[134:135]
	s_mov_b32 m0, s68
	ds_read_b128 v[182:185], v149 offset:16384
	ds_read_b128 v[186:189], v149 offset:17408
	ds_read_b128 v[190:193], v149 offset:18432
	ds_read_b128 v[194:197], v149 offset:19456
	ds_read_b128 v[198:201], v149 offset:20480
	ds_read_b128 v[202:205], v149 offset:21504
	ds_read_b128 v[206:209], v149 offset:22528
	ds_read_b128 v[210:213], v149 offset:23552
	global_load_lds_dwordx4 v[214:215], off
	s_add_i32 m0, s68, 0x2000
	s_add_u32 s68, s46, 0x40000
	v_lshl_add_u64 v[216:217], s[46:47], 0, v[130:131]
	s_addc_u32 s69, s47, 0
	s_add_i32 s70, s64, s50
	global_load_lds_dwordx4 v[216:217], off
	s_mov_b32 m0, s70
	v_lshl_add_u64 v[220:221], s[48:49], 0, v[132:133]
	global_load_lds_dwordx4 v134, s[68:69]
	s_add_i32 m0, s70, 0x2000
	s_nop 0
	global_load_lds_dwordx4 v130, s[68:69]
	v_lshl_add_u64 v[218:219], s[48:49], 0, v[136:137]
	s_mov_b32 m0, s53
	s_nop 0
	global_load_lds_dwordx4 v[218:219], off
	s_mov_b32 m0, s54
	s_nop 0
	global_load_lds_dwordx4 v[220:221], off
	s_waitcnt vmcnt(8)
	s_waitcnt lgkmcnt(0)
	s_barrier
	v_mfma_f32_16x16x32_bf16 v[60:63], v[150:153], v[182:185], v[60:63]
	v_mfma_f32_16x16x32_bf16 v[56:59], v[158:161], v[182:185], v[56:59]
	v_mfma_f32_16x16x32_bf16 v[52:55], v[150:153], v[190:193], v[52:55]
	v_mfma_f32_16x16x32_bf16 v[48:51], v[158:161], v[190:193], v[48:51]
	v_mfma_f32_16x16x32_bf16 v[36:39], v[150:153], v[198:201], v[36:39]
	v_mfma_f32_16x16x32_bf16 v[32:35], v[158:161], v[198:201], v[32:35]
	v_mfma_f32_16x16x32_bf16 v[20:23], v[150:153], v[206:209], v[20:23]
	v_mfma_f32_16x16x32_bf16 v[16:19], v[158:161], v[206:209], v[16:19]
	v_mfma_f32_16x16x32_bf16 v[60:63], v[154:157], v[186:189], v[60:63]
	v_mfma_f32_16x16x32_bf16 v[56:59], v[162:165], v[186:189], v[56:59]
	v_mfma_f32_16x16x32_bf16 v[52:55], v[154:157], v[194:197], v[52:55]
	v_mfma_f32_16x16x32_bf16 v[48:51], v[162:165], v[194:197], v[48:51]
	v_mfma_f32_16x16x32_bf16 v[36:39], v[154:157], v[202:205], v[36:39]
	v_mfma_f32_16x16x32_bf16 v[32:35], v[162:165], v[202:205], v[32:35]
	v_mfma_f32_16x16x32_bf16 v[20:23], v[154:157], v[210:213], v[20:23]
	v_mfma_f32_16x16x32_bf16 v[16:19], v[162:165], v[210:213], v[16:19]
	v_mfma_f32_16x16x32_bf16 v[44:47], v[166:169], v[182:185], v[44:47]
	v_mfma_f32_16x16x32_bf16 v[40:43], v[174:177], v[182:185], v[40:43]
	v_mfma_f32_16x16x32_bf16 v[28:31], v[166:169], v[190:193], v[28:31]
	v_mfma_f32_16x16x32_bf16 v[24:27], v[174:177], v[190:193], v[24:27]
	v_mfma_f32_16x16x32_bf16 v[12:15], v[166:169], v[198:201], v[12:15]
	v_mfma_f32_16x16x32_bf16 v[8:11], v[174:177], v[198:201], v[8:11]
	v_mfma_f32_16x16x32_bf16 v[4:7], v[166:169], v[206:209], v[4:7]
	v_mfma_f32_16x16x32_bf16 v[0:3], v[174:177], v[206:209], v[0:3]
	v_mfma_f32_16x16x32_bf16 v[44:47], v[170:173], v[186:189], v[44:47]
	v_mfma_f32_16x16x32_bf16 v[40:43], v[178:181], v[186:189], v[40:43]
	v_mfma_f32_16x16x32_bf16 v[28:31], v[170:173], v[194:197], v[28:31]
	v_mfma_f32_16x16x32_bf16 v[24:27], v[178:181], v[194:197], v[24:27]
	v_mfma_f32_16x16x32_bf16 v[12:15], v[170:173], v[202:205], v[12:15]
	v_mfma_f32_16x16x32_bf16 v[8:11], v[178:181], v[202:205], v[8:11]
	v_mfma_f32_16x16x32_bf16 v[4:7], v[170:173], v[210:213], v[4:7]
	v_mfma_f32_16x16x32_bf16 v[0:3], v[178:181], v[210:213], v[0:3]
	s_barrier
; #define PG8_STAGE(bufoff, gbase, voff) do { _Pragma("unroll") for (int _i = 0; _i < 2; ++_i) \
;         __builtin_amdgcn_global_load_lds((const unsigned*)((const char*)(gbase) + (voff)[_i]), (LAS unsigned*)(lds + (bufoff) + ldsw + _i * 8192), 16, 0, 0); } while (0)
; #define PG8_LDA(dst, b, h) do { _Pragma("unroll") for (int m = 0; m < 4; ++m) _Pragma("unroll") for (int k = 0; k < 2; ++k) dst[m][k] = *(const LAS bf16x8*)(lds + PG8_SA(b, h) + aoff + m * 2048 + k * 1024); } while (0)
; #define PG8_LDB(dst, b, h) do { _Pragma("unroll") for (int n = 0; n < 2; ++n) _Pragma("unroll") for (int k = 0; k < 2; ++k) dst[n][k] = *(const LAS bf16x8*)(lds + PG8_SB(b, h) + boff + n * 2048 + k * 1024); } while (0)
; #define PG8_MMA(ai, bj, At, Bt) do { __builtin_amdgcn_s_setprio(1); _Pragma("unroll") for (int m = 0; m < 4; ++m) _Pragma("unroll") for (int n = 0; n < 2; ++n) _Pragma("unroll") for (int k = 0; k < 2; ++k) \
;         acc[ai][bj][m][n] = __builtin_amdgcn_mfma_f32_16x16x32_bf16(Bt[n][k], At[m][k], acc[ai][bj][m][n], 0, 0, 0); __builtin_amdgcn_s_setprio(0); } while (0)
; #define PG8_WAIT_V(n) asm volatile("s_waitcnt vmcnt(" #n ")" ::: "memory")
; #define PG8_WAIT_L(n) asm volatile("s_waitcnt lgkmcnt(" #n ")" ::: "memory")
; #define PG8_BAR __builtin_amdgcn_s_barrier()
; #define PG8_SCHED __builtin_amdgcn_sched_barrier(0)
; template <class Epi, bool SP2 = false>
; __device__ __forceinline__ void gemm_phase(LAS unsigned char* lds, const Gemm g, const StaticOrder& S, const Epi& E) {
;     ...
;             PG8_LDB(B0, 1, 0); PG8_LDB(B1, 1, 1); PG8_SCHED; PG8_LDA(At, 1, 0); PG8_STAGE(PG8_SA(0, 1), a2 + hstepA, voffA);
;             PG8_WAIT_V(8); PG8_WAIT_L(0); PG8_BAR; PG8_MMA(0, 0, At, B0); PG8_MMA(0, 1, At, B1); PG8_BAR; PG8_SCHED;
;             PG8_LDA(At, 1, 1); PG8_STAGE(PG8_SB(1, 0), b3, voffB); PG8_STAGE(PG8_SB(1, 1), b3 + hstepB, voffB); PG8_STAGE(PG8_SA(1, 0), a3, voffA);
;             PG8_WAIT_V(8); PG8_WAIT_L(0); PG8_BAR; PG8_MMA(1, 0, At, B0); PG8_MMA(1, 1, At, B1); PG8_BAR; PG8_SCHED;
	s_add_i32 s68, 0, 0x18000
	s_add_i32 s69, 0, 0x1c000
	v_add_u32_e32 v162, s68, v146
	v_add_u32_e32 v178, s69, v146
	ds_read_b128 v[150:153], v162
	ds_read_b128 v[154:157], v162 offset:1024
	ds_read_b128 v[158:161], v162 offset:2048
	ds_read_b128 v[162:165], v162 offset:3072
	ds_read_b128 v[166:169], v178
	ds_read_b128 v[170:173], v178 offset:1024
	ds_read_b128 v[174:177], v178 offset:2048
	ds_read_b128 v[178:181], v178 offset:3072
	s_add_u32 s48, s48, 0x40000
	s_addc_u32 s49, s49, 0
	s_mov_b32 m0, s55
	ds_read_b128 v[182:185], v149 offset:32768
	ds_read_b128 v[186:189], v149 offset:33792
	ds_read_b128 v[190:193], v149 offset:34816
	ds_read_b128 v[194:197], v149 offset:35840
	ds_read_b128 v[198:201], v149 offset:36864
	ds_read_b128 v[202:205], v149 offset:37888
	ds_read_b128 v[206:209], v149 offset:38912
	ds_read_b128 v[210:213], v149 offset:39936
	global_load_lds_dwordx4 v136, s[48:49]
	v_lshl_add_u64 v[222:223], s[48:49], 0, v[132:133]
	s_mov_b32 m0, s56
	s_nop 0
	global_load_lds_dwordx4 v[222:223], off
	s_waitcnt vmcnt(8)
	s_waitcnt lgkmcnt(0)
	s_barrier
	v_mfma_f32_16x16x32_bf16 v[124:127], v[150:153], v[182:185], v[124:127]
	v_mfma_f32_16x16x32_bf16 v[120:123], v[158:161], v[182:185], v[120:123]
	v_mfma_f32_16x16x32_bf16 v[116:119], v[150:153], v[190:193], v[116:119]
	v_mfma_f32_16x16x32_bf16 v[112:115], v[158:161], v[190:193], v[112:115]
	v_mfma_f32_16x16x32_bf16 v[100:103], v[150:153], v[198:201], v[100:103]
	v_mfma_f32_16x16x32_bf16 v[96:99], v[158:161], v[198:201], v[96:99]
	v_mfma_f32_16x16x32_bf16 v[84:87], v[150:153], v[206:209], v[84:87]
	v_mfma_f32_16x16x32_bf16 v[80:83], v[158:161], v[206:209], v[80:83]
	v_mfma_f32_16x16x32_bf16 v[124:127], v[154:157], v[186:189], v[124:127]
	v_mfma_f32_16x16x32_bf16 v[120:123], v[162:165], v[186:189], v[120:123]
	v_mfma_f32_16x16x32_bf16 v[116:119], v[154:157], v[194:197], v[116:119]
	v_mfma_f32_16x16x32_bf16 v[112:115], v[162:165], v[194:197], v[112:115]
	v_mfma_f32_16x16x32_bf16 v[100:103], v[154:157], v[202:205], v[100:103]
	v_mfma_f32_16x16x32_bf16 v[96:99], v[162:165], v[202:205], v[96:99]
	v_mfma_f32_16x16x32_bf16 v[84:87], v[154:157], v[210:213], v[84:87]
	v_mfma_f32_16x16x32_bf16 v[80:83], v[162:165], v[210:213], v[80:83]
	v_mfma_f32_16x16x32_bf16 v[108:111], v[166:169], v[182:185], v[108:111]
	v_mfma_f32_16x16x32_bf16 v[104:107], v[174:177], v[182:185], v[104:107]
	v_mfma_f32_16x16x32_bf16 v[92:95], v[166:169], v[190:193], v[92:95]
	v_mfma_f32_16x16x32_bf16 v[88:91], v[174:177], v[190:193], v[88:91]
	v_mfma_f32_16x16x32_bf16 v[76:79], v[166:169], v[198:201], v[76:79]
	v_mfma_f32_16x16x32_bf16 v[72:75], v[174:177], v[198:201], v[72:75]
	v_mfma_f32_16x16x32_bf16 v[68:71], v[166:169], v[206:209], v[68:71]
	v_mfma_f32_16x16x32_bf16 v[64:67], v[174:177], v[206:209], v[64:67]
	v_mfma_f32_16x16x32_bf16 v[108:111], v[170:173], v[186:189], v[108:111]
	v_mfma_f32_16x16x32_bf16 v[104:107], v[178:181], v[186:189], v[104:107]
	v_mfma_f32_16x16x32_bf16 v[92:95], v[170:173], v[194:197], v[92:95]
	v_mfma_f32_16x16x32_bf16 v[88:91], v[178:181], v[194:197], v[88:91]
	v_mfma_f32_16x16x32_bf16 v[76:79], v[170:173], v[202:205], v[76:79]
	v_mfma_f32_16x16x32_bf16 v[72:75], v[178:181], v[202:205], v[72:75]
	v_mfma_f32_16x16x32_bf16 v[68:71], v[170:173], v[210:213], v[68:71]
	v_mfma_f32_16x16x32_bf16 v[64:67], v[178:181], v[210:213], v[64:67]
	s_barrier
	s_add_i32 s48, s68, s50
	v_lshl_add_u64 v[214:215], v[214:215], 0, s[12:13]
	s_mov_b32 m0, s48
	ds_read_b128 v[182:185], v149 offset:49152
	ds_read_b128 v[186:189], v149 offset:50176
	ds_read_b128 v[190:193], v149 offset:51200
	ds_read_b128 v[194:197], v149 offset:52224
	ds_read_b128 v[198:201], v149 offset:53248
	ds_read_b128 v[202:205], v149 offset:54272
	ds_read_b128 v[206:209], v149 offset:55296
	ds_read_b128 v[210:213], v149 offset:56320
	global_load_lds_dwordx4 v[214:215], off
	s_add_i32 m0, s48, 0x2000
	s_add_u32 s46, s46, 0x40080
	v_lshl_add_u64 v[214:215], v[216:217], 0, s[12:13]
	s_addc_u32 s47, s47, 0
	s_add_i32 s48, s69, s50
	global_load_lds_dwordx4 v[214:215], off
	s_mov_b32 m0, s48
	s_nop 0
	global_load_lds_dwordx4 v134, s[46:47]
	s_add_i32 m0, s48, 0x2000
	s_nop 0
	global_load_lds_dwordx4 v130, s[46:47]
	v_lshl_add_u64 v[214:215], v[218:219], 0, s[12:13]
	s_mov_b32 m0, s59
	s_nop 0
	global_load_lds_dwordx4 v[214:215], off
	v_lshl_add_u64 v[214:215], v[220:221], 0, s[12:13]
	s_mov_b32 m0, s60
	s_nop 0
	global_load_lds_dwordx4 v[214:215], off
	s_waitcnt vmcnt(8)
	s_waitcnt lgkmcnt(0)
	s_barrier
	v_mfma_f32_16x16x32_bf16 v[60:63], v[150:153], v[182:185], v[60:63]
	v_mfma_f32_16x16x32_bf16 v[56:59], v[158:161], v[182:185], v[56:59]
	v_mfma_f32_16x16x32_bf16 v[52:55], v[150:153], v[190:193], v[52:55]
	v_mfma_f32_16x16x32_bf16 v[48:51], v[158:161], v[190:193], v[48:51]
	v_mfma_f32_16x16x32_bf16 v[36:39], v[150:153], v[198:201], v[36:39]
	v_mfma_f32_16x16x32_bf16 v[32:35], v[158:161], v[198:201], v[32:35]
	v_mfma_f32_16x16x32_bf16 v[20:23], v[150:153], v[206:209], v[20:23]
	v_mfma_f32_16x16x32_bf16 v[16:19], v[158:161], v[206:209], v[16:19]
	v_mfma_f32_16x16x32_bf16 v[60:63], v[154:157], v[186:189], v[60:63]
	v_mfma_f32_16x16x32_bf16 v[56:59], v[162:165], v[186:189], v[56:59]
	v_mfma_f32_16x16x32_bf16 v[52:55], v[154:157], v[194:197], v[52:55]
	v_mfma_f32_16x16x32_bf16 v[48:51], v[162:165], v[194:197], v[48:51]
	v_mfma_f32_16x16x32_bf16 v[36:39], v[154:157], v[202:205], v[36:39]
	v_mfma_f32_16x16x32_bf16 v[32:35], v[162:165], v[202:205], v[32:35]
	v_mfma_f32_16x16x32_bf16 v[20:23], v[154:157], v[210:213], v[20:23]
	v_mfma_f32_16x16x32_bf16 v[16:19], v[162:165], v[210:213], v[16:19]
	v_mfma_f32_16x16x32_bf16 v[44:47], v[166:169], v[182:185], v[44:47]
	v_mfma_f32_16x16x32_bf16 v[40:43], v[174:177], v[182:185], v[40:43]
	v_mfma_f32_16x16x32_bf16 v[28:31], v[166:169], v[190:193], v[28:31]
	v_mfma_f32_16x16x32_bf16 v[24:27], v[174:177], v[190:193], v[24:27]
	v_mfma_f32_16x16x32_bf16 v[12:15], v[166:169], v[198:201], v[12:15]
	v_mfma_f32_16x16x32_bf16 v[8:11], v[174:177], v[198:201], v[8:11]
	v_mfma_f32_16x16x32_bf16 v[4:7], v[166:169], v[206:209], v[4:7]
	v_mfma_f32_16x16x32_bf16 v[0:3], v[174:177], v[206:209], v[0:3]
	v_mfma_f32_16x16x32_bf16 v[44:47], v[170:173], v[186:189], v[44:47]
	v_mfma_f32_16x16x32_bf16 v[40:43], v[178:181], v[186:189], v[40:43]
	v_mfma_f32_16x16x32_bf16 v[28:31], v[170:173], v[194:197], v[28:31]
	v_mfma_f32_16x16x32_bf16 v[24:27], v[178:181], v[194:197], v[24:27]
	v_mfma_f32_16x16x32_bf16 v[12:15], v[170:173], v[202:205], v[12:15]
	v_mfma_f32_16x16x32_bf16 v[8:11], v[178:181], v[202:205], v[8:11]
	v_mfma_f32_16x16x32_bf16 v[4:7], v[170:173], v[210:213], v[4:7]
	v_mfma_f32_16x16x32_bf16 v[0:3], v[178:181], v[210:213], v[0:3]
	s_barrier
	s_add_i32 s78, s78, 2
	s_add_u32 s34, s34, 0x100
	s_addc_u32 s35, s35, 0
	s_add_u32 s76, s76, 0x100
	s_addc_u32 s77, s77, 0
	s_cmp_gt_u32 s78, 13
	s_cbranch_scc0 .LBB0_955
	s_and_b64 vcc, exec, s[26:27]
	s_cbranch_vccz .LBB0_958
	s_barrier

; #define PG8_STAGE(bufoff, gbase, voff) do { _Pragma("unroll") for (int _i = 0; _i < 2; ++_i) \
;         __builtin_amdgcn_global_load_lds((const unsigned*)((const char*)(gbase) + (voff)[_i]), (LAS unsigned*)(lds + (bufoff) + ldsw + _i * 8192), 16, 0, 0); } while (0)
; #define PG8_WAIT_V(n) asm volatile("s_waitcnt vmcnt(" #n ")" ::: "memory")
; #define PG8_BAR __builtin_amdgcn_s_barrier()
; template <class Epi, bool SP2 = false>
; __device__ __forceinline__ void gemm_phase(LAS unsigned char* lds, const Gemm g, const StaticOrder& S, const Epi& E) {
;     const int tid = threadIdx.x, wid = __builtin_amdgcn_readfirstlane(tid >> 6), lane = tid & 63, wr = wid >> 2, wc = wid & 3, fr = lane & 15, fq = lane >> 4;
;     const int K = g.K, nt = K / BK, lda = g.lda;
;     unsigned voffA[2], voffB[2];
; #pragma unroll
;     for (int i = 0; i < 2; ++i) { int R, C; stage_rc(tid * 16 + i * 8192, R, C); const int Rb = Epi::PERM ? ((R & ~31) + perm32(R & 31)) : R;
;         voffA[i] = (unsigned)(R * lda + C) * 2u; voffB[i] = (unsigned)(Rb * K + C) * 2u; }
;     const size_t kstep = (size_t)(BK * 2);
;     const size_t hstepA = (size_t)HALF * lda * 2, hstepB = (size_t)HALF * K * 2;
;     const size_t tstepA = 2 * hstepA, tstepB = 2 * hstepB;
;     const unsigned ldsw = (unsigned)wid * 1024u;
;     const int aoff = lds_byte(wr * 64 + fr, fq * 8), boff = lds_byte(wc * 32 + fr, fq * 8);
;     ...
;     if constexpr (SP2) {
;         PG8_STAGE(PG8_SB(0, 0), cB, voffB); PG8_STAGE(PG8_SB(0, 1), cB + hstepB, voffB); PG8_STAGE(PG8_SA(0, 0), cA, voffA); PG8_STAGE(PG8_SA(0, 1), cA + hstepA, voffA);
;         if (wr == 1) PG8_BAR;
;         PG8_WAIT_V(2); PG8_BAR;
;         PG8_STAGE(PG8_SB(1, 0), cB + kstep, voffB); PG8_STAGE(PG8_SA(1, 0), cA + kstep, voffA); PG8_STAGE(PG8_SB(1, 1), cB + hstepB + kstep, voffB);
;         PG8_WAIT_V(6); PG8_BAR;
.LBB0_1071:
	s_lshl_b32 s8, s8, 5
	s_lshl_b32 s44, s9, 6
	s_lshl_b32 s12, s9, 13
	s_and_b32 s45, s8, 0x60
	s_mov_b64 s[8:9], 0x80
	s_add_i32 m0, s27, 0x18000
	v_lshl_add_u64 v[6:7], v[6:7], 0, s[8:9]
	s_lshl_b32 s13, s45, 7
	s_waitcnt vmcnt(2)
	s_barrier
	global_load_lds_dwordx4 v[6:7], off
	v_lshl_add_u64 v[4:5], v[4:5], 0, s[8:9]
	s_add_i32 m0, s27, 0x1a000
	s_add_i32 s46, s27, 0x8000
	s_add_i32 s47, s27, 0xa000
	global_load_lds_dwordx4 v[4:5], off
	v_lshl_add_u64 v[0:1], v[0:1], 0, s[8:9]
	s_mov_b32 m0, s46
	s_add_u32 s10, s30, 0x40080
	global_load_lds_dwordx4 v[0:1], off
	v_lshl_add_u64 v[0:1], v[2:3], 0, s[8:9]
	s_mov_b32 m0, s47
	s_addc_u32 s11, s31, 0
	global_load_lds_dwordx4 v[0:1], off
	s_add_i32 m0, s27, 0x1c000
	s_nop 0
	global_load_lds_dwordx4 v134, s[10:11]
	v_lshl_add_u64 v[0:1], s[10:11], 0, v[130:131]
	s_add_i32 m0, s27, 0x1e000
	s_sext_i32_i16 s33, s0
	global_load_lds_dwordx4 v[0:1], off
	v_and_b32_e32 v0, 48, v128
	v_lshlrev_b32_e32 v1, 6, v128
	s_movk_i32 s0, 0x3c0
	v_and_or_b32 v0, v1, s0, v0
	v_lshlrev_b32_e32 v1, 2, v128
	v_and_b32_e32 v1, 32, v1
	v_bitop3_b32 v2, v0, s12, v1 bitop3:0xde
	v_bitop3_b32 v148, s13, v0, v1 bitop3:0xf6
	v_lshlrev_b32_e32 v0, 8, v128
	v_and_b32_e32 v0, 0x38000, v0
	v_lshlrev_b32_e32 v1, 11, v11
	v_or3_b32 v0, v9, v0, v1
	v_add_u32_e32 v138, v0, v10
	v_lshlrev_b32_e32 v0, 4, v8
	s_waitcnt vmcnt(6)
	s_cmpk_lt_u32 s1, 0x100
	v_and_b32_e32 v0, 0x78000, v0
	s_cselect_b64 s[10:11], -1, 0
	v_or3_b32 v0, v9, v0, v1
	s_add_i32 s50, 0, 0x10000
	s_add_i32 s51, 0, 0x14000
	s_ashr_i32 s48, s90, 31
	s_mov_b32 s49, s90
	v_mov_b32_e32 v139, v135
	v_add_u32_e32 v140, v0, v10
	v_mov_b32_e32 v141, v135
	v_mov_b64_e32 v[142:143], 0x2100
	v_mov_b64_e32 v[144:145], 0x20ff
	v_add_u32_e32 v149, s50, v148
	v_add_u32_e32 v150, s51, v148
	v_add_u32_e32 v151, 0, v2
	s_movk_i32 s52, 0x1600
	s_barrier
	s_waitcnt vmcnt(0)
	s_branch .LBB0_1074

; #define PG8_STAGE(bufoff, gbase, voff) do { _Pragma("unroll") for (int _i = 0; _i < 2; ++_i) \
;         __builtin_amdgcn_global_load_lds((const unsigned*)((const char*)(gbase) + (voff)[_i]), (LAS unsigned*)(lds + (bufoff) + ldsw + _i * 8192), 16, 0, 0); } while (0)
; #define PG8_LDA(dst, b, h) do { _Pragma("unroll") for (int m = 0; m < 4; ++m) _Pragma("unroll") for (int k = 0; k < 2; ++k) dst[m][k] = *(const LAS bf16x8*)(lds + PG8_SA(b, h) + aoff + m * 2048 + k * 1024); } while (0)
; #define PG8_LDB(dst, b, h) do { _Pragma("unroll") for (int n = 0; n < 2; ++n) _Pragma("unroll") for (int k = 0; k < 2; ++k) dst[n][k] = *(const LAS bf16x8*)(lds + PG8_SB(b, h) + boff + n * 2048 + k * 1024); } while (0)
; #define PG8_MMA(ai, bj, At, Bt) do { __builtin_amdgcn_s_setprio(1); _Pragma("unroll") for (int m = 0; m < 4; ++m) _Pragma("unroll") for (int n = 0; n < 2; ++n) _Pragma("unroll") for (int k = 0; k < 2; ++k) \
;         acc[ai][bj][m][n] = __builtin_amdgcn_mfma_f32_16x16x32_bf16(Bt[n][k], At[m][k], acc[ai][bj][m][n], 0, 0, 0); __builtin_amdgcn_s_setprio(0); } while (0)
; template <class Epi, bool SP2 = false>
; __device__ __forceinline__ void gemm_phase(LAS unsigned char* lds, const Gemm g, const StaticOrder& S, const Epi& E) {
;     ...
;         const bool has_next = S.next(ui + 1, nxt);
;         const char* nA = has_next ? (const char*)g.A + (size_t)nxt.pm * tstepA : cA; const char* nB = has_next ? (const char*)g.Bt + (size_t)nxt.pn * tstepB : cB;
;         for (int t = 0; t < nt; t += 2) {
;             const bool last = (t == nt - 2);
;             const char* a1 = cA + (size_t)(t + 1) * kstep;
;             const char* a2 = last ? nA : cA + (size_t)(t + 2) * kstep; const char* b2 = last ? nB : cB + (size_t)(t + 2) * kstep;
;             const char* a3 = a2 + kstep; const char* b3 = b2 + kstep;
;             if constexpr (SP2) {
;             PG8_LDB(B0, 0, 0); PG8_LDB(B1, 0, 1); PG8_SCHED; PG8_LDA(At, 0, 0); PG8_STAGE(PG8_SA(1, 1), a1 + hstepA, voffA);
;             PG8_WAIT_V(8); PG8_WAIT_L(0); PG8_BAR; PG8_MMA(0, 0, At, B0); PG8_MMA(0, 1, At, B1); PG8_BAR; PG8_SCHED;
;             PG8_LDA(At, 0, 1); PG8_STAGE(PG8_SB(0, 0), b2, voffB); PG8_STAGE(PG8_SB(0, 1), b2 + hstepB, voffB); PG8_STAGE(PG8_SA(0, 0), a2, voffA);
;             PG8_WAIT_V(8); PG8_WAIT_L(0); PG8_BAR; PG8_MMA(1, 0, At, B0); PG8_MMA(1, 1, At, B1); PG8_BAR; PG8_SCHED;
.LBB0_1077:
	ds_read_b128 v[152:155], v149
	ds_read_b128 v[156:159], v149 offset:1024
	ds_read_b128 v[160:163], v149 offset:2048
	ds_read_b128 v[164:167], v149 offset:3072
	ds_read_b128 v[168:171], v150
	ds_read_b128 v[172:175], v150 offset:1024
	ds_read_b128 v[176:179], v150 offset:2048
	ds_read_b128 v[180:183], v150 offset:3072
	s_add_u32 s30, s28, 0xfffc0080
	s_addc_u32 s31, s29, -1
	s_cmp_eq_u32 s57, 12
	s_cselect_b32 s35, s19, s31
	s_cselect_b32 s34, s53, s30
	s_cselect_b32 s31, s13, s56
	s_cselect_b32 s30, s54, s55
	s_add_i32 m0, s27, 0xc000
	ds_read_b128 v[184:187], v151
	ds_read_b128 v[188:191], v151 offset:1024
	ds_read_b128 v[192:195], v151 offset:2048
	ds_read_b128 v[196:199], v151 offset:3072
	ds_read_b128 v[200:203], v151 offset:4096
	ds_read_b128 v[204:207], v151 offset:5120
	ds_read_b128 v[208:211], v151 offset:6144
	ds_read_b128 v[212:215], v151 offset:7168
	global_load_lds_dwordx4 v138, s[28:29]
	s_add_i32 m0, s27, 0xe000
	s_nop 0
	global_load_lds_dwordx4 v140, s[28:29]
	s_waitcnt vmcnt(8)
	s_waitcnt lgkmcnt(0)
	s_barrier
	v_mfma_f32_16x16x32_bf16 v[124:127], v[152:155], v[184:187], v[124:127]
	v_mfma_f32_16x16x32_bf16 v[120:123], v[160:163], v[184:187], v[120:123]
	v_mfma_f32_16x16x32_bf16 v[108:111], v[152:155], v[192:195], v[108:111]
	v_mfma_f32_16x16x32_bf16 v[104:107], v[160:163], v[192:195], v[104:107]
	v_mfma_f32_16x16x32_bf16 v[92:95], v[152:155], v[200:203], v[92:95]
	v_mfma_f32_16x16x32_bf16 v[88:91], v[160:163], v[200:203], v[88:91]
	v_mfma_f32_16x16x32_bf16 v[76:79], v[152:155], v[208:211], v[76:79]
	v_mfma_f32_16x16x32_bf16 v[72:75], v[160:163], v[208:211], v[72:75]
	v_mfma_f32_16x16x32_bf16 v[124:127], v[156:159], v[188:191], v[124:127]
	v_mfma_f32_16x16x32_bf16 v[120:123], v[164:167], v[188:191], v[120:123]
	v_mfma_f32_16x16x32_bf16 v[108:111], v[156:159], v[196:199], v[108:111]
	v_mfma_f32_16x16x32_bf16 v[104:107], v[164:167], v[196:199], v[104:107]
	v_mfma_f32_16x16x32_bf16 v[92:95], v[156:159], v[204:207], v[92:95]
	v_mfma_f32_16x16x32_bf16 v[88:91], v[164:167], v[204:207], v[88:91]
	v_mfma_f32_16x16x32_bf16 v[76:79], v[156:159], v[212:215], v[76:79]
	v_mfma_f32_16x16x32_bf16 v[72:75], v[164:167], v[212:215], v[72:75]
	v_mfma_f32_16x16x32_bf16 v[116:119], v[168:171], v[184:187], v[116:119]
	v_mfma_f32_16x16x32_bf16 v[112:115], v[176:179], v[184:187], v[112:115]
	v_mfma_f32_16x16x32_bf16 v[100:103], v[168:171], v[192:195], v[100:103]
	v_mfma_f32_16x16x32_bf16 v[96:99], v[176:179], v[192:195], v[96:99]
	v_mfma_f32_16x16x32_bf16 v[84:87], v[168:171], v[200:203], v[84:87]
	v_mfma_f32_16x16x32_bf16 v[80:83], v[176:179], v[200:203], v[80:83]
	v_mfma_f32_16x16x32_bf16 v[68:71], v[168:171], v[208:211], v[68:71]
	v_mfma_f32_16x16x32_bf16 v[64:67], v[176:179], v[208:211], v[64:67]
	v_mfma_f32_16x16x32_bf16 v[116:119], v[172:175], v[188:191], v[116:119]
	v_mfma_f32_16x16x32_bf16 v[112:115], v[180:183], v[188:191], v[112:115]
	v_mfma_f32_16x16x32_bf16 v[100:103], v[172:175], v[196:199], v[100:103]
	v_mfma_f32_16x16x32_bf16 v[96:99], v[180:183], v[196:199], v[96:99]
	v_mfma_f32_16x16x32_bf16 v[84:87], v[172:175], v[204:207], v[84:87]
	v_mfma_f32_16x16x32_bf16 v[80:83], v[180:183], v[204:207], v[80:83]
	v_mfma_f32_16x16x32_bf16 v[68:71], v[172:175], v[212:215], v[68:71]
	v_mfma_f32_16x16x32_bf16 v[64:67], v[180:183], v[212:215], v[64:67]
	s_barrier
	s_add_i32 s58, s50, s37
	v_lshl_add_u64 v[146:147], s[30:31], 0, v[134:135]
	s_mov_b32 m0, s58
	ds_read_b128 v[184:187], v151 offset:16384
	ds_read_b128 v[188:191], v151 offset:17408
	ds_read_b128 v[192:195], v151 offset:18432
	ds_read_b128 v[196:199], v151 offset:19456
	ds_read_b128 v[200:203], v151 offset:20480
	ds_read_b128 v[204:207], v151 offset:21504
	ds_read_b128 v[208:211], v151 offset:22528
	ds_read_b128 v[212:215], v151 offset:23552
	global_load_lds_dwordx4 v[146:147], off
	s_add_i32 m0, s58, 0x2000
	s_add_u32 s58, s30, 0x40000
	v_lshl_add_u64 v[216:217], s[30:31], 0, v[130:131]
	s_addc_u32 s59, s31, 0
	s_add_i32 s60, s51, s37
	global_load_lds_dwordx4 v[216:217], off
	s_mov_b32 m0, s60
	v_lshl_add_u64 v[220:221], s[34:35], 0, v[132:133]
	global_load_lds_dwordx4 v134, s[58:59]
	s_add_i32 m0, s60, 0x2000
	s_nop 0
	global_load_lds_dwordx4 v130, s[58:59]
	v_lshl_add_u64 v[218:219], s[34:35], 0, v[136:137]
	s_mov_b32 m0, s27
	s_nop 0
	global_load_lds_dwordx4 v[218:219], off
	s_mov_b32 m0, s40
	s_nop 0
	global_load_lds_dwordx4 v[220:221], off
	s_waitcnt vmcnt(8)
	s_waitcnt lgkmcnt(0)
	s_barrier
	v_mfma_f32_16x16x32_bf16 v[60:63], v[152:155], v[184:187], v[60:63]
	v_mfma_f32_16x16x32_bf16 v[56:59], v[160:163], v[184:187], v[56:59]
	v_mfma_f32_16x16x32_bf16 v[44:47], v[152:155], v[192:195], v[44:47]
	v_mfma_f32_16x16x32_bf16 v[40:43], v[160:163], v[192:195], v[40:43]
	v_mfma_f32_16x16x32_bf16 v[28:31], v[152:155], v[200:203], v[28:31]
	v_mfma_f32_16x16x32_bf16 v[24:27], v[160:163], v[200:203], v[24:27]
	v_mfma_f32_16x16x32_bf16 v[12:15], v[152:155], v[208:211], v[12:15]
	v_mfma_f32_16x16x32_bf16 v[8:11], v[160:163], v[208:211], v[8:11]
	v_mfma_f32_16x16x32_bf16 v[60:63], v[156:159], v[188:191], v[60:63]
	v_mfma_f32_16x16x32_bf16 v[56:59], v[164:167], v[188:191], v[56:59]
	v_mfma_f32_16x16x32_bf16 v[44:47], v[156:159], v[196:199], v[44:47]
	v_mfma_f32_16x16x32_bf16 v[40:43], v[164:167], v[196:199], v[40:43]
	v_mfma_f32_16x16x32_bf16 v[28:31], v[156:159], v[204:207], v[28:31]
	v_mfma_f32_16x16x32_bf16 v[24:27], v[164:167], v[204:207], v[24:27]
	v_mfma_f32_16x16x32_bf16 v[12:15], v[156:159], v[212:215], v[12:15]
	v_mfma_f32_16x16x32_bf16 v[8:11], v[164:167], v[212:215], v[8:11]
	v_mfma_f32_16x16x32_bf16 v[52:55], v[168:171], v[184:187], v[52:55]
	v_mfma_f32_16x16x32_bf16 v[48:51], v[176:179], v[184:187], v[48:51]
	v_mfma_f32_16x16x32_bf16 v[36:39], v[168:171], v[192:195], v[36:39]
	v_mfma_f32_16x16x32_bf16 v[32:35], v[176:179], v[192:195], v[32:35]
	v_mfma_f32_16x16x32_bf16 v[20:23], v[168:171], v[200:203], v[20:23]
	v_mfma_f32_16x16x32_bf16 v[16:19], v[176:179], v[200:203], v[16:19]
	v_mfma_f32_16x16x32_bf16 v[4:7], v[168:171], v[208:211], v[4:7]
	v_mfma_f32_16x16x32_bf16 v[0:3], v[176:179], v[208:211], v[0:3]
	v_mfma_f32_16x16x32_bf16 v[52:55], v[172:175], v[188:191], v[52:55]
	v_mfma_f32_16x16x32_bf16 v[48:51], v[180:183], v[188:191], v[48:51]
	v_mfma_f32_16x16x32_bf16 v[36:39], v[172:175], v[196:199], v[36:39]
	v_mfma_f32_16x16x32_bf16 v[32:35], v[180:183], v[196:199], v[32:35]
	v_mfma_f32_16x16x32_bf16 v[20:23], v[172:175], v[204:207], v[20:23]
	v_mfma_f32_16x16x32_bf16 v[16:19], v[180:183], v[204:207], v[16:19]
	v_mfma_f32_16x16x32_bf16 v[4:7], v[172:175], v[212:215], v[4:7]
	v_mfma_f32_16x16x32_bf16 v[0:3], v[180:183], v[212:215], v[0:3]
	s_barrier
; #define PG8_STAGE(bufoff, gbase, voff) do { _Pragma("unroll") for (int _i = 0; _i < 2; ++_i) \
;         __builtin_amdgcn_global_load_lds((const unsigned*)((const char*)(gbase) + (voff)[_i]), (LAS unsigned*)(lds + (bufoff) + ldsw + _i * 8192), 16, 0, 0); } while (0)
; #define PG8_LDA(dst, b, h) do { _Pragma("unroll") for (int m = 0; m < 4; ++m) _Pragma("unroll") for (int k = 0; k < 2; ++k) dst[m][k] = *(const LAS bf16x8*)(lds + PG8_SA(b, h) + aoff + m * 2048 + k * 1024); } while (0)
; #define PG8_LDB(dst, b, h) do { _Pragma("unroll") for (int n = 0; n < 2; ++n) _Pragma("unroll") for (int k = 0; k < 2; ++k) dst[n][k] = *(const LAS bf16x8*)(lds + PG8_SB(b, h) + boff + n * 2048 + k * 1024); } while (0)
; #define PG8_MMA(ai, bj, At, Bt) do { __builtin_amdgcn_s_setprio(1); _Pragma("unroll") for (int m = 0; m < 4; ++m) _Pragma("unroll") for (int n = 0; n < 2; ++n) _Pragma("unroll") for (int k = 0; k < 2; ++k) \
;         acc[ai][bj][m][n] = __builtin_amdgcn_mfma_f32_16x16x32_bf16(Bt[n][k], At[m][k], acc[ai][bj][m][n], 0, 0, 0); __builtin_amdgcn_s_setprio(0); } while (0)
; #define PG8_WAIT_V(n) asm volatile("s_waitcnt vmcnt(" #n ")" ::: "memory")
; #define PG8_WAIT_L(n) asm volatile("s_waitcnt lgkmcnt(" #n ")" ::: "memory")
; #define PG8_BAR __builtin_amdgcn_s_barrier()
; #define PG8_SCHED __builtin_amdgcn_sched_barrier(0)
; template <class Epi, bool SP2 = false>
; __device__ __forceinline__ void gemm_phase(LAS unsigned char* lds, const Gemm g, const StaticOrder& S, const Epi& E) {
;     ...
;             PG8_LDB(B0, 1, 0); PG8_LDB(B1, 1, 1); PG8_SCHED; PG8_LDA(At, 1, 0); PG8_STAGE(PG8_SA(0, 1), a2 + hstepA, voffA);
;             PG8_WAIT_V(8); PG8_WAIT_L(0); PG8_BAR; PG8_MMA(0, 0, At, B0); PG8_MMA(0, 1, At, B1); PG8_BAR; PG8_SCHED;
;             PG8_LDA(At, 1, 1); PG8_STAGE(PG8_SB(1, 0), b3, voffB); PG8_STAGE(PG8_SB(1, 1), b3 + hstepB, voffB); PG8_STAGE(PG8_SA(1, 0), a3, voffA);
;             PG8_WAIT_V(8); PG8_WAIT_L(0); PG8_BAR; PG8_MMA(1, 0, At, B0); PG8_MMA(1, 1, At, B1); PG8_BAR; PG8_SCHED;
	s_add_i32 s58, 0, 0x18000
	s_add_i32 s59, 0, 0x1c000
	v_add_u32_e32 v164, s58, v148
	v_add_u32_e32 v180, s59, v148
	ds_read_b128 v[152:155], v164
	ds_read_b128 v[156:159], v164 offset:1024
	ds_read_b128 v[160:163], v164 offset:2048
	ds_read_b128 v[164:167], v164 offset:3072
	ds_read_b128 v[168:171], v180
	ds_read_b128 v[172:175], v180 offset:1024
	ds_read_b128 v[176:179], v180 offset:2048
	ds_read_b128 v[180:183], v180 offset:3072
	s_add_u32 s34, s34, 0x40000
	s_addc_u32 s35, s35, 0
	s_mov_b32 m0, s41
	ds_read_b128 v[184:187], v151 offset:32768
	ds_read_b128 v[188:191], v151 offset:33792
	ds_read_b128 v[192:195], v151 offset:34816
	ds_read_b128 v[196:199], v151 offset:35840
	ds_read_b128 v[200:203], v151 offset:36864
	ds_read_b128 v[204:207], v151 offset:37888
	ds_read_b128 v[208:211], v151 offset:38912
	ds_read_b128 v[212:215], v151 offset:39936
	global_load_lds_dwordx4 v136, s[34:35]
	v_lshl_add_u64 v[222:223], s[34:35], 0, v[132:133]
	s_mov_b32 m0, s42
	s_nop 0
	global_load_lds_dwordx4 v[222:223], off
	s_waitcnt vmcnt(8)
	s_waitcnt lgkmcnt(0)
	s_barrier
	v_mfma_f32_16x16x32_bf16 v[124:127], v[152:155], v[184:187], v[124:127]
	v_mfma_f32_16x16x32_bf16 v[120:123], v[160:163], v[184:187], v[120:123]
	v_mfma_f32_16x16x32_bf16 v[108:111], v[152:155], v[192:195], v[108:111]
	v_mfma_f32_16x16x32_bf16 v[104:107], v[160:163], v[192:195], v[104:107]
	v_mfma_f32_16x16x32_bf16 v[92:95], v[152:155], v[200:203], v[92:95]
	v_mfma_f32_16x16x32_bf16 v[88:91], v[160:163], v[200:203], v[88:91]
	v_mfma_f32_16x16x32_bf16 v[76:79], v[152:155], v[208:211], v[76:79]
	v_mfma_f32_16x16x32_bf16 v[72:75], v[160:163], v[208:211], v[72:75]
	v_mfma_f32_16x16x32_bf16 v[124:127], v[156:159], v[188:191], v[124:127]
	v_mfma_f32_16x16x32_bf16 v[120:123], v[164:167], v[188:191], v[120:123]
	v_mfma_f32_16x16x32_bf16 v[108:111], v[156:159], v[196:199], v[108:111]
	v_mfma_f32_16x16x32_bf16 v[104:107], v[164:167], v[196:199], v[104:107]
	v_mfma_f32_16x16x32_bf16 v[92:95], v[156:159], v[204:207], v[92:95]
	v_mfma_f32_16x16x32_bf16 v[88:91], v[164:167], v[204:207], v[88:91]
	v_mfma_f32_16x16x32_bf16 v[76:79], v[156:159], v[212:215], v[76:79]
	v_mfma_f32_16x16x32_bf16 v[72:75], v[164:167], v[212:215], v[72:75]
	v_mfma_f32_16x16x32_bf16 v[116:119], v[168:171], v[184:187], v[116:119]
	v_mfma_f32_16x16x32_bf16 v[112:115], v[176:179], v[184:187], v[112:115]
	v_mfma_f32_16x16x32_bf16 v[100:103], v[168:171], v[192:195], v[100:103]
	v_mfma_f32_16x16x32_bf16 v[96:99], v[176:179], v[192:195], v[96:99]
	v_mfma_f32_16x16x32_bf16 v[84:87], v[168:171], v[200:203], v[84:87]
	v_mfma_f32_16x16x32_bf16 v[80:83], v[176:179], v[200:203], v[80:83]
	v_mfma_f32_16x16x32_bf16 v[68:71], v[168:171], v[208:211], v[68:71]
	v_mfma_f32_16x16x32_bf16 v[64:67], v[176:179], v[208:211], v[64:67]
	v_mfma_f32_16x16x32_bf16 v[116:119], v[172:175], v[188:191], v[116:119]
	v_mfma_f32_16x16x32_bf16 v[112:115], v[180:183], v[188:191], v[112:115]
	v_mfma_f32_16x16x32_bf16 v[100:103], v[172:175], v[196:199], v[100:103]
	v_mfma_f32_16x16x32_bf16 v[96:99], v[180:183], v[196:199], v[96:99]
	v_mfma_f32_16x16x32_bf16 v[84:87], v[172:175], v[204:207], v[84:87]
	v_mfma_f32_16x16x32_bf16 v[80:83], v[180:183], v[204:207], v[80:83]
	v_mfma_f32_16x16x32_bf16 v[68:71], v[172:175], v[212:215], v[68:71]
	v_mfma_f32_16x16x32_bf16 v[64:67], v[180:183], v[212:215], v[64:67]
	s_barrier
	s_add_i32 s34, s58, s37
	v_lshl_add_u64 v[146:147], v[146:147], 0, s[8:9]
	s_mov_b32 m0, s34
	ds_read_b128 v[184:187], v151 offset:49152
	ds_read_b128 v[188:191], v151 offset:50176
	ds_read_b128 v[192:195], v151 offset:51200
	ds_read_b128 v[196:199], v151 offset:52224
	ds_read_b128 v[200:203], v151 offset:53248
	ds_read_b128 v[204:207], v151 offset:54272
	ds_read_b128 v[208:211], v151 offset:55296
	ds_read_b128 v[212:215], v151 offset:56320
	global_load_lds_dwordx4 v[146:147], off
	s_add_i32 m0, s34, 0x2000
	s_add_u32 s30, s30, 0x40080
	v_lshl_add_u64 v[146:147], v[216:217], 0, s[8:9]
	s_addc_u32 s31, s31, 0
	s_add_i32 s34, s59, s37
	global_load_lds_dwordx4 v[146:147], off
	s_mov_b32 m0, s34
	s_nop 0
	global_load_lds_dwordx4 v134, s[30:31]
	s_add_i32 m0, s34, 0x2000
	s_nop 0
	global_load_lds_dwordx4 v130, s[30:31]
	v_lshl_add_u64 v[146:147], v[218:219], 0, s[8:9]
	s_mov_b32 m0, s46
	s_nop 0
	global_load_lds_dwordx4 v[146:147], off
	v_lshl_add_u64 v[146:147], v[220:221], 0, s[8:9]
	s_mov_b32 m0, s47
	s_nop 0
	global_load_lds_dwordx4 v[146:147], off
	s_waitcnt vmcnt(8)
	s_waitcnt lgkmcnt(0)
	s_barrier
	v_mfma_f32_16x16x32_bf16 v[60:63], v[152:155], v[184:187], v[60:63]
	v_mfma_f32_16x16x32_bf16 v[56:59], v[160:163], v[184:187], v[56:59]
	v_mfma_f32_16x16x32_bf16 v[44:47], v[152:155], v[192:195], v[44:47]
	v_mfma_f32_16x16x32_bf16 v[40:43], v[160:163], v[192:195], v[40:43]
	v_mfma_f32_16x16x32_bf16 v[28:31], v[152:155], v[200:203], v[28:31]
	v_mfma_f32_16x16x32_bf16 v[24:27], v[160:163], v[200:203], v[24:27]
	v_mfma_f32_16x16x32_bf16 v[12:15], v[152:155], v[208:211], v[12:15]
	v_mfma_f32_16x16x32_bf16 v[8:11], v[160:163], v[208:211], v[8:11]
	v_mfma_f32_16x16x32_bf16 v[60:63], v[156:159], v[188:191], v[60:63]
	v_mfma_f32_16x16x32_bf16 v[56:59], v[164:167], v[188:191], v[56:59]
	v_mfma_f32_16x16x32_bf16 v[44:47], v[156:159], v[196:199], v[44:47]
	v_mfma_f32_16x16x32_bf16 v[40:43], v[164:167], v[196:199], v[40:43]
	v_mfma_f32_16x16x32_bf16 v[28:31], v[156:159], v[204:207], v[28:31]
	v_mfma_f32_16x16x32_bf16 v[24:27], v[164:167], v[204:207], v[24:27]
	v_mfma_f32_16x16x32_bf16 v[12:15], v[156:159], v[212:215], v[12:15]
	v_mfma_f32_16x16x32_bf16 v[8:11], v[164:167], v[212:215], v[8:11]
	v_mfma_f32_16x16x32_bf16 v[52:55], v[168:171], v[184:187], v[52:55]
	v_mfma_f32_16x16x32_bf16 v[48:51], v[176:179], v[184:187], v[48:51]
	v_mfma_f32_16x16x32_bf16 v[36:39], v[168:171], v[192:195], v[36:39]
	v_mfma_f32_16x16x32_bf16 v[32:35], v[176:179], v[192:195], v[32:35]
	v_mfma_f32_16x16x32_bf16 v[20:23], v[168:171], v[200:203], v[20:23]
	v_mfma_f32_16x16x32_bf16 v[16:19], v[176:179], v[200:203], v[16:19]
	v_mfma_f32_16x16x32_bf16 v[4:7], v[168:171], v[208:211], v[4:7]
	v_mfma_f32_16x16x32_bf16 v[0:3], v[176:179], v[208:211], v[0:3]
	v_mfma_f32_16x16x32_bf16 v[52:55], v[172:175], v[188:191], v[52:55]
	v_mfma_f32_16x16x32_bf16 v[48:51], v[180:183], v[188:191], v[48:51]
	v_mfma_f32_16x16x32_bf16 v[36:39], v[172:175], v[196:199], v[36:39]
	v_mfma_f32_16x16x32_bf16 v[32:35], v[180:183], v[196:199], v[32:35]
	v_mfma_f32_16x16x32_bf16 v[20:23], v[172:175], v[204:207], v[20:23]
	v_mfma_f32_16x16x32_bf16 v[16:19], v[180:183], v[204:207], v[16:19]
	v_mfma_f32_16x16x32_bf16 v[4:7], v[172:175], v[212:215], v[4:7]
	v_mfma_f32_16x16x32_bf16 v[0:3], v[180:183], v[212:215], v[0:3]
	s_barrier
	s_add_i32 s57, s57, 2
	s_add_u32 s28, s28, 0x100
	s_addc_u32 s29, s29, 0
	s_add_u32 s55, s55, 0x100
	s_addc_u32 s56, s56, 0
	s_cmp_gt_u32 s57, 13
	s_cbranch_scc0 .LBB0_1077
	s_and_b64 vcc, exec, s[10:11]
	s_cbranch_vccz .LBB0_1080
	s_barrier

; #define PG8_STAGE(bufoff, gbase, voff) do { _Pragma("unroll") for (int _i = 0; _i < 2; ++_i) \
;         __builtin_amdgcn_global_load_lds((const unsigned*)((const char*)(gbase) + (voff)[_i]), (LAS unsigned*)(lds + (bufoff) + ldsw + _i * 8192), 16, 0, 0); } while (0)
; #define PG8_WAIT_V(n) asm volatile("s_waitcnt vmcnt(" #n ")" ::: "memory")
; #define PG8_BAR __builtin_amdgcn_s_barrier()
; template <class Epi, bool SP2 = false>
; __device__ __forceinline__ void gemm_phase(LAS unsigned char* lds, const Gemm g, const StaticOrder& S, const Epi& E) {
;     const int tid = threadIdx.x, wid = __builtin_amdgcn_readfirstlane(tid >> 6), lane = tid & 63, wr = wid >> 2, wc = wid & 3, fr = lane & 15, fq = lane >> 4;
;     const int K = g.K, nt = K / BK, lda = g.lda;
;     unsigned voffA[2], voffB[2];
; #pragma unroll
;     for (int i = 0; i < 2; ++i) { int R, C; stage_rc(tid * 16 + i * 8192, R, C); const int Rb = Epi::PERM ? ((R & ~31) + perm32(R & 31)) : R;
;         voffA[i] = (unsigned)(R * lda + C) * 2u; voffB[i] = (unsigned)(Rb * K + C) * 2u; }
;     const size_t kstep = (size_t)(BK * 2);
;     const size_t hstepA = (size_t)HALF * lda * 2, hstepB = (size_t)HALF * K * 2;
;     const size_t tstepA = 2 * hstepA, tstepB = 2 * hstepB;
;     const unsigned ldsw = (unsigned)wid * 1024u;
;     const int aoff = lds_byte(wr * 64 + fr, fq * 8), boff = lds_byte(wc * 32 + fr, fq * 8);
;     ...
;     if constexpr (SP2) {
;         PG8_STAGE(PG8_SB(0, 0), cB, voffB); PG8_STAGE(PG8_SB(0, 1), cB + hstepB, voffB); PG8_STAGE(PG8_SA(0, 0), cA, voffA); PG8_STAGE(PG8_SA(0, 1), cA + hstepA, voffA);
;         if (wr == 1) PG8_BAR;
;         PG8_WAIT_V(2); PG8_BAR;
;         PG8_STAGE(PG8_SB(1, 0), cB + kstep, voffB); PG8_STAGE(PG8_SA(1, 0), cA + kstep, voffA); PG8_STAGE(PG8_SB(1, 1), cB + hstepB + kstep, voffB);
;         PG8_WAIT_V(6); PG8_BAR;
.LBB0_1138:
	s_lshl_b32 s1, s1, 5
	s_mov_b64 s[10:11], 0x80
	s_and_b32 s47, s1, 0x60
	s_add_i32 m0, s41, 0x18000
	v_lshl_add_u64 v[6:7], v[6:7], 0, s[10:11]
	s_lshl_b32 s46, s4, 6
	s_lshl_b32 s4, s4, 13
	s_lshl_b32 s1, s47, 7
	s_waitcnt vmcnt(2)
	s_barrier
	global_load_lds_dwordx4 v[6:7], off
	v_lshl_add_u64 v[4:5], v[4:5], 0, s[10:11]
	s_add_i32 m0, s41, 0x1a000
	s_add_i32 s48, s41, 0x8000
	s_add_i32 s49, s41, 0xa000
	global_load_lds_dwordx4 v[4:5], off
	v_lshl_add_u64 v[0:1], v[0:1], 0, s[10:11]
	s_mov_b32 m0, s48
	s_add_u32 s12, s34, 0xb0080
	global_load_lds_dwordx4 v[0:1], off
	v_lshl_add_u64 v[0:1], v[2:3], 0, s[10:11]
	s_mov_b32 m0, s49
	s_addc_u32 s13, s35, 0
	global_load_lds_dwordx4 v[0:1], off
	s_add_i32 m0, s41, 0x1c000
	s_nop 0
	global_load_lds_dwordx4 v134, s[12:13]
	v_lshl_add_u64 v[0:1], s[12:13], 0, v[130:131]
	s_add_i32 m0, s41, 0x1e000
	s_sext_i32_i8 s61, s5
	global_load_lds_dwordx4 v[0:1], off
	v_and_b32_e32 v0, 48, v128
	v_lshlrev_b32_e32 v1, 6, v128
	s_movk_i32 s5, 0x3c0
	v_and_or_b32 v0, v1, s5, v0
	v_lshlrev_b32_e32 v1, 2, v128
	v_and_b32_e32 v1, 32, v1
	v_bitop3_b32 v2, v0, s4, v1 bitop3:0xde
	v_bitop3_b32 v146, s1, v0, v1 bitop3:0xf6
	s_waitcnt vmcnt(6)
	s_cmpk_lt_u32 s0, 0x100
	v_add_u16_e32 v0, v8, v9
	s_cselect_b64 s[12:13], -1, 0
	v_lshrrev_b16_e32 v0, 1, v0
	s_add_i32 s52, 0, 0x10000
	s_add_i32 s53, 0, 0x14000
	s_ashr_i32 s50, s90, 31
	s_mov_b32 s51, s90
	v_add_lshl_u32 v138, v11, v0, 1
	v_mov_b32_e32 v139, v135
	v_add_lshl_u32 v140, v10, v0, 1
	v_mov_b32_e32 v141, v135
	v_mov_b64_e32 v[142:143], 0x600
	v_mov_b64_e32 v[144:145], 0x5ff
	v_add_u32_e32 v147, s52, v146
	v_add_u32_e32 v148, s53, v146
	v_add_u32_e32 v149, 0, v2
	s_mov_b64 s[18:19], 0x40000
	s_mov_b32 s54, 0x40000
	s_mov_b64 s[20:21], 0x48000
	s_mov_b32 s55, 0x48000
	s_mov_b64 s[24:25], 0x50000
	s_mov_b32 s56, 0x50000
	s_mov_b64 s[26:27], 0x58000
	s_mov_b32 s57, 0x58000
	s_barrier
	s_waitcnt vmcnt(0)
	s_branch .LBB0_1141

; #define PG8_STAGE(bufoff, gbase, voff) do { _Pragma("unroll") for (int _i = 0; _i < 2; ++_i) \
;         __builtin_amdgcn_global_load_lds((const unsigned*)((const char*)(gbase) + (voff)[_i]), (LAS unsigned*)(lds + (bufoff) + ldsw + _i * 8192), 16, 0, 0); } while (0)
; #define PG8_LDA(dst, b, h) do { _Pragma("unroll") for (int m = 0; m < 4; ++m) _Pragma("unroll") for (int k = 0; k < 2; ++k) dst[m][k] = *(const LAS bf16x8*)(lds + PG8_SA(b, h) + aoff + m * 2048 + k * 1024); } while (0)
; #define PG8_LDB(dst, b, h) do { _Pragma("unroll") for (int n = 0; n < 2; ++n) _Pragma("unroll") for (int k = 0; k < 2; ++k) dst[n][k] = *(const LAS bf16x8*)(lds + PG8_SB(b, h) + boff + n * 2048 + k * 1024); } while (0)
; #define PG8_MMA(ai, bj, At, Bt) do { __builtin_amdgcn_s_setprio(1); _Pragma("unroll") for (int m = 0; m < 4; ++m) _Pragma("unroll") for (int n = 0; n < 2; ++n) _Pragma("unroll") for (int k = 0; k < 2; ++k) \
;         acc[ai][bj][m][n] = __builtin_amdgcn_mfma_f32_16x16x32_bf16(Bt[n][k], At[m][k], acc[ai][bj][m][n], 0, 0, 0); __builtin_amdgcn_s_setprio(0); } while (0)
; template <class Epi, bool SP2 = false>
; __device__ __forceinline__ void gemm_phase(LAS unsigned char* lds, const Gemm g, const StaticOrder& S, const Epi& E) {
;     ...
;         const bool has_next = S.next(ui + 1, nxt);
;         const char* nA = has_next ? (const char*)g.A + (size_t)nxt.pm * tstepA : cA; const char* nB = has_next ? (const char*)g.Bt + (size_t)nxt.pn * tstepB : cB;
;         for (int t = 0; t < nt; t += 2) {
;             const bool last = (t == nt - 2);
;             const char* a1 = cA + (size_t)(t + 1) * kstep;
;             const char* a2 = last ? nA : cA + (size_t)(t + 2) * kstep; const char* b2 = last ? nB : cB + (size_t)(t + 2) * kstep;
;             const char* a3 = a2 + kstep; const char* b3 = b2 + kstep;
;             if constexpr (SP2) {
;             PG8_LDB(B0, 0, 0); PG8_LDB(B1, 0, 1); PG8_SCHED; PG8_LDA(At, 0, 0); PG8_STAGE(PG8_SA(1, 1), a1 + hstepA, voffA);
;             PG8_WAIT_V(8); PG8_WAIT_L(0); PG8_BAR; PG8_MMA(0, 0, At, B0); PG8_MMA(0, 1, At, B1); PG8_BAR; PG8_SCHED;
;             PG8_LDA(At, 0, 1); PG8_STAGE(PG8_SB(0, 0), b2, voffB); PG8_STAGE(PG8_SB(0, 1), b2 + hstepB, voffB); PG8_STAGE(PG8_SA(0, 0), a2, voffA);
;             PG8_WAIT_V(8); PG8_WAIT_L(0); PG8_BAR; PG8_MMA(1, 0, At, B0); PG8_MMA(1, 1, At, B1); PG8_BAR; PG8_SCHED;
.LBB0_1148:
	ds_read_b128 v[150:153], v147
	ds_read_b128 v[154:157], v147 offset:1024
	ds_read_b128 v[158:161], v147 offset:2048
	ds_read_b128 v[162:165], v147 offset:3072
	ds_read_b128 v[166:169], v148
	ds_read_b128 v[170:173], v148 offset:1024
	ds_read_b128 v[174:177], v148 offset:2048
	ds_read_b128 v[178:181], v148 offset:3072
	s_add_u32 s34, s30, 0xfff50080
	s_addc_u32 s35, s31, -1
	s_cmp_eq_u32 s64, 40
	s_cselect_b32 s37, s5, s35
	s_cselect_b32 s36, s4, s34
	s_cselect_b32 s35, s29, s63
	s_cselect_b32 s34, s28, s62
	s_add_i32 m0, s41, 0xc000
	ds_read_b128 v[182:185], v149
	ds_read_b128 v[186:189], v149 offset:1024
	ds_read_b128 v[190:193], v149 offset:2048
	ds_read_b128 v[194:197], v149 offset:3072
	ds_read_b128 v[198:201], v149 offset:4096
	ds_read_b128 v[202:205], v149 offset:5120
	ds_read_b128 v[206:209], v149 offset:6144
	ds_read_b128 v[210:213], v149 offset:7168
	global_load_lds_dwordx4 v138, s[30:31]
	s_add_i32 m0, s41, 0xe000
	s_nop 0
	global_load_lds_dwordx4 v140, s[30:31]
	s_waitcnt vmcnt(8)
	s_waitcnt lgkmcnt(0)
	s_barrier
	v_mfma_f32_16x16x32_bf16 v[124:127], v[150:153], v[182:185], v[124:127]
	v_mfma_f32_16x16x32_bf16 v[120:123], v[158:161], v[182:185], v[120:123]
	v_mfma_f32_16x16x32_bf16 v[116:119], v[150:153], v[190:193], v[116:119]
	v_mfma_f32_16x16x32_bf16 v[112:115], v[158:161], v[190:193], v[112:115]
	v_mfma_f32_16x16x32_bf16 v[100:103], v[150:153], v[198:201], v[100:103]
	v_mfma_f32_16x16x32_bf16 v[96:99], v[158:161], v[198:201], v[96:99]
	v_mfma_f32_16x16x32_bf16 v[84:87], v[150:153], v[206:209], v[84:87]
	v_mfma_f32_16x16x32_bf16 v[80:83], v[158:161], v[206:209], v[80:83]
	v_mfma_f32_16x16x32_bf16 v[124:127], v[154:157], v[186:189], v[124:127]
	v_mfma_f32_16x16x32_bf16 v[120:123], v[162:165], v[186:189], v[120:123]
	v_mfma_f32_16x16x32_bf16 v[116:119], v[154:157], v[194:197], v[116:119]
	v_mfma_f32_16x16x32_bf16 v[112:115], v[162:165], v[194:197], v[112:115]
	v_mfma_f32_16x16x32_bf16 v[100:103], v[154:157], v[202:205], v[100:103]
	v_mfma_f32_16x16x32_bf16 v[96:99], v[162:165], v[202:205], v[96:99]
	v_mfma_f32_16x16x32_bf16 v[84:87], v[154:157], v[210:213], v[84:87]
	v_mfma_f32_16x16x32_bf16 v[80:83], v[162:165], v[210:213], v[80:83]
	v_mfma_f32_16x16x32_bf16 v[108:111], v[166:169], v[182:185], v[108:111]
	v_mfma_f32_16x16x32_bf16 v[104:107], v[174:177], v[182:185], v[104:107]
	v_mfma_f32_16x16x32_bf16 v[92:95], v[166:169], v[190:193], v[92:95]
	v_mfma_f32_16x16x32_bf16 v[88:91], v[174:177], v[190:193], v[88:91]
	v_mfma_f32_16x16x32_bf16 v[76:79], v[166:169], v[198:201], v[76:79]
	v_mfma_f32_16x16x32_bf16 v[72:75], v[174:177], v[198:201], v[72:75]
	v_mfma_f32_16x16x32_bf16 v[68:71], v[166:169], v[206:209], v[68:71]
	v_mfma_f32_16x16x32_bf16 v[64:67], v[174:177], v[206:209], v[64:67]
	v_mfma_f32_16x16x32_bf16 v[108:111], v[170:173], v[186:189], v[108:111]
	v_mfma_f32_16x16x32_bf16 v[104:107], v[178:181], v[186:189], v[104:107]
	v_mfma_f32_16x16x32_bf16 v[92:95], v[170:173], v[194:197], v[92:95]
	v_mfma_f32_16x16x32_bf16 v[88:91], v[178:181], v[194:197], v[88:91]
	v_mfma_f32_16x16x32_bf16 v[76:79], v[170:173], v[202:205], v[76:79]
	v_mfma_f32_16x16x32_bf16 v[72:75], v[178:181], v[202:205], v[72:75]
	v_mfma_f32_16x16x32_bf16 v[68:71], v[170:173], v[210:213], v[68:71]
	v_mfma_f32_16x16x32_bf16 v[64:67], v[178:181], v[210:213], v[64:67]
	s_barrier
	s_add_i32 s65, s52, s38
	v_lshl_add_u64 v[214:215], s[34:35], 0, v[134:135]
	s_mov_b32 m0, s65
	ds_read_b128 v[182:185], v149 offset:16384
	ds_read_b128 v[186:189], v149 offset:17408
	ds_read_b128 v[190:193], v149 offset:18432
	ds_read_b128 v[194:197], v149 offset:19456
	ds_read_b128 v[198:201], v149 offset:20480
	ds_read_b128 v[202:205], v149 offset:21504
	ds_read_b128 v[206:209], v149 offset:22528
	ds_read_b128 v[210:213], v149 offset:23552
	global_load_lds_dwordx4 v[214:215], off
	s_add_i32 m0, s65, 0x2000
	s_add_u32 s66, s34, 0xb0000
	v_lshl_add_u64 v[216:217], s[34:35], 0, v[130:131]
	s_addc_u32 s67, s35, 0
	s_add_i32 s65, s53, s38
	global_load_lds_dwordx4 v[216:217], off
	s_mov_b32 m0, s65
	v_lshl_add_u64 v[220:221], s[36:37], 0, v[132:133]
	global_load_lds_dwordx4 v134, s[66:67]
	s_add_i32 m0, s65, 0x2000
	s_nop 0
	global_load_lds_dwordx4 v130, s[66:67]
	v_lshl_add_u64 v[218:219], s[36:37], 0, v[136:137]
	s_mov_b32 m0, s41
	s_nop 0
	global_load_lds_dwordx4 v[218:219], off
	s_mov_b32 m0, s42
	s_nop 0
	global_load_lds_dwordx4 v[220:221], off
	s_waitcnt vmcnt(8)
	s_waitcnt lgkmcnt(0)
	s_barrier
	v_mfma_f32_16x16x32_bf16 v[60:63], v[150:153], v[182:185], v[60:63]
	v_mfma_f32_16x16x32_bf16 v[56:59], v[158:161], v[182:185], v[56:59]
	v_mfma_f32_16x16x32_bf16 v[52:55], v[150:153], v[190:193], v[52:55]
	v_mfma_f32_16x16x32_bf16 v[48:51], v[158:161], v[190:193], v[48:51]
	v_mfma_f32_16x16x32_bf16 v[36:39], v[150:153], v[198:201], v[36:39]
	v_mfma_f32_16x16x32_bf16 v[32:35], v[158:161], v[198:201], v[32:35]
	v_mfma_f32_16x16x32_bf16 v[20:23], v[150:153], v[206:209], v[20:23]
	v_mfma_f32_16x16x32_bf16 v[16:19], v[158:161], v[206:209], v[16:19]
	v_mfma_f32_16x16x32_bf16 v[60:63], v[154:157], v[186:189], v[60:63]
	v_mfma_f32_16x16x32_bf16 v[56:59], v[162:165], v[186:189], v[56:59]
	v_mfma_f32_16x16x32_bf16 v[52:55], v[154:157], v[194:197], v[52:55]
	v_mfma_f32_16x16x32_bf16 v[48:51], v[162:165], v[194:197], v[48:51]
	v_mfma_f32_16x16x32_bf16 v[36:39], v[154:157], v[202:205], v[36:39]
	v_mfma_f32_16x16x32_bf16 v[32:35], v[162:165], v[202:205], v[32:35]
	v_mfma_f32_16x16x32_bf16 v[20:23], v[154:157], v[210:213], v[20:23]
	v_mfma_f32_16x16x32_bf16 v[16:19], v[162:165], v[210:213], v[16:19]
	v_mfma_f32_16x16x32_bf16 v[44:47], v[166:169], v[182:185], v[44:47]
	v_mfma_f32_16x16x32_bf16 v[40:43], v[174:177], v[182:185], v[40:43]
	v_mfma_f32_16x16x32_bf16 v[28:31], v[166:169], v[190:193], v[28:31]
	v_mfma_f32_16x16x32_bf16 v[24:27], v[174:177], v[190:193], v[24:27]
	v_mfma_f32_16x16x32_bf16 v[12:15], v[166:169], v[198:201], v[12:15]
	v_mfma_f32_16x16x32_bf16 v[8:11], v[174:177], v[198:201], v[8:11]
	v_mfma_f32_16x16x32_bf16 v[4:7], v[166:169], v[206:209], v[4:7]
	v_mfma_f32_16x16x32_bf16 v[0:3], v[174:177], v[206:209], v[0:3]
	v_mfma_f32_16x16x32_bf16 v[44:47], v[170:173], v[186:189], v[44:47]
	v_mfma_f32_16x16x32_bf16 v[40:43], v[178:181], v[186:189], v[40:43]
	v_mfma_f32_16x16x32_bf16 v[28:31], v[170:173], v[194:197], v[28:31]
	v_mfma_f32_16x16x32_bf16 v[24:27], v[178:181], v[194:197], v[24:27]
	v_mfma_f32_16x16x32_bf16 v[12:15], v[170:173], v[202:205], v[12:15]
	v_mfma_f32_16x16x32_bf16 v[8:11], v[178:181], v[202:205], v[8:11]
	v_mfma_f32_16x16x32_bf16 v[4:7], v[170:173], v[210:213], v[4:7]
	v_mfma_f32_16x16x32_bf16 v[0:3], v[178:181], v[210:213], v[0:3]
	s_barrier
; #define PG8_STAGE(bufoff, gbase, voff) do { _Pragma("unroll") for (int _i = 0; _i < 2; ++_i) \
;         __builtin_amdgcn_global_load_lds((const unsigned*)((const char*)(gbase) + (voff)[_i]), (LAS unsigned*)(lds + (bufoff) + ldsw + _i * 8192), 16, 0, 0); } while (0)
; #define PG8_LDA(dst, b, h) do { _Pragma("unroll") for (int m = 0; m < 4; ++m) _Pragma("unroll") for (int k = 0; k < 2; ++k) dst[m][k] = *(const LAS bf16x8*)(lds + PG8_SA(b, h) + aoff + m * 2048 + k * 1024); } while (0)
; #define PG8_LDB(dst, b, h) do { _Pragma("unroll") for (int n = 0; n < 2; ++n) _Pragma("unroll") for (int k = 0; k < 2; ++k) dst[n][k] = *(const LAS bf16x8*)(lds + PG8_SB(b, h) + boff + n * 2048 + k * 1024); } while (0)
; #define PG8_MMA(ai, bj, At, Bt) do { __builtin_amdgcn_s_setprio(1); _Pragma("unroll") for (int m = 0; m < 4; ++m) _Pragma("unroll") for (int n = 0; n < 2; ++n) _Pragma("unroll") for (int k = 0; k < 2; ++k) \
;         acc[ai][bj][m][n] = __builtin_amdgcn_mfma_f32_16x16x32_bf16(Bt[n][k], At[m][k], acc[ai][bj][m][n], 0, 0, 0); __builtin_amdgcn_s_setprio(0); } while (0)
; #define PG8_WAIT_V(n) asm volatile("s_waitcnt vmcnt(" #n ")" ::: "memory")
; #define PG8_WAIT_L(n) asm volatile("s_waitcnt lgkmcnt(" #n ")" ::: "memory")
; #define PG8_BAR __builtin_amdgcn_s_barrier()
; #define PG8_SCHED __builtin_amdgcn_sched_barrier(0)
; template <class Epi, bool SP2 = false>
; __device__ __forceinline__ void gemm_phase(LAS unsigned char* lds, const Gemm g, const StaticOrder& S, const Epi& E) {
;     ...
;             PG8_LDB(B0, 1, 0); PG8_LDB(B1, 1, 1); PG8_SCHED; PG8_LDA(At, 1, 0); PG8_STAGE(PG8_SA(0, 1), a2 + hstepA, voffA);
;             PG8_WAIT_V(8); PG8_WAIT_L(0); PG8_BAR; PG8_MMA(0, 0, At, B0); PG8_MMA(0, 1, At, B1); PG8_BAR; PG8_SCHED;
;             PG8_LDA(At, 1, 1); PG8_STAGE(PG8_SB(1, 0), b3, voffB); PG8_STAGE(PG8_SB(1, 1), b3 + hstepB, voffB); PG8_STAGE(PG8_SA(1, 0), a3, voffA);
;             PG8_WAIT_V(8); PG8_WAIT_L(0); PG8_BAR; PG8_MMA(1, 0, At, B0); PG8_MMA(1, 1, At, B1); PG8_BAR; PG8_SCHED;
	s_add_i32 s65, 0, 0x18000
	s_add_i32 s66, 0, 0x1c000
	v_add_u32_e32 v162, s65, v146
	v_add_u32_e32 v178, s66, v146
	ds_read_b128 v[150:153], v162
	ds_read_b128 v[154:157], v162 offset:1024
	ds_read_b128 v[158:161], v162 offset:2048
	ds_read_b128 v[162:165], v162 offset:3072
	ds_read_b128 v[166:169], v178
	ds_read_b128 v[170:173], v178 offset:1024
	ds_read_b128 v[174:177], v178 offset:2048
	ds_read_b128 v[178:181], v178 offset:3072
	s_add_u32 s36, s36, 0xb0000
	s_addc_u32 s37, s37, 0
	s_mov_b32 m0, s43
	ds_read_b128 v[182:185], v149 offset:32768
	ds_read_b128 v[186:189], v149 offset:33792
	ds_read_b128 v[190:193], v149 offset:34816
	ds_read_b128 v[194:197], v149 offset:35840
	ds_read_b128 v[198:201], v149 offset:36864
	ds_read_b128 v[202:205], v149 offset:37888
	ds_read_b128 v[206:209], v149 offset:38912
	ds_read_b128 v[210:213], v149 offset:39936
	global_load_lds_dwordx4 v136, s[36:37]
	v_lshl_add_u64 v[222:223], s[36:37], 0, v[132:133]
	s_mov_b32 m0, s44
	s_nop 0
	global_load_lds_dwordx4 v[222:223], off
	s_waitcnt vmcnt(8)
	s_waitcnt lgkmcnt(0)
	s_barrier
	v_mfma_f32_16x16x32_bf16 v[124:127], v[150:153], v[182:185], v[124:127]
	v_mfma_f32_16x16x32_bf16 v[120:123], v[158:161], v[182:185], v[120:123]
	v_mfma_f32_16x16x32_bf16 v[116:119], v[150:153], v[190:193], v[116:119]
	v_mfma_f32_16x16x32_bf16 v[112:115], v[158:161], v[190:193], v[112:115]
	v_mfma_f32_16x16x32_bf16 v[100:103], v[150:153], v[198:201], v[100:103]
	v_mfma_f32_16x16x32_bf16 v[96:99], v[158:161], v[198:201], v[96:99]
	v_mfma_f32_16x16x32_bf16 v[84:87], v[150:153], v[206:209], v[84:87]
	v_mfma_f32_16x16x32_bf16 v[80:83], v[158:161], v[206:209], v[80:83]
	v_mfma_f32_16x16x32_bf16 v[124:127], v[154:157], v[186:189], v[124:127]
	v_mfma_f32_16x16x32_bf16 v[120:123], v[162:165], v[186:189], v[120:123]
	v_mfma_f32_16x16x32_bf16 v[116:119], v[154:157], v[194:197], v[116:119]
	v_mfma_f32_16x16x32_bf16 v[112:115], v[162:165], v[194:197], v[112:115]
	v_mfma_f32_16x16x32_bf16 v[100:103], v[154:157], v[202:205], v[100:103]
	v_mfma_f32_16x16x32_bf16 v[96:99], v[162:165], v[202:205], v[96:99]
	v_mfma_f32_16x16x32_bf16 v[84:87], v[154:157], v[210:213], v[84:87]
	v_mfma_f32_16x16x32_bf16 v[80:83], v[162:165], v[210:213], v[80:83]
	v_mfma_f32_16x16x32_bf16 v[108:111], v[166:169], v[182:185], v[108:111]
	v_mfma_f32_16x16x32_bf16 v[104:107], v[174:177], v[182:185], v[104:107]
	v_mfma_f32_16x16x32_bf16 v[92:95], v[166:169], v[190:193], v[92:95]
	v_mfma_f32_16x16x32_bf16 v[88:91], v[174:177], v[190:193], v[88:91]
	v_mfma_f32_16x16x32_bf16 v[76:79], v[166:169], v[198:201], v[76:79]
	v_mfma_f32_16x16x32_bf16 v[72:75], v[174:177], v[198:201], v[72:75]
	v_mfma_f32_16x16x32_bf16 v[68:71], v[166:169], v[206:209], v[68:71]
	v_mfma_f32_16x16x32_bf16 v[64:67], v[174:177], v[206:209], v[64:67]
	v_mfma_f32_16x16x32_bf16 v[108:111], v[170:173], v[186:189], v[108:111]
	v_mfma_f32_16x16x32_bf16 v[104:107], v[178:181], v[186:189], v[104:107]
	v_mfma_f32_16x16x32_bf16 v[92:95], v[170:173], v[194:197], v[92:95]
	v_mfma_f32_16x16x32_bf16 v[88:91], v[178:181], v[194:197], v[88:91]
	v_mfma_f32_16x16x32_bf16 v[76:79], v[170:173], v[202:205], v[76:79]
	v_mfma_f32_16x16x32_bf16 v[72:75], v[178:181], v[202:205], v[72:75]
	v_mfma_f32_16x16x32_bf16 v[68:71], v[170:173], v[210:213], v[68:71]
	v_mfma_f32_16x16x32_bf16 v[64:67], v[178:181], v[210:213], v[64:67]
	s_barrier
	s_add_i32 s36, s65, s38
	v_lshl_add_u64 v[214:215], v[214:215], 0, s[10:11]
	s_mov_b32 m0, s36
	ds_read_b128 v[182:185], v149 offset:49152
	ds_read_b128 v[186:189], v149 offset:50176
	ds_read_b128 v[190:193], v149 offset:51200
	ds_read_b128 v[194:197], v149 offset:52224
	ds_read_b128 v[198:201], v149 offset:53248
	ds_read_b128 v[202:205], v149 offset:54272
	ds_read_b128 v[206:209], v149 offset:55296
	ds_read_b128 v[210:213], v149 offset:56320
	global_load_lds_dwordx4 v[214:215], off
	s_add_i32 m0, s36, 0x2000
	s_add_u32 s34, s34, 0xb0080
	v_lshl_add_u64 v[214:215], v[216:217], 0, s[10:11]
	s_addc_u32 s35, s35, 0
	s_add_i32 s36, s66, s38
	global_load_lds_dwordx4 v[214:215], off
	s_mov_b32 m0, s36
	s_nop 0
	global_load_lds_dwordx4 v134, s[34:35]
	s_add_i32 m0, s36, 0x2000
	s_nop 0
	global_load_lds_dwordx4 v130, s[34:35]
	v_lshl_add_u64 v[214:215], v[218:219], 0, s[10:11]
	s_mov_b32 m0, s48
	s_nop 0
	global_load_lds_dwordx4 v[214:215], off
	v_lshl_add_u64 v[214:215], v[220:221], 0, s[10:11]
	s_mov_b32 m0, s49
	s_nop 0
	global_load_lds_dwordx4 v[214:215], off
	s_waitcnt vmcnt(8)
	s_waitcnt lgkmcnt(0)
	s_barrier
	v_mfma_f32_16x16x32_bf16 v[60:63], v[150:153], v[182:185], v[60:63]
	v_mfma_f32_16x16x32_bf16 v[56:59], v[158:161], v[182:185], v[56:59]
	v_mfma_f32_16x16x32_bf16 v[52:55], v[150:153], v[190:193], v[52:55]
	v_mfma_f32_16x16x32_bf16 v[48:51], v[158:161], v[190:193], v[48:51]
	v_mfma_f32_16x16x32_bf16 v[36:39], v[150:153], v[198:201], v[36:39]
	v_mfma_f32_16x16x32_bf16 v[32:35], v[158:161], v[198:201], v[32:35]
	v_mfma_f32_16x16x32_bf16 v[20:23], v[150:153], v[206:209], v[20:23]
	v_mfma_f32_16x16x32_bf16 v[16:19], v[158:161], v[206:209], v[16:19]
	v_mfma_f32_16x16x32_bf16 v[60:63], v[154:157], v[186:189], v[60:63]
	v_mfma_f32_16x16x32_bf16 v[56:59], v[162:165], v[186:189], v[56:59]
	v_mfma_f32_16x16x32_bf16 v[52:55], v[154:157], v[194:197], v[52:55]
	v_mfma_f32_16x16x32_bf16 v[48:51], v[162:165], v[194:197], v[48:51]
	v_mfma_f32_16x16x32_bf16 v[36:39], v[154:157], v[202:205], v[36:39]
	v_mfma_f32_16x16x32_bf16 v[32:35], v[162:165], v[202:205], v[32:35]
	v_mfma_f32_16x16x32_bf16 v[20:23], v[154:157], v[210:213], v[20:23]
	v_mfma_f32_16x16x32_bf16 v[16:19], v[162:165], v[210:213], v[16:19]
	v_mfma_f32_16x16x32_bf16 v[44:47], v[166:169], v[182:185], v[44:47]
	v_mfma_f32_16x16x32_bf16 v[40:43], v[174:177], v[182:185], v[40:43]
	v_mfma_f32_16x16x32_bf16 v[28:31], v[166:169], v[190:193], v[28:31]
	v_mfma_f32_16x16x32_bf16 v[24:27], v[174:177], v[190:193], v[24:27]
	v_mfma_f32_16x16x32_bf16 v[12:15], v[166:169], v[198:201], v[12:15]
	v_mfma_f32_16x16x32_bf16 v[8:11], v[174:177], v[198:201], v[8:11]
	v_mfma_f32_16x16x32_bf16 v[4:7], v[166:169], v[206:209], v[4:7]
	v_mfma_f32_16x16x32_bf16 v[0:3], v[174:177], v[206:209], v[0:3]
	v_mfma_f32_16x16x32_bf16 v[44:47], v[170:173], v[186:189], v[44:47]
	v_mfma_f32_16x16x32_bf16 v[40:43], v[178:181], v[186:189], v[40:43]
	v_mfma_f32_16x16x32_bf16 v[28:31], v[170:173], v[194:197], v[28:31]
	v_mfma_f32_16x16x32_bf16 v[24:27], v[178:181], v[194:197], v[24:27]
	v_mfma_f32_16x16x32_bf16 v[12:15], v[170:173], v[202:205], v[12:15]
	v_mfma_f32_16x16x32_bf16 v[8:11], v[178:181], v[202:205], v[8:11]
	v_mfma_f32_16x16x32_bf16 v[4:7], v[170:173], v[210:213], v[4:7]
	v_mfma_f32_16x16x32_bf16 v[0:3], v[178:181], v[210:213], v[0:3]
	s_barrier
	s_add_i32 s64, s64, 2
	s_add_u32 s30, s30, 0x100
	s_addc_u32 s31, s31, 0
	s_add_u32 s62, s62, 0x100
	s_addc_u32 s63, s63, 0
	s_cmp_gt_u32 s64, 41
	s_cbranch_scc0 .LBB0_1148
	s_and_b64 vcc, exec, s[12:13]
	s_cbranch_vccz .LBB0_1151
	s_barrier
